# all 16-MFMA runs of the GEMM K-loops start 8-byte aligned (one s_nop 0 pad before a load-segment wait where needed), on top of 64-byte aligned loop heads
# speedup vs baseline: 1.0015x; 1.0015x over previous
; #define PG8_STAGE(bufoff, gbase, voff) do { _Pragma("unroll") for (int _i = 0; _i < 2; ++_i) \
;         __builtin_amdgcn_global_load_lds((const unsigned*)((const char*)(gbase) + (voff)[_i]), (PG8_LAS unsigned*)(lds + (bufoff) + ldsw + _i * 8192), 16, 0, 0); } while (0)
; #define PG8_LDA(dst, b, h) do { _Pragma("unroll") for (int m = 0; m < 4; ++m) _Pragma("unroll") for (int k = 0; k < 2; ++k) dst[m][k] = *(const PG8_LAS bf16x8*)(lds + PG8_SA(b, h) + aoff + m * 2048 + k * 1024); } while (0)
; #define PG8_LDB(dst, b, h) do { _Pragma("unroll") for (int n = 0; n < 2; ++n) _Pragma("unroll") for (int k = 0; k < 2; ++k) dst[n][k] = *(const PG8_LAS bf16x8*)(lds + PG8_SB(b, h) + boff + n * 2048 + k * 1024); } while (0)
; #define PG8_MMA(ai, bj, At, Bt) do { __builtin_amdgcn_s_setprio(1); _Pragma("unroll") for (int m = 0; m < 4; ++m) _Pragma("unroll") for (int n = 0; n < 2; ++n) _Pragma("unroll") for (int k = 0; k < 2; ++k) \
;         acc[ai][bj][m][n] = __builtin_amdgcn_mfma_f32_16x16x32_bf16(Bt[n][k], At[m][k], acc[ai][bj][m][n], 0, 0, 0); __builtin_amdgcn_s_setprio(0); } while (0)
; #define PG8_WAIT_V(n) asm volatile("s_waitcnt vmcnt(" #n ")" ::: "memory")
; #define PG8_WAIT_L(n) asm volatile("s_waitcnt lgkmcnt(" #n ")" ::: "memory")
; #define PG8_BAR __builtin_amdgcn_s_barrier()
; #define PG8_SCHED __builtin_amdgcn_sched_barrier(0)
; template <class Epi, class Sched, bool ALIGN_EPI = false, bool SP2 = false>
; __device__ __forceinline__ void gemm_phase(PG8_LAS unsigned char* lds, const Gemm g, const Sched& S, const Epi& E) {
;     ...
;             PG8_LDB(B0, 0, 0); PG8_LDB(B1, 0, 1); PG8_SCHED; PG8_LDA(At, 0, 0); PG8_STAGE(PG8_SA(1, 1), a1 + hstep, voffA);
;             PG8_WAIT_V(8); PG8_WAIT_L(0); PG8_BAR; PG8_MMA(0, 0, At, B0); PG8_MMA(0, 1, At, B1); PG8_BAR; PG8_SCHED;
;             PG8_LDA(At, 0, 1); PG8_STAGE(PG8_SB(0, 0), b2, voffB); PG8_STAGE(PG8_SB(0, 1), b2 + hstep, voffB); PG8_STAGE(PG8_SA(0, 0), a2, voffA);
.LBB0_95:
	ds_read_b128 v[144:147], v155
	ds_read_b128 v[148:151], v155 offset:1024
	ds_read_b128 v[158:161], v155 offset:2048
	ds_read_b128 v[162:165], v155 offset:3072
	ds_read_b128 v[166:169], v156
	ds_read_b128 v[170:173], v156 offset:1024
	ds_read_b128 v[174:177], v156 offset:2048
	ds_read_b128 v[178:181], v156 offset:3072
	s_add_u32 s0, s80, 0xfff80080
	s_addc_u32 s1, s81, -1
	s_cmp_eq_u32 s56, 28
	s_cselect_b32 s83, s23, s1
	s_cselect_b32 s82, s52, s0
	s_cselect_b32 s1, s21, s55
	s_cselect_b32 s0, s53, s54
	v_lshl_add_u64 v[214:215], s[80:81], 0, v[136:137]
	s_add_i32 m0, s36, 0xc000
	ds_read_b128 v[182:185], v157
	ds_read_b128 v[186:189], v157 offset:1024
	ds_read_b128 v[190:193], v157 offset:2048
	ds_read_b128 v[194:197], v157 offset:3072
	ds_read_b128 v[198:201], v157 offset:4096
	ds_read_b128 v[202:205], v157 offset:5120
	ds_read_b128 v[206:209], v157 offset:6144
	ds_read_b128 v[210:213], v157 offset:7168
	global_load_lds_dwordx4 v[214:215], off
	v_lshl_add_u64 v[214:215], s[80:81], 0, v[138:139]
	s_add_i32 m0, s36, 0xe000
	s_nop 0
	global_load_lds_dwordx4 v[214:215], off
	s_waitcnt vmcnt(8)
	s_waitcnt lgkmcnt(0)
	s_barrier
	s_setprio 1
	s_waitcnt lgkmcnt(0)
	v_mfma_f32_16x16x32_bf16 v[124:127], v[144:147], v[182:185], v[124:127]
	v_mfma_f32_16x16x32_bf16 v[120:123], v[158:161], v[182:185], v[120:123]
	v_mfma_f32_16x16x32_bf16 v[108:111], v[144:147], v[190:193], v[108:111]
	v_mfma_f32_16x16x32_bf16 v[104:107], v[158:161], v[190:193], v[104:107]
	v_mfma_f32_16x16x32_bf16 v[92:95], v[144:147], v[198:201], v[92:95]
	v_mfma_f32_16x16x32_bf16 v[88:91], v[158:161], v[198:201], v[88:91]
	v_mfma_f32_16x16x32_bf16 v[76:79], v[144:147], v[206:209], v[76:79]
	v_mfma_f32_16x16x32_bf16 v[72:75], v[158:161], v[206:209], v[72:75]
	v_mfma_f32_16x16x32_bf16 v[124:127], v[148:151], v[186:189], v[124:127]
	v_mfma_f32_16x16x32_bf16 v[120:123], v[162:165], v[186:189], v[120:123]
	v_mfma_f32_16x16x32_bf16 v[108:111], v[148:151], v[194:197], v[108:111]
	v_mfma_f32_16x16x32_bf16 v[104:107], v[162:165], v[194:197], v[104:107]
	v_mfma_f32_16x16x32_bf16 v[92:95], v[148:151], v[202:205], v[92:95]
	v_mfma_f32_16x16x32_bf16 v[88:91], v[162:165], v[202:205], v[88:91]
	v_mfma_f32_16x16x32_bf16 v[76:79], v[148:151], v[210:213], v[76:79]
	v_mfma_f32_16x16x32_bf16 v[72:75], v[162:165], v[210:213], v[72:75]
	s_setprio 0
	s_setprio 1
	v_mfma_f32_16x16x32_bf16 v[116:119], v[166:169], v[182:185], v[116:119]
	v_mfma_f32_16x16x32_bf16 v[112:115], v[174:177], v[182:185], v[112:115]
	v_mfma_f32_16x16x32_bf16 v[100:103], v[166:169], v[190:193], v[100:103]
	v_mfma_f32_16x16x32_bf16 v[96:99], v[174:177], v[190:193], v[96:99]
	v_mfma_f32_16x16x32_bf16 v[84:87], v[166:169], v[198:201], v[84:87]
	v_mfma_f32_16x16x32_bf16 v[80:83], v[174:177], v[198:201], v[80:83]
	v_mfma_f32_16x16x32_bf16 v[68:71], v[166:169], v[206:209], v[68:71]
	v_mfma_f32_16x16x32_bf16 v[64:67], v[174:177], v[206:209], v[64:67]
	v_mfma_f32_16x16x32_bf16 v[116:119], v[170:173], v[186:189], v[116:119]
	v_mfma_f32_16x16x32_bf16 v[112:115], v[178:181], v[186:189], v[112:115]
	v_mfma_f32_16x16x32_bf16 v[100:103], v[170:173], v[194:197], v[100:103]
	v_mfma_f32_16x16x32_bf16 v[96:99], v[178:181], v[194:197], v[96:99]
	v_mfma_f32_16x16x32_bf16 v[84:87], v[170:173], v[202:205], v[84:87]
	v_mfma_f32_16x16x32_bf16 v[80:83], v[178:181], v[202:205], v[80:83]
	v_mfma_f32_16x16x32_bf16 v[68:71], v[170:173], v[210:213], v[68:71]
	v_mfma_f32_16x16x32_bf16 v[64:67], v[178:181], v[210:213], v[64:67]
	s_setprio 0
	s_barrier
	s_add_i32 s57, s45, s3
	v_lshl_add_u64 v[214:215], s[0:1], 0, v[132:133]
	s_mov_b32 m0, s57
	ds_read_b128 v[182:185], v157 offset:16384
	ds_read_b128 v[186:189], v157 offset:17408
	ds_read_b128 v[190:193], v157 offset:18432
	ds_read_b128 v[194:197], v157 offset:19456
	ds_read_b128 v[198:201], v157 offset:20480
	ds_read_b128 v[202:205], v157 offset:21504
	ds_read_b128 v[206:209], v157 offset:22528
	ds_read_b128 v[210:213], v157 offset:23552
	global_load_lds_dwordx4 v[214:215], off
	s_add_i32 m0, s57, 0x2000
	s_add_u32 s58, s0, 0x80000
	v_lshl_add_u64 v[216:217], s[0:1], 0, v[128:129]
	s_addc_u32 s59, s1, 0
	s_add_i32 s57, s46, s3
	global_load_lds_dwordx4 v[216:217], off
	v_lshl_add_u64 v[218:219], s[58:59], 0, v[132:133]
	s_mov_b32 m0, s57
	v_lshl_add_u64 v[220:221], s[82:83], 0, v[130:131]
	global_load_lds_dwordx4 v[218:219], off
	v_lshl_add_u64 v[218:219], s[58:59], 0, v[128:129]
	s_add_i32 m0, s57, 0x2000
	s_nop 0
	global_load_lds_dwordx4 v[218:219], off
	v_lshl_add_u64 v[218:219], s[82:83], 0, v[134:135]
	s_mov_b32 m0, s36
	s_nop 0
	global_load_lds_dwordx4 v[218:219], off
	s_mov_b32 m0, s37
	s_nop 0
	global_load_lds_dwordx4 v[220:221], off
	s_waitcnt vmcnt(8)
	s_waitcnt lgkmcnt(0)
	s_barrier
; #define PG8_STAGE(bufoff, gbase, voff) do { _Pragma("unroll") for (int _i = 0; _i < 2; ++_i) \
;         __builtin_amdgcn_global_load_lds((const unsigned*)((const char*)(gbase) + (voff)[_i]), (PG8_LAS unsigned*)(lds + (bufoff) + ldsw + _i * 8192), 16, 0, 0); } while (0)
; #define PG8_LDA(dst, b, h) do { _Pragma("unroll") for (int m = 0; m < 4; ++m) _Pragma("unroll") for (int k = 0; k < 2; ++k) dst[m][k] = *(const PG8_LAS bf16x8*)(lds + PG8_SA(b, h) + aoff + m * 2048 + k * 1024); } while (0)
; #define PG8_LDB(dst, b, h) do { _Pragma("unroll") for (int n = 0; n < 2; ++n) _Pragma("unroll") for (int k = 0; k < 2; ++k) dst[n][k] = *(const PG8_LAS bf16x8*)(lds + PG8_SB(b, h) + boff + n * 2048 + k * 1024); } while (0)
; #define PG8_MMA(ai, bj, At, Bt) do { __builtin_amdgcn_s_setprio(1); _Pragma("unroll") for (int m = 0; m < 4; ++m) _Pragma("unroll") for (int n = 0; n < 2; ++n) _Pragma("unroll") for (int k = 0; k < 2; ++k) \
;         acc[ai][bj][m][n] = __builtin_amdgcn_mfma_f32_16x16x32_bf16(Bt[n][k], At[m][k], acc[ai][bj][m][n], 0, 0, 0); __builtin_amdgcn_s_setprio(0); } while (0)
; #define PG8_WAIT_V(n) asm volatile("s_waitcnt vmcnt(" #n ")" ::: "memory")
; #define PG8_WAIT_L(n) asm volatile("s_waitcnt lgkmcnt(" #n ")" ::: "memory")
; #define PG8_BAR __builtin_amdgcn_s_barrier()
; #define PG8_SCHED __builtin_amdgcn_sched_barrier(0)
; template <class Epi, class Sched, bool ALIGN_EPI = false, bool SP2 = false>
; __device__ __forceinline__ void gemm_phase(PG8_LAS unsigned char* lds, const Gemm g, const Sched& S, const Epi& E) {
;     ...
;             PG8_WAIT_V(8); PG8_WAIT_L(0); PG8_BAR; PG8_MMA(1, 0, At, B0); PG8_MMA(1, 1, At, B1); PG8_BAR; PG8_SCHED;
;             PG8_LDB(B0, 1, 0); PG8_LDB(B1, 1, 1); PG8_SCHED; PG8_LDA(At, 1, 0); PG8_STAGE(PG8_SA(0, 1), a2 + hstep, voffA);
;             PG8_WAIT_V(8); PG8_WAIT_L(0); PG8_BAR; PG8_MMA(0, 0, At, B0); PG8_MMA(0, 1, At, B1); PG8_BAR; PG8_SCHED;
	s_setprio 1
	s_nop 0
	s_waitcnt lgkmcnt(0)
	v_mfma_f32_16x16x32_bf16 v[60:63], v[144:147], v[182:185], v[60:63]
	v_mfma_f32_16x16x32_bf16 v[56:59], v[158:161], v[182:185], v[56:59]
	v_mfma_f32_16x16x32_bf16 v[44:47], v[144:147], v[190:193], v[44:47]
	v_mfma_f32_16x16x32_bf16 v[40:43], v[158:161], v[190:193], v[40:43]
	v_mfma_f32_16x16x32_bf16 v[28:31], v[144:147], v[198:201], v[28:31]
	v_mfma_f32_16x16x32_bf16 v[24:27], v[158:161], v[198:201], v[24:27]
	v_mfma_f32_16x16x32_bf16 v[12:15], v[144:147], v[206:209], v[12:15]
	v_mfma_f32_16x16x32_bf16 v[8:11], v[158:161], v[206:209], v[8:11]
	v_mfma_f32_16x16x32_bf16 v[60:63], v[148:151], v[186:189], v[60:63]
	v_mfma_f32_16x16x32_bf16 v[56:59], v[162:165], v[186:189], v[56:59]
	v_mfma_f32_16x16x32_bf16 v[44:47], v[148:151], v[194:197], v[44:47]
	v_mfma_f32_16x16x32_bf16 v[40:43], v[162:165], v[194:197], v[40:43]
	v_mfma_f32_16x16x32_bf16 v[28:31], v[148:151], v[202:205], v[28:31]
	v_mfma_f32_16x16x32_bf16 v[24:27], v[162:165], v[202:205], v[24:27]
	v_mfma_f32_16x16x32_bf16 v[12:15], v[148:151], v[210:213], v[12:15]
	v_mfma_f32_16x16x32_bf16 v[8:11], v[162:165], v[210:213], v[8:11]
	s_setprio 0
	s_setprio 1
	v_mfma_f32_16x16x32_bf16 v[52:55], v[166:169], v[182:185], v[52:55]
	v_mfma_f32_16x16x32_bf16 v[48:51], v[174:177], v[182:185], v[48:51]
	v_mfma_f32_16x16x32_bf16 v[36:39], v[166:169], v[190:193], v[36:39]
	v_mfma_f32_16x16x32_bf16 v[32:35], v[174:177], v[190:193], v[32:35]
	v_mfma_f32_16x16x32_bf16 v[20:23], v[166:169], v[198:201], v[20:23]
	v_mfma_f32_16x16x32_bf16 v[16:19], v[174:177], v[198:201], v[16:19]
	v_mfma_f32_16x16x32_bf16 v[4:7], v[166:169], v[206:209], v[4:7]
	v_mfma_f32_16x16x32_bf16 v[0:3], v[174:177], v[206:209], v[0:3]
	v_mfma_f32_16x16x32_bf16 v[52:55], v[170:173], v[186:189], v[52:55]
	v_mfma_f32_16x16x32_bf16 v[48:51], v[178:181], v[186:189], v[48:51]
	v_mfma_f32_16x16x32_bf16 v[36:39], v[170:173], v[194:197], v[36:39]
	v_mfma_f32_16x16x32_bf16 v[32:35], v[178:181], v[194:197], v[32:35]
	v_mfma_f32_16x16x32_bf16 v[20:23], v[170:173], v[202:205], v[20:23]
	v_mfma_f32_16x16x32_bf16 v[16:19], v[178:181], v[202:205], v[16:19]
	v_mfma_f32_16x16x32_bf16 v[4:7], v[170:173], v[210:213], v[4:7]
	v_mfma_f32_16x16x32_bf16 v[0:3], v[178:181], v[210:213], v[0:3]
	s_setprio 0
	s_barrier
	s_add_i32 s57, 0, 0x18000
	s_add_i32 s65, 0, 0x1c000
	v_add_u32_e32 v162, s57, v153
	v_add_u32_e32 v178, s65, v153
	ds_read_b128 v[144:147], v162
	ds_read_b128 v[148:151], v162 offset:1024
	ds_read_b128 v[158:161], v162 offset:2048
	ds_read_b128 v[162:165], v162 offset:3072
	ds_read_b128 v[166:169], v178
	ds_read_b128 v[170:173], v178 offset:1024
	ds_read_b128 v[174:177], v178 offset:2048
	ds_read_b128 v[178:181], v178 offset:3072
	s_add_u32 s58, s82, 0x80000
	s_addc_u32 s59, s83, 0
	s_mov_b32 m0, s38
	v_lshl_add_u64 v[228:229], s[58:59], 0, v[134:135]
	ds_read_b128 v[182:185], v157 offset:32768
	ds_read_b128 v[186:189], v157 offset:33792
	ds_read_b128 v[190:193], v157 offset:34816
	ds_read_b128 v[194:197], v157 offset:35840
	ds_read_b128 v[198:201], v157 offset:36864
	ds_read_b128 v[202:205], v157 offset:37888
	ds_read_b128 v[206:209], v157 offset:38912
	ds_read_b128 v[210:213], v157 offset:39936
	global_load_lds_dwordx4 v[228:229], off
	v_lshl_add_u64 v[228:229], s[58:59], 0, v[130:131]
	s_mov_b32 m0, s39
	s_nop 0
	global_load_lds_dwordx4 v[228:229], off
	s_waitcnt vmcnt(8)
	s_waitcnt lgkmcnt(0)
	s_barrier
	s_setprio 1
	s_nop 0
	s_waitcnt lgkmcnt(0)
	v_mfma_f32_16x16x32_bf16 v[124:127], v[144:147], v[182:185], v[124:127]
	v_mfma_f32_16x16x32_bf16 v[120:123], v[158:161], v[182:185], v[120:123]
	v_mfma_f32_16x16x32_bf16 v[108:111], v[144:147], v[190:193], v[108:111]
	v_mfma_f32_16x16x32_bf16 v[104:107], v[158:161], v[190:193], v[104:107]
	v_mfma_f32_16x16x32_bf16 v[92:95], v[144:147], v[198:201], v[92:95]
	v_mfma_f32_16x16x32_bf16 v[88:91], v[158:161], v[198:201], v[88:91]
	v_mfma_f32_16x16x32_bf16 v[76:79], v[144:147], v[206:209], v[76:79]
	v_mfma_f32_16x16x32_bf16 v[72:75], v[158:161], v[206:209], v[72:75]
	v_mfma_f32_16x16x32_bf16 v[124:127], v[148:151], v[186:189], v[124:127]
	v_mfma_f32_16x16x32_bf16 v[120:123], v[162:165], v[186:189], v[120:123]
	v_mfma_f32_16x16x32_bf16 v[108:111], v[148:151], v[194:197], v[108:111]
	v_mfma_f32_16x16x32_bf16 v[104:107], v[162:165], v[194:197], v[104:107]
	v_mfma_f32_16x16x32_bf16 v[92:95], v[148:151], v[202:205], v[92:95]
	v_mfma_f32_16x16x32_bf16 v[88:91], v[162:165], v[202:205], v[88:91]
	v_mfma_f32_16x16x32_bf16 v[76:79], v[148:151], v[210:213], v[76:79]
	v_mfma_f32_16x16x32_bf16 v[72:75], v[162:165], v[210:213], v[72:75]
	s_setprio 0
	s_setprio 1
	v_mfma_f32_16x16x32_bf16 v[116:119], v[166:169], v[182:185], v[116:119]
	v_mfma_f32_16x16x32_bf16 v[112:115], v[174:177], v[182:185], v[112:115]
	v_mfma_f32_16x16x32_bf16 v[100:103], v[166:169], v[190:193], v[100:103]
	v_mfma_f32_16x16x32_bf16 v[96:99], v[174:177], v[190:193], v[96:99]
	v_mfma_f32_16x16x32_bf16 v[84:87], v[166:169], v[198:201], v[84:87]
	v_mfma_f32_16x16x32_bf16 v[80:83], v[174:177], v[198:201], v[80:83]
	v_mfma_f32_16x16x32_bf16 v[68:71], v[166:169], v[206:209], v[68:71]
	v_mfma_f32_16x16x32_bf16 v[64:67], v[174:177], v[206:209], v[64:67]
	v_mfma_f32_16x16x32_bf16 v[116:119], v[170:173], v[186:189], v[116:119]
	v_mfma_f32_16x16x32_bf16 v[112:115], v[178:181], v[186:189], v[112:115]
	v_mfma_f32_16x16x32_bf16 v[100:103], v[170:173], v[194:197], v[100:103]
	v_mfma_f32_16x16x32_bf16 v[96:99], v[178:181], v[194:197], v[96:99]
	v_mfma_f32_16x16x32_bf16 v[84:87], v[170:173], v[202:205], v[84:87]
	v_mfma_f32_16x16x32_bf16 v[80:83], v[178:181], v[202:205], v[80:83]
	v_mfma_f32_16x16x32_bf16 v[68:71], v[170:173], v[210:213], v[68:71]
	v_mfma_f32_16x16x32_bf16 v[64:67], v[178:181], v[210:213], v[64:67]
	s_setprio 0
	s_barrier
; #define PG8_STAGE(bufoff, gbase, voff) do { _Pragma("unroll") for (int _i = 0; _i < 2; ++_i) \
;         __builtin_amdgcn_global_load_lds((const unsigned*)((const char*)(gbase) + (voff)[_i]), (PG8_LAS unsigned*)(lds + (bufoff) + ldsw + _i * 8192), 16, 0, 0); } while (0)
; #define PG8_LDA(dst, b, h) do { _Pragma("unroll") for (int m = 0; m < 4; ++m) _Pragma("unroll") for (int k = 0; k < 2; ++k) dst[m][k] = *(const PG8_LAS bf16x8*)(lds + PG8_SA(b, h) + aoff + m * 2048 + k * 1024); } while (0)
; #define PG8_MMA(ai, bj, At, Bt) do { __builtin_amdgcn_s_setprio(1); _Pragma("unroll") for (int m = 0; m < 4; ++m) _Pragma("unroll") for (int n = 0; n < 2; ++n) _Pragma("unroll") for (int k = 0; k < 2; ++k) \
;         acc[ai][bj][m][n] = __builtin_amdgcn_mfma_f32_16x16x32_bf16(Bt[n][k], At[m][k], acc[ai][bj][m][n], 0, 0, 0); __builtin_amdgcn_s_setprio(0); } while (0)
; #define PG8_WAIT_V(n) asm volatile("s_waitcnt vmcnt(" #n ")" ::: "memory")
; #define PG8_WAIT_L(n) asm volatile("s_waitcnt lgkmcnt(" #n ")" ::: "memory")
; #define PG8_BAR __builtin_amdgcn_s_barrier()
; #define PG8_SCHED __builtin_amdgcn_sched_barrier(0)
; template <class Epi, class Sched, bool ALIGN_EPI = false, bool SP2 = false>
; __device__ __forceinline__ void gemm_phase(PG8_LAS unsigned char* lds, const Gemm g, const Sched& S, const Epi& E) {
;     ...
;         for (int t = 0; t < nt; t += 2) {
;     ...
;             PG8_LDA(At, 1, 1); PG8_STAGE(PG8_SB(1, 0), b3, voffB); PG8_STAGE(PG8_SB(1, 1), b3 + hstep, voffB); PG8_STAGE(PG8_SA(1, 0), a3, voffA);
;             PG8_WAIT_V(8); PG8_WAIT_L(0); PG8_BAR; PG8_MMA(1, 0, At, B0); PG8_MMA(1, 1, At, B1); PG8_BAR; PG8_SCHED;
;     ...
;         if constexpr (ALIGN_EPI) { if (wr == 0) PG8_BAR; }
	s_add_i32 s57, s57, s3
	v_lshl_add_u64 v[214:215], v[214:215], 0, s[12:13]
	s_mov_b32 m0, s57
	ds_read_b128 v[182:185], v157 offset:49152
	ds_read_b128 v[186:189], v157 offset:50176
	ds_read_b128 v[190:193], v157 offset:51200
	ds_read_b128 v[194:197], v157 offset:52224
	ds_read_b128 v[198:201], v157 offset:53248
	ds_read_b128 v[202:205], v157 offset:54272
	ds_read_b128 v[206:209], v157 offset:55296
	ds_read_b128 v[210:213], v157 offset:56320
	global_load_lds_dwordx4 v[214:215], off
	s_add_i32 m0, s57, 0x2000
	s_add_u32 s0, s0, 0x80080
	v_lshl_add_u64 v[214:215], v[216:217], 0, s[12:13]
	s_addc_u32 s1, s1, 0
	s_add_i32 s57, s65, s3
	global_load_lds_dwordx4 v[214:215], off
	v_lshl_add_u64 v[214:215], s[0:1], 0, v[132:133]
	s_mov_b32 m0, s57
	s_nop 0
	global_load_lds_dwordx4 v[214:215], off
	v_lshl_add_u64 v[214:215], s[0:1], 0, v[128:129]
	s_add_i32 m0, s57, 0x2000
	s_nop 0
	global_load_lds_dwordx4 v[214:215], off
	v_lshl_add_u64 v[214:215], v[218:219], 0, s[12:13]
	s_mov_b32 m0, s41
	s_nop 0
	global_load_lds_dwordx4 v[214:215], off
	v_lshl_add_u64 v[214:215], v[220:221], 0, s[12:13]
	s_mov_b32 m0, s42
	s_nop 0
	global_load_lds_dwordx4 v[214:215], off
	s_waitcnt vmcnt(8)
	s_waitcnt lgkmcnt(0)
	s_barrier
	s_setprio 1
	s_waitcnt lgkmcnt(0)
	v_mfma_f32_16x16x32_bf16 v[60:63], v[144:147], v[182:185], v[60:63]
	v_mfma_f32_16x16x32_bf16 v[56:59], v[158:161], v[182:185], v[56:59]
	v_mfma_f32_16x16x32_bf16 v[44:47], v[144:147], v[190:193], v[44:47]
	v_mfma_f32_16x16x32_bf16 v[40:43], v[158:161], v[190:193], v[40:43]
	v_mfma_f32_16x16x32_bf16 v[28:31], v[144:147], v[198:201], v[28:31]
	v_mfma_f32_16x16x32_bf16 v[24:27], v[158:161], v[198:201], v[24:27]
	v_mfma_f32_16x16x32_bf16 v[12:15], v[144:147], v[206:209], v[12:15]
	v_mfma_f32_16x16x32_bf16 v[8:11], v[158:161], v[206:209], v[8:11]
	v_mfma_f32_16x16x32_bf16 v[60:63], v[148:151], v[186:189], v[60:63]
	v_mfma_f32_16x16x32_bf16 v[56:59], v[162:165], v[186:189], v[56:59]
	v_mfma_f32_16x16x32_bf16 v[44:47], v[148:151], v[194:197], v[44:47]
	v_mfma_f32_16x16x32_bf16 v[40:43], v[162:165], v[194:197], v[40:43]
	v_mfma_f32_16x16x32_bf16 v[28:31], v[148:151], v[202:205], v[28:31]
	v_mfma_f32_16x16x32_bf16 v[24:27], v[162:165], v[202:205], v[24:27]
	v_mfma_f32_16x16x32_bf16 v[12:15], v[148:151], v[210:213], v[12:15]
	v_mfma_f32_16x16x32_bf16 v[8:11], v[162:165], v[210:213], v[8:11]
	s_setprio 0
	s_setprio 1
	v_mfma_f32_16x16x32_bf16 v[52:55], v[166:169], v[182:185], v[52:55]
	v_mfma_f32_16x16x32_bf16 v[48:51], v[174:177], v[182:185], v[48:51]
	v_mfma_f32_16x16x32_bf16 v[36:39], v[166:169], v[190:193], v[36:39]
	v_mfma_f32_16x16x32_bf16 v[32:35], v[174:177], v[190:193], v[32:35]
	v_mfma_f32_16x16x32_bf16 v[20:23], v[166:169], v[198:201], v[20:23]
	v_mfma_f32_16x16x32_bf16 v[16:19], v[174:177], v[198:201], v[16:19]
	v_mfma_f32_16x16x32_bf16 v[4:7], v[166:169], v[206:209], v[4:7]
	v_mfma_f32_16x16x32_bf16 v[0:3], v[174:177], v[206:209], v[0:3]
	v_mfma_f32_16x16x32_bf16 v[52:55], v[170:173], v[186:189], v[52:55]
	v_mfma_f32_16x16x32_bf16 v[48:51], v[178:181], v[186:189], v[48:51]
	v_mfma_f32_16x16x32_bf16 v[36:39], v[170:173], v[194:197], v[36:39]
	v_mfma_f32_16x16x32_bf16 v[32:35], v[178:181], v[194:197], v[32:35]
	v_mfma_f32_16x16x32_bf16 v[20:23], v[170:173], v[202:205], v[20:23]
	v_mfma_f32_16x16x32_bf16 v[16:19], v[178:181], v[202:205], v[16:19]
	v_mfma_f32_16x16x32_bf16 v[4:7], v[170:173], v[210:213], v[4:7]
	v_mfma_f32_16x16x32_bf16 v[0:3], v[178:181], v[210:213], v[0:3]
	s_setprio 0
	s_barrier
	s_add_i32 s56, s56, 2
	s_add_u32 s80, s80, 0x100
	s_addc_u32 s81, s81, 0
	s_add_u32 s54, s54, 0x100
	s_addc_u32 s55, s55, 0
	s_cmp_gt_u32 s56, 29
	s_cbranch_scc0 .LBB0_95
	s_and_b64 vcc, exec, s[14:15]
	s_cbranch_vccz .LBB0_98
	s_barrier

; #define PG8_STAGE(bufoff, gbase, voff) do { _Pragma("unroll") for (int _i = 0; _i < 2; ++_i) \
;         __builtin_amdgcn_global_load_lds((const unsigned*)((const char*)(gbase) + (voff)[_i]), (PG8_LAS unsigned*)(lds + (bufoff) + ldsw + _i * 8192), 16, 0, 0); } while (0)
; #define PG8_LDA(dst, b, h) do { _Pragma("unroll") for (int m = 0; m < 4; ++m) _Pragma("unroll") for (int k = 0; k < 2; ++k) dst[m][k] = *(const PG8_LAS bf16x8*)(lds + PG8_SA(b, h) + aoff + m * 2048 + k * 1024); } while (0)
; #define PG8_LDB(dst, b, h) do { _Pragma("unroll") for (int n = 0; n < 2; ++n) _Pragma("unroll") for (int k = 0; k < 2; ++k) dst[n][k] = *(const PG8_LAS bf16x8*)(lds + PG8_SB(b, h) + boff + n * 2048 + k * 1024); } while (0)
; #define PG8_MMA(ai, bj, At, Bt) do { __builtin_amdgcn_s_setprio(1); _Pragma("unroll") for (int m = 0; m < 4; ++m) _Pragma("unroll") for (int n = 0; n < 2; ++n) _Pragma("unroll") for (int k = 0; k < 2; ++k) \
;         acc[ai][bj][m][n] = __builtin_amdgcn_mfma_f32_16x16x32_bf16(Bt[n][k], At[m][k], acc[ai][bj][m][n], 0, 0, 0); __builtin_amdgcn_s_setprio(0); } while (0)
; #define PG8_WAIT_V(n) asm volatile("s_waitcnt vmcnt(" #n ")" ::: "memory")
; #define PG8_WAIT_L(n) asm volatile("s_waitcnt lgkmcnt(" #n ")" ::: "memory")
; #define PG8_BAR __builtin_amdgcn_s_barrier()
; #define PG8_SCHED __builtin_amdgcn_sched_barrier(0)
; template <class Epi, class Sched, bool ALIGN_EPI = false, bool SP2 = false>
; __device__ __forceinline__ void gemm_phase(PG8_LAS unsigned char* lds, const Gemm g, const Sched& S, const Epi& E) {
;     ...
;             PG8_LDB(B0, 0, 0); PG8_LDB(B1, 0, 1); PG8_SCHED; PG8_LDA(At, 0, 0); PG8_STAGE(PG8_SA(1, 1), a1 + hstep, voffA);
;             PG8_WAIT_V(8); PG8_WAIT_L(0); PG8_BAR; PG8_MMA(0, 0, At, B0); PG8_MMA(0, 1, At, B1); PG8_BAR; PG8_SCHED;
;             PG8_LDA(At, 0, 1); PG8_STAGE(PG8_SB(0, 0), b2, voffB); PG8_STAGE(PG8_SB(0, 1), b2 + hstep, voffB); PG8_STAGE(PG8_SA(0, 0), a2, voffA);
.LBB0_177:
	ds_read_b128 v[128:131], v203
	ds_read_b128 v[132:135], v203 offset:1024
	ds_read_b128 v[136:139], v203 offset:2048
	ds_read_b128 v[140:143], v203 offset:3072
	ds_read_b128 v[144:147], v204
	ds_read_b128 v[148:151], v204 offset:1024
	ds_read_b128 v[152:155], v204 offset:2048
	ds_read_b128 v[156:159], v204 offset:3072
	s_add_u32 s0, s50, 0x100
	s_addc_u32 s1, s51, 0
	s_cmpk_eq_i32 s56, 0x54
	s_cselect_b32 s81, s11, s1
	s_cselect_b32 s80, s10, s0
	s_cselect_b32 s25, s75, s55
	s_cselect_b32 s24, s74, s54
	v_lshl_add_u64 v[212:213], s[50:51], 0, v[180:181]
	s_add_i32 m0, s33, 0xc000
	ds_read_b128 v[160:163], v205
	ds_read_b128 v[164:167], v205 offset:1024
	ds_read_b128 v[168:171], v205 offset:2048
	ds_read_b128 v[172:175], v205 offset:3072
	ds_read_b128 v[188:191], v205 offset:4096
	ds_read_b128 v[192:195], v205 offset:5120
	ds_read_b128 v[196:199], v205 offset:6144
	ds_read_b128 v[208:211], v205 offset:7168
	global_load_lds_dwordx4 v[212:213], off
	v_lshl_add_u64 v[212:213], s[50:51], 0, v[182:183]
	s_add_i32 m0, s33, 0xe000
	s_nop 0
	global_load_lds_dwordx4 v[212:213], off
	s_waitcnt vmcnt(8)
	s_waitcnt lgkmcnt(0)
	s_barrier
	s_setprio 1
	s_waitcnt lgkmcnt(0)
	v_mfma_f32_16x16x32_bf16 v[124:127], v[128:131], v[160:163], v[124:127]
	v_mfma_f32_16x16x32_bf16 v[120:123], v[136:139], v[160:163], v[120:123]
	v_mfma_f32_16x16x32_bf16 v[108:111], v[128:131], v[168:171], v[108:111]
	v_mfma_f32_16x16x32_bf16 v[104:107], v[136:139], v[168:171], v[104:107]
	v_mfma_f32_16x16x32_bf16 v[92:95], v[128:131], v[188:191], v[92:95]
	v_mfma_f32_16x16x32_bf16 v[88:91], v[136:139], v[188:191], v[88:91]
	v_mfma_f32_16x16x32_bf16 v[76:79], v[128:131], v[196:199], v[76:79]
	v_mfma_f32_16x16x32_bf16 v[72:75], v[136:139], v[196:199], v[72:75]
	v_mfma_f32_16x16x32_bf16 v[124:127], v[132:135], v[164:167], v[124:127]
	v_mfma_f32_16x16x32_bf16 v[120:123], v[140:143], v[164:167], v[120:123]
	v_mfma_f32_16x16x32_bf16 v[108:111], v[132:135], v[172:175], v[108:111]
	v_mfma_f32_16x16x32_bf16 v[104:107], v[140:143], v[172:175], v[104:107]
	v_mfma_f32_16x16x32_bf16 v[92:95], v[132:135], v[192:195], v[92:95]
	v_mfma_f32_16x16x32_bf16 v[88:91], v[140:143], v[192:195], v[88:91]
	v_mfma_f32_16x16x32_bf16 v[76:79], v[132:135], v[208:211], v[76:79]
	v_mfma_f32_16x16x32_bf16 v[72:75], v[140:143], v[208:211], v[72:75]
	s_setprio 0
	s_setprio 1
	v_mfma_f32_16x16x32_bf16 v[116:119], v[144:147], v[160:163], v[116:119]
	v_mfma_f32_16x16x32_bf16 v[112:115], v[152:155], v[160:163], v[112:115]
	v_mfma_f32_16x16x32_bf16 v[100:103], v[144:147], v[168:171], v[100:103]
	v_mfma_f32_16x16x32_bf16 v[96:99], v[152:155], v[168:171], v[96:99]
	v_mfma_f32_16x16x32_bf16 v[84:87], v[144:147], v[188:191], v[84:87]
	v_mfma_f32_16x16x32_bf16 v[80:83], v[152:155], v[188:191], v[80:83]
	v_mfma_f32_16x16x32_bf16 v[68:71], v[144:147], v[196:199], v[68:71]
	v_mfma_f32_16x16x32_bf16 v[64:67], v[152:155], v[196:199], v[64:67]
	v_mfma_f32_16x16x32_bf16 v[116:119], v[148:151], v[164:167], v[116:119]
	v_mfma_f32_16x16x32_bf16 v[112:115], v[156:159], v[164:167], v[112:115]
	v_mfma_f32_16x16x32_bf16 v[100:103], v[148:151], v[172:175], v[100:103]
	v_mfma_f32_16x16x32_bf16 v[96:99], v[156:159], v[172:175], v[96:99]
	v_mfma_f32_16x16x32_bf16 v[84:87], v[148:151], v[192:195], v[84:87]
	v_mfma_f32_16x16x32_bf16 v[80:83], v[156:159], v[192:195], v[80:83]
	v_mfma_f32_16x16x32_bf16 v[68:71], v[148:151], v[208:211], v[68:71]
	v_mfma_f32_16x16x32_bf16 v[64:67], v[156:159], v[208:211], v[64:67]
	s_setprio 0
	s_barrier
	s_add_i32 s50, s44, s3
	v_lshl_add_u64 v[212:213], s[24:25], 0, v[176:177]
	s_mov_b32 m0, s50
	ds_read_b128 v[160:163], v205 offset:16384
	ds_read_b128 v[164:167], v205 offset:17408
	ds_read_b128 v[168:171], v205 offset:18432
	ds_read_b128 v[172:175], v205 offset:19456
	ds_read_b128 v[188:191], v205 offset:20480
	ds_read_b128 v[192:195], v205 offset:21504
	ds_read_b128 v[196:199], v205 offset:22528
	ds_read_b128 v[208:211], v205 offset:23552
	global_load_lds_dwordx4 v[212:213], off
	s_add_i32 m0, s50, 0x2000
	s_add_u32 s50, s24, 0x160000
	v_lshl_add_u64 v[214:215], s[24:25], 0, v[178:179]
	s_addc_u32 s51, s25, 0
	s_add_i32 s57, s45, s3
	global_load_lds_dwordx4 v[214:215], off
	v_lshl_add_u64 v[216:217], s[50:51], 0, v[176:177]
	s_mov_b32 m0, s57
	v_lshl_add_u64 v[218:219], s[80:81], 0, v[178:179]
	global_load_lds_dwordx4 v[216:217], off
	v_lshl_add_u64 v[216:217], s[50:51], 0, v[178:179]
	s_add_i32 m0, s57, 0x2000
	s_nop 0
	global_load_lds_dwordx4 v[216:217], off
	v_lshl_add_u64 v[216:217], s[80:81], 0, v[176:177]
	s_mov_b32 m0, s33
	s_nop 0
	global_load_lds_dwordx4 v[216:217], off
	s_mov_b32 m0, s35
	s_nop 0
	global_load_lds_dwordx4 v[218:219], off
	s_waitcnt vmcnt(8)
	s_waitcnt lgkmcnt(0)
	s_barrier
; #define PG8_STAGE(bufoff, gbase, voff) do { _Pragma("unroll") for (int _i = 0; _i < 2; ++_i) \
;         __builtin_amdgcn_global_load_lds((const unsigned*)((const char*)(gbase) + (voff)[_i]), (PG8_LAS unsigned*)(lds + (bufoff) + ldsw + _i * 8192), 16, 0, 0); } while (0)
; #define PG8_LDA(dst, b, h) do { _Pragma("unroll") for (int m = 0; m < 4; ++m) _Pragma("unroll") for (int k = 0; k < 2; ++k) dst[m][k] = *(const PG8_LAS bf16x8*)(lds + PG8_SA(b, h) + aoff + m * 2048 + k * 1024); } while (0)
; #define PG8_LDB(dst, b, h) do { _Pragma("unroll") for (int n = 0; n < 2; ++n) _Pragma("unroll") for (int k = 0; k < 2; ++k) dst[n][k] = *(const PG8_LAS bf16x8*)(lds + PG8_SB(b, h) + boff + n * 2048 + k * 1024); } while (0)
; #define PG8_MMA(ai, bj, At, Bt) do { __builtin_amdgcn_s_setprio(1); _Pragma("unroll") for (int m = 0; m < 4; ++m) _Pragma("unroll") for (int n = 0; n < 2; ++n) _Pragma("unroll") for (int k = 0; k < 2; ++k) \
;         acc[ai][bj][m][n] = __builtin_amdgcn_mfma_f32_16x16x32_bf16(Bt[n][k], At[m][k], acc[ai][bj][m][n], 0, 0, 0); __builtin_amdgcn_s_setprio(0); } while (0)
; #define PG8_WAIT_V(n) asm volatile("s_waitcnt vmcnt(" #n ")" ::: "memory")
; #define PG8_WAIT_L(n) asm volatile("s_waitcnt lgkmcnt(" #n ")" ::: "memory")
; #define PG8_BAR __builtin_amdgcn_s_barrier()
; #define PG8_SCHED __builtin_amdgcn_sched_barrier(0)
; template <class Epi, class Sched, bool ALIGN_EPI = false, bool SP2 = false>
; __device__ __forceinline__ void gemm_phase(PG8_LAS unsigned char* lds, const Gemm g, const Sched& S, const Epi& E) {
;     ...
;             PG8_WAIT_V(8); PG8_WAIT_L(0); PG8_BAR; PG8_MMA(1, 0, At, B0); PG8_MMA(1, 1, At, B1); PG8_BAR; PG8_SCHED;
;             PG8_LDB(B0, 1, 0); PG8_LDB(B1, 1, 1); PG8_SCHED; PG8_LDA(At, 1, 0); PG8_STAGE(PG8_SA(0, 1), a2 + hstep, voffA);
;             PG8_WAIT_V(8); PG8_WAIT_L(0); PG8_BAR; PG8_MMA(0, 0, At, B0); PG8_MMA(0, 1, At, B1); PG8_BAR; PG8_SCHED;
	s_setprio 1
	s_nop 0
	s_waitcnt lgkmcnt(0)
	v_mfma_f32_16x16x32_bf16 v[60:63], v[128:131], v[160:163], v[60:63]
	v_mfma_f32_16x16x32_bf16 v[56:59], v[136:139], v[160:163], v[56:59]
	v_mfma_f32_16x16x32_bf16 v[44:47], v[128:131], v[168:171], v[44:47]
	v_mfma_f32_16x16x32_bf16 v[40:43], v[136:139], v[168:171], v[40:43]
	v_mfma_f32_16x16x32_bf16 v[28:31], v[128:131], v[188:191], v[28:31]
	v_mfma_f32_16x16x32_bf16 v[24:27], v[136:139], v[188:191], v[24:27]
	v_mfma_f32_16x16x32_bf16 v[12:15], v[128:131], v[196:199], v[12:15]
	v_mfma_f32_16x16x32_bf16 v[8:11], v[136:139], v[196:199], v[8:11]
	v_mfma_f32_16x16x32_bf16 v[60:63], v[132:135], v[164:167], v[60:63]
	v_mfma_f32_16x16x32_bf16 v[56:59], v[140:143], v[164:167], v[56:59]
	v_mfma_f32_16x16x32_bf16 v[44:47], v[132:135], v[172:175], v[44:47]
	v_mfma_f32_16x16x32_bf16 v[40:43], v[140:143], v[172:175], v[40:43]
	v_mfma_f32_16x16x32_bf16 v[28:31], v[132:135], v[192:195], v[28:31]
	v_mfma_f32_16x16x32_bf16 v[24:27], v[140:143], v[192:195], v[24:27]
	v_mfma_f32_16x16x32_bf16 v[12:15], v[132:135], v[208:211], v[12:15]
	v_mfma_f32_16x16x32_bf16 v[8:11], v[140:143], v[208:211], v[8:11]
	s_setprio 0
	s_setprio 1
	v_mfma_f32_16x16x32_bf16 v[52:55], v[144:147], v[160:163], v[52:55]
	v_mfma_f32_16x16x32_bf16 v[48:51], v[152:155], v[160:163], v[48:51]
	v_mfma_f32_16x16x32_bf16 v[36:39], v[144:147], v[168:171], v[36:39]
	v_mfma_f32_16x16x32_bf16 v[32:35], v[152:155], v[168:171], v[32:35]
	v_mfma_f32_16x16x32_bf16 v[20:23], v[144:147], v[188:191], v[20:23]
	v_mfma_f32_16x16x32_bf16 v[16:19], v[152:155], v[188:191], v[16:19]
	v_mfma_f32_16x16x32_bf16 v[4:7], v[144:147], v[196:199], v[4:7]
	v_mfma_f32_16x16x32_bf16 v[0:3], v[152:155], v[196:199], v[0:3]
	v_mfma_f32_16x16x32_bf16 v[52:55], v[148:151], v[164:167], v[52:55]
	v_mfma_f32_16x16x32_bf16 v[48:51], v[156:159], v[164:167], v[48:51]
	v_mfma_f32_16x16x32_bf16 v[36:39], v[148:151], v[172:175], v[36:39]
	v_mfma_f32_16x16x32_bf16 v[32:35], v[156:159], v[172:175], v[32:35]
	v_mfma_f32_16x16x32_bf16 v[20:23], v[148:151], v[192:195], v[20:23]
	v_mfma_f32_16x16x32_bf16 v[16:19], v[156:159], v[192:195], v[16:19]
	v_mfma_f32_16x16x32_bf16 v[4:7], v[148:151], v[208:211], v[4:7]
	v_mfma_f32_16x16x32_bf16 v[0:3], v[156:159], v[208:211], v[0:3]
	s_setprio 0
	s_barrier
	s_add_i32 s57, 0, 0x18000
	s_add_i32 s58, 0, 0x1c000
	v_add_u32_e32 v140, s57, v201
	v_add_u32_e32 v156, s58, v201
	ds_read_b128 v[128:131], v140
	ds_read_b128 v[132:135], v140 offset:1024
	ds_read_b128 v[136:139], v140 offset:2048
	ds_read_b128 v[140:143], v140 offset:3072
	ds_read_b128 v[144:147], v156
	ds_read_b128 v[148:151], v156 offset:1024
	ds_read_b128 v[152:155], v156 offset:2048
	ds_read_b128 v[156:159], v156 offset:3072
	s_add_u32 s50, s80, 0x160000
	s_addc_u32 s51, s81, 0
	s_mov_b32 m0, s36
	v_lshl_add_u64 v[220:221], s[50:51], 0, v[176:177]
	ds_read_b128 v[160:163], v205 offset:32768
	ds_read_b128 v[164:167], v205 offset:33792
	ds_read_b128 v[168:171], v205 offset:34816
	ds_read_b128 v[172:175], v205 offset:35840
	ds_read_b128 v[188:191], v205 offset:36864
	ds_read_b128 v[192:195], v205 offset:37888
	ds_read_b128 v[196:199], v205 offset:38912
	ds_read_b128 v[208:211], v205 offset:39936
	global_load_lds_dwordx4 v[220:221], off
	v_lshl_add_u64 v[220:221], s[50:51], 0, v[178:179]
	s_mov_b32 m0, s37
	s_nop 0
	global_load_lds_dwordx4 v[220:221], off
	s_waitcnt vmcnt(8)
	s_waitcnt lgkmcnt(0)
	s_barrier
	s_setprio 1
	s_nop 0
	s_waitcnt lgkmcnt(0)
	v_mfma_f32_16x16x32_bf16 v[124:127], v[128:131], v[160:163], v[124:127]
	v_mfma_f32_16x16x32_bf16 v[120:123], v[136:139], v[160:163], v[120:123]
	v_mfma_f32_16x16x32_bf16 v[108:111], v[128:131], v[168:171], v[108:111]
	v_mfma_f32_16x16x32_bf16 v[104:107], v[136:139], v[168:171], v[104:107]
	v_mfma_f32_16x16x32_bf16 v[92:95], v[128:131], v[188:191], v[92:95]
	v_mfma_f32_16x16x32_bf16 v[88:91], v[136:139], v[188:191], v[88:91]
	v_mfma_f32_16x16x32_bf16 v[76:79], v[128:131], v[196:199], v[76:79]
	v_mfma_f32_16x16x32_bf16 v[72:75], v[136:139], v[196:199], v[72:75]
	v_mfma_f32_16x16x32_bf16 v[124:127], v[132:135], v[164:167], v[124:127]
	v_mfma_f32_16x16x32_bf16 v[120:123], v[140:143], v[164:167], v[120:123]
	v_mfma_f32_16x16x32_bf16 v[108:111], v[132:135], v[172:175], v[108:111]
	v_mfma_f32_16x16x32_bf16 v[104:107], v[140:143], v[172:175], v[104:107]
	v_mfma_f32_16x16x32_bf16 v[92:95], v[132:135], v[192:195], v[92:95]
	v_mfma_f32_16x16x32_bf16 v[88:91], v[140:143], v[192:195], v[88:91]
	v_mfma_f32_16x16x32_bf16 v[76:79], v[132:135], v[208:211], v[76:79]
	v_mfma_f32_16x16x32_bf16 v[72:75], v[140:143], v[208:211], v[72:75]
	s_setprio 0
	s_setprio 1
	v_mfma_f32_16x16x32_bf16 v[116:119], v[144:147], v[160:163], v[116:119]
	v_mfma_f32_16x16x32_bf16 v[112:115], v[152:155], v[160:163], v[112:115]
	v_mfma_f32_16x16x32_bf16 v[100:103], v[144:147], v[168:171], v[100:103]
	v_mfma_f32_16x16x32_bf16 v[96:99], v[152:155], v[168:171], v[96:99]
	v_mfma_f32_16x16x32_bf16 v[84:87], v[144:147], v[188:191], v[84:87]
	v_mfma_f32_16x16x32_bf16 v[80:83], v[152:155], v[188:191], v[80:83]
	v_mfma_f32_16x16x32_bf16 v[68:71], v[144:147], v[196:199], v[68:71]
	v_mfma_f32_16x16x32_bf16 v[64:67], v[152:155], v[196:199], v[64:67]
	v_mfma_f32_16x16x32_bf16 v[116:119], v[148:151], v[164:167], v[116:119]
	v_mfma_f32_16x16x32_bf16 v[112:115], v[156:159], v[164:167], v[112:115]
	v_mfma_f32_16x16x32_bf16 v[100:103], v[148:151], v[172:175], v[100:103]
	v_mfma_f32_16x16x32_bf16 v[96:99], v[156:159], v[172:175], v[96:99]
	v_mfma_f32_16x16x32_bf16 v[84:87], v[148:151], v[192:195], v[84:87]
	v_mfma_f32_16x16x32_bf16 v[80:83], v[156:159], v[192:195], v[80:83]
	v_mfma_f32_16x16x32_bf16 v[68:71], v[148:151], v[208:211], v[68:71]
	v_mfma_f32_16x16x32_bf16 v[64:67], v[156:159], v[208:211], v[64:67]
	s_setprio 0
	s_barrier
; #define PG8_STAGE(bufoff, gbase, voff) do { _Pragma("unroll") for (int _i = 0; _i < 2; ++_i) \
;         __builtin_amdgcn_global_load_lds((const unsigned*)((const char*)(gbase) + (voff)[_i]), (PG8_LAS unsigned*)(lds + (bufoff) + ldsw + _i * 8192), 16, 0, 0); } while (0)
; #define PG8_LDA(dst, b, h) do { _Pragma("unroll") for (int m = 0; m < 4; ++m) _Pragma("unroll") for (int k = 0; k < 2; ++k) dst[m][k] = *(const PG8_LAS bf16x8*)(lds + PG8_SA(b, h) + aoff + m * 2048 + k * 1024); } while (0)
; #define PG8_MMA(ai, bj, At, Bt) do { __builtin_amdgcn_s_setprio(1); _Pragma("unroll") for (int m = 0; m < 4; ++m) _Pragma("unroll") for (int n = 0; n < 2; ++n) _Pragma("unroll") for (int k = 0; k < 2; ++k) \
;         acc[ai][bj][m][n] = __builtin_amdgcn_mfma_f32_16x16x32_bf16(Bt[n][k], At[m][k], acc[ai][bj][m][n], 0, 0, 0); __builtin_amdgcn_s_setprio(0); } while (0)
; #define PG8_WAIT_V(n) asm volatile("s_waitcnt vmcnt(" #n ")" ::: "memory")
; #define PG8_WAIT_L(n) asm volatile("s_waitcnt lgkmcnt(" #n ")" ::: "memory")
; #define PG8_BAR __builtin_amdgcn_s_barrier()
; #define PG8_SCHED __builtin_amdgcn_sched_barrier(0)
; template <class Epi, class Sched, bool ALIGN_EPI = false, bool SP2 = false>
; __device__ __forceinline__ void gemm_phase(PG8_LAS unsigned char* lds, const Gemm g, const Sched& S, const Epi& E) {
;     ...
;         for (int t = 0; t < nt; t += 2) {
;     ...
;             PG8_LDA(At, 1, 1); PG8_STAGE(PG8_SB(1, 0), b3, voffB); PG8_STAGE(PG8_SB(1, 1), b3 + hstep, voffB); PG8_STAGE(PG8_SA(1, 0), a3, voffA);
;             PG8_WAIT_V(8); PG8_WAIT_L(0); PG8_BAR; PG8_MMA(1, 0, At, B0); PG8_MMA(1, 1, At, B1); PG8_BAR; PG8_SCHED;
;     ...
;         if constexpr (ALIGN_EPI) { if (wr == 0) PG8_BAR; }
	s_add_i32 s50, s57, s3
	v_lshl_add_u64 v[212:213], v[212:213], 0, s[14:15]
	s_mov_b32 m0, s50
	ds_read_b128 v[160:163], v205 offset:49152
	ds_read_b128 v[164:167], v205 offset:50176
	ds_read_b128 v[168:171], v205 offset:51200
	ds_read_b128 v[172:175], v205 offset:52224
	ds_read_b128 v[188:191], v205 offset:53248
	ds_read_b128 v[192:195], v205 offset:54272
	ds_read_b128 v[196:199], v205 offset:55296
	ds_read_b128 v[208:211], v205 offset:56320
	global_load_lds_dwordx4 v[212:213], off
	s_add_i32 m0, s50, 0x2000
	s_add_u32 s24, s24, 0x160080
	v_lshl_add_u64 v[212:213], v[214:215], 0, s[14:15]
	s_addc_u32 s25, s25, 0
	s_add_i32 s50, s58, s3
	global_load_lds_dwordx4 v[212:213], off
	v_lshl_add_u64 v[212:213], s[24:25], 0, v[176:177]
	s_mov_b32 m0, s50
	s_nop 0
	global_load_lds_dwordx4 v[212:213], off
	v_lshl_add_u64 v[212:213], s[24:25], 0, v[178:179]
	s_add_i32 m0, s50, 0x2000
	s_nop 0
	global_load_lds_dwordx4 v[212:213], off
	v_lshl_add_u64 v[212:213], v[216:217], 0, s[14:15]
	s_mov_b32 m0, s39
	s_nop 0
	global_load_lds_dwordx4 v[212:213], off
	v_lshl_add_u64 v[212:213], v[218:219], 0, s[14:15]
	s_mov_b32 m0, s40
	s_nop 0
	global_load_lds_dwordx4 v[212:213], off
	s_waitcnt vmcnt(8)
	s_waitcnt lgkmcnt(0)
	s_barrier
	s_setprio 1
	s_waitcnt lgkmcnt(0)
	v_mfma_f32_16x16x32_bf16 v[60:63], v[128:131], v[160:163], v[60:63]
	v_mfma_f32_16x16x32_bf16 v[56:59], v[136:139], v[160:163], v[56:59]
	v_mfma_f32_16x16x32_bf16 v[44:47], v[128:131], v[168:171], v[44:47]
	v_mfma_f32_16x16x32_bf16 v[40:43], v[136:139], v[168:171], v[40:43]
	v_mfma_f32_16x16x32_bf16 v[28:31], v[128:131], v[188:191], v[28:31]
	v_mfma_f32_16x16x32_bf16 v[24:27], v[136:139], v[188:191], v[24:27]
	v_mfma_f32_16x16x32_bf16 v[12:15], v[128:131], v[196:199], v[12:15]
	v_mfma_f32_16x16x32_bf16 v[8:11], v[136:139], v[196:199], v[8:11]
	v_mfma_f32_16x16x32_bf16 v[60:63], v[132:135], v[164:167], v[60:63]
	v_mfma_f32_16x16x32_bf16 v[56:59], v[140:143], v[164:167], v[56:59]
	v_mfma_f32_16x16x32_bf16 v[44:47], v[132:135], v[172:175], v[44:47]
	v_mfma_f32_16x16x32_bf16 v[40:43], v[140:143], v[172:175], v[40:43]
	v_mfma_f32_16x16x32_bf16 v[28:31], v[132:135], v[192:195], v[28:31]
	v_mfma_f32_16x16x32_bf16 v[24:27], v[140:143], v[192:195], v[24:27]
	v_mfma_f32_16x16x32_bf16 v[12:15], v[132:135], v[208:211], v[12:15]
	v_mfma_f32_16x16x32_bf16 v[8:11], v[140:143], v[208:211], v[8:11]
	s_setprio 0
	s_setprio 1
	v_mfma_f32_16x16x32_bf16 v[52:55], v[144:147], v[160:163], v[52:55]
	v_mfma_f32_16x16x32_bf16 v[48:51], v[152:155], v[160:163], v[48:51]
	v_mfma_f32_16x16x32_bf16 v[36:39], v[144:147], v[168:171], v[36:39]
	v_mfma_f32_16x16x32_bf16 v[32:35], v[152:155], v[168:171], v[32:35]
	v_mfma_f32_16x16x32_bf16 v[20:23], v[144:147], v[188:191], v[20:23]
	v_mfma_f32_16x16x32_bf16 v[16:19], v[152:155], v[188:191], v[16:19]
	v_mfma_f32_16x16x32_bf16 v[4:7], v[144:147], v[196:199], v[4:7]
	v_mfma_f32_16x16x32_bf16 v[0:3], v[152:155], v[196:199], v[0:3]
	v_mfma_f32_16x16x32_bf16 v[52:55], v[148:151], v[164:167], v[52:55]
	v_mfma_f32_16x16x32_bf16 v[48:51], v[156:159], v[164:167], v[48:51]
	v_mfma_f32_16x16x32_bf16 v[36:39], v[148:151], v[172:175], v[36:39]
	v_mfma_f32_16x16x32_bf16 v[32:35], v[156:159], v[172:175], v[32:35]
	v_mfma_f32_16x16x32_bf16 v[20:23], v[148:151], v[192:195], v[20:23]
	v_mfma_f32_16x16x32_bf16 v[16:19], v[156:159], v[192:195], v[16:19]
	v_mfma_f32_16x16x32_bf16 v[4:7], v[148:151], v[208:211], v[4:7]
	v_mfma_f32_16x16x32_bf16 v[0:3], v[156:159], v[208:211], v[0:3]
	s_setprio 0
	s_barrier
	s_add_i32 s56, s56, 2
	s_add_u32 s54, s54, 0x100
	s_addc_u32 s55, s55, 0
	s_cmpk_gt_u32 s56, 0x55
	s_mov_b64 s[50:51], s[0:1]
	s_cbranch_scc0 .LBB0_177
	s_and_b64 vcc, exec, s[20:21]
	s_cbranch_vccz .LBB0_180
	s_barrier

; #define PG8_STAGE(bufoff, gbase, voff) do { _Pragma("unroll") for (int _i = 0; _i < 2; ++_i) \
;         __builtin_amdgcn_global_load_lds((const unsigned*)((const char*)(gbase) + (voff)[_i]), (PG8_LAS unsigned*)(lds + (bufoff) + ldsw + _i * 8192), 16, 0, 0); } while (0)
; #define PG8_LDA(dst, b, h) do { _Pragma("unroll") for (int m = 0; m < 4; ++m) _Pragma("unroll") for (int k = 0; k < 2; ++k) dst[m][k] = *(const PG8_LAS bf16x8*)(lds + PG8_SA(b, h) + aoff + m * 2048 + k * 1024); } while (0)
; #define PG8_LDB(dst, b, h) do { _Pragma("unroll") for (int n = 0; n < 2; ++n) _Pragma("unroll") for (int k = 0; k < 2; ++k) dst[n][k] = *(const PG8_LAS bf16x8*)(lds + PG8_SB(b, h) + boff + n * 2048 + k * 1024); } while (0)
; #define PG8_MMA(ai, bj, At, Bt) do { __builtin_amdgcn_s_setprio(1); _Pragma("unroll") for (int m = 0; m < 4; ++m) _Pragma("unroll") for (int n = 0; n < 2; ++n) _Pragma("unroll") for (int k = 0; k < 2; ++k) \
;         acc[ai][bj][m][n] = __builtin_amdgcn_mfma_f32_16x16x32_bf16(Bt[n][k], At[m][k], acc[ai][bj][m][n], 0, 0, 0); __builtin_amdgcn_s_setprio(0); } while (0)
; #define PG8_WAIT_V(n) asm volatile("s_waitcnt vmcnt(" #n ")" ::: "memory")
; #define PG8_WAIT_L(n) asm volatile("s_waitcnt lgkmcnt(" #n ")" ::: "memory")
; #define PG8_BAR __builtin_amdgcn_s_barrier()
; #define PG8_SCHED __builtin_amdgcn_sched_barrier(0)
; template <class Epi, class Sched, bool ALIGN_EPI = false, bool SP2 = false>
; __device__ __forceinline__ void gemm_phase(PG8_LAS unsigned char* lds, const Gemm g, const Sched& S, const Epi& E) {
;     ...
;             PG8_LDB(B0, 0, 0); PG8_LDB(B1, 0, 1); PG8_SCHED; PG8_LDA(At, 0, 0); PG8_STAGE(PG8_SA(1, 1), a1 + hstep, voffA);
;             PG8_WAIT_V(8); PG8_WAIT_L(0); PG8_BAR; PG8_MMA(0, 0, At, B0); PG8_MMA(0, 1, At, B1); PG8_BAR; PG8_SCHED;
;             PG8_LDA(At, 0, 1); PG8_STAGE(PG8_SB(0, 0), b2, voffB); PG8_STAGE(PG8_SB(0, 1), b2 + hstep, voffB); PG8_STAGE(PG8_SA(0, 0), a2, voffA);
.LBB0_263:
	ds_read_b128 v[4:7], v208
	ds_read_b128 v[12:15], v208 offset:1024
	ds_read_b128 v[16:19], v208 offset:2048
	ds_read_b128 v[20:23], v208 offset:3072
	ds_read_b128 v[164:167], v209
	ds_read_b128 v[168:171], v209 offset:1024
	ds_read_b128 v[172:175], v209 offset:2048
	ds_read_b128 v[176:179], v209 offset:3072
	s_add_u32 s0, s4, 0xfff80080
	s_addc_u32 s1, s5, -1
	s_cmp_eq_u32 s17, 28
	s_cselect_b32 s7, s3, s1
	s_cselect_b32 s6, s11, s0
	s_cselect_b32 s1, s12, s16
	s_cselect_b32 s0, s13, s15
	v_lshl_add_u64 v[220:221], s[4:5], 0, v[156:157]
	s_add_i32 m0, s25, 0xc000
	ds_read_b128 v[180:183], v210
	ds_read_b128 v[184:187], v210 offset:1024
	ds_read_b128 v[188:191], v210 offset:2048
	ds_read_b128 v[192:195], v210 offset:3072
	ds_read_b128 v[196:199], v210 offset:4096
	ds_read_b128 v[200:203], v210 offset:5120
	ds_read_b128 v[216:219], v210 offset:6144
	ds_read_b128 v[228:231], v210 offset:7168
	global_load_lds_dwordx4 v[220:221], off
	v_lshl_add_u64 v[220:221], s[4:5], 0, v[158:159]
	s_add_i32 m0, s25, 0xe000
	s_nop 0
	global_load_lds_dwordx4 v[220:221], off
	s_waitcnt vmcnt(8)
	s_waitcnt lgkmcnt(0)
	s_barrier
	s_setprio 1
	s_waitcnt lgkmcnt(0)
	v_mfma_f32_16x16x32_bf16 v[140:143], v[4:7], v[180:183], v[140:143]
	v_mfma_f32_16x16x32_bf16 v[136:139], v[16:19], v[180:183], v[136:139]
	v_mfma_f32_16x16x32_bf16 v[124:127], v[4:7], v[188:191], v[124:127]
	v_mfma_f32_16x16x32_bf16 v[120:123], v[16:19], v[188:191], v[120:123]
	v_mfma_f32_16x16x32_bf16 v[108:111], v[4:7], v[196:199], v[108:111]
	v_mfma_f32_16x16x32_bf16 v[104:107], v[16:19], v[196:199], v[104:107]
	v_mfma_f32_16x16x32_bf16 v[92:95], v[4:7], v[216:219], v[92:95]
	v_mfma_f32_16x16x32_bf16 v[88:91], v[16:19], v[216:219], v[88:91]
	v_mfma_f32_16x16x32_bf16 v[140:143], v[12:15], v[184:187], v[140:143]
	v_mfma_f32_16x16x32_bf16 v[136:139], v[20:23], v[184:187], v[136:139]
	v_mfma_f32_16x16x32_bf16 v[124:127], v[12:15], v[192:195], v[124:127]
	v_mfma_f32_16x16x32_bf16 v[120:123], v[20:23], v[192:195], v[120:123]
	v_mfma_f32_16x16x32_bf16 v[108:111], v[12:15], v[200:203], v[108:111]
	v_mfma_f32_16x16x32_bf16 v[104:107], v[20:23], v[200:203], v[104:107]
	v_mfma_f32_16x16x32_bf16 v[92:95], v[12:15], v[228:231], v[92:95]
	v_mfma_f32_16x16x32_bf16 v[88:91], v[20:23], v[228:231], v[88:91]
	s_setprio 0
	s_setprio 1
	v_mfma_f32_16x16x32_bf16 v[132:135], v[164:167], v[180:183], v[132:135]
	v_mfma_f32_16x16x32_bf16 v[128:131], v[172:175], v[180:183], v[128:131]
	v_mfma_f32_16x16x32_bf16 v[116:119], v[164:167], v[188:191], v[116:119]
	v_mfma_f32_16x16x32_bf16 v[112:115], v[172:175], v[188:191], v[112:115]
	v_mfma_f32_16x16x32_bf16 v[100:103], v[164:167], v[196:199], v[100:103]
	v_mfma_f32_16x16x32_bf16 v[96:99], v[172:175], v[196:199], v[96:99]
	v_mfma_f32_16x16x32_bf16 v[84:87], v[164:167], v[216:219], v[84:87]
	v_mfma_f32_16x16x32_bf16 v[80:83], v[172:175], v[216:219], v[80:83]
	v_mfma_f32_16x16x32_bf16 v[132:135], v[168:171], v[184:187], v[132:135]
	v_mfma_f32_16x16x32_bf16 v[128:131], v[176:179], v[184:187], v[128:131]
	v_mfma_f32_16x16x32_bf16 v[116:119], v[168:171], v[192:195], v[116:119]
	v_mfma_f32_16x16x32_bf16 v[112:115], v[176:179], v[192:195], v[112:115]
	v_mfma_f32_16x16x32_bf16 v[100:103], v[168:171], v[200:203], v[100:103]
	v_mfma_f32_16x16x32_bf16 v[96:99], v[176:179], v[200:203], v[96:99]
	v_mfma_f32_16x16x32_bf16 v[84:87], v[168:171], v[228:231], v[84:87]
	v_mfma_f32_16x16x32_bf16 v[80:83], v[176:179], v[228:231], v[80:83]
	s_setprio 0
	s_barrier
	s_add_i32 s20, s54, s24
	v_lshl_add_u64 v[220:221], s[0:1], 0, v[146:147]
	s_mov_b32 m0, s20
	ds_read_b128 v[180:183], v210 offset:16384
	ds_read_b128 v[184:187], v210 offset:17408
	ds_read_b128 v[188:191], v210 offset:18432
	ds_read_b128 v[192:195], v210 offset:19456
	ds_read_b128 v[196:199], v210 offset:20480
	ds_read_b128 v[200:203], v210 offset:21504
	ds_read_b128 v[216:219], v210 offset:22528
	ds_read_b128 v[228:231], v210 offset:23552
	global_load_lds_dwordx4 v[220:221], off
	s_add_i32 m0, s20, 0x2000
	s_add_u32 s36, s0, 0x80000
	v_lshl_add_u64 v[232:233], s[0:1], 0, v[150:151]
	s_addc_u32 s37, s1, 0
	s_add_i32 s20, s55, s24
	global_load_lds_dwordx4 v[232:233], off
	v_lshl_add_u64 v[234:235], s[36:37], 0, v[146:147]
	s_mov_b32 m0, s20
	v_lshl_add_u64 v[236:237], s[6:7], 0, v[148:149]
	global_load_lds_dwordx4 v[234:235], off
	v_lshl_add_u64 v[234:235], s[36:37], 0, v[150:151]
	s_add_i32 m0, s20, 0x2000
	s_nop 0
	global_load_lds_dwordx4 v[234:235], off
	v_lshl_add_u64 v[234:235], s[6:7], 0, v[144:145]
	s_mov_b32 m0, s25
	s_nop 0
	global_load_lds_dwordx4 v[234:235], off
	s_mov_b32 m0, s35
	s_nop 0
	global_load_lds_dwordx4 v[236:237], off
	s_waitcnt vmcnt(8)
	s_waitcnt lgkmcnt(0)
	s_barrier
; #define PG8_STAGE(bufoff, gbase, voff) do { _Pragma("unroll") for (int _i = 0; _i < 2; ++_i) \
;         __builtin_amdgcn_global_load_lds((const unsigned*)((const char*)(gbase) + (voff)[_i]), (PG8_LAS unsigned*)(lds + (bufoff) + ldsw + _i * 8192), 16, 0, 0); } while (0)
; #define PG8_LDA(dst, b, h) do { _Pragma("unroll") for (int m = 0; m < 4; ++m) _Pragma("unroll") for (int k = 0; k < 2; ++k) dst[m][k] = *(const PG8_LAS bf16x8*)(lds + PG8_SA(b, h) + aoff + m * 2048 + k * 1024); } while (0)
; #define PG8_LDB(dst, b, h) do { _Pragma("unroll") for (int n = 0; n < 2; ++n) _Pragma("unroll") for (int k = 0; k < 2; ++k) dst[n][k] = *(const PG8_LAS bf16x8*)(lds + PG8_SB(b, h) + boff + n * 2048 + k * 1024); } while (0)
; #define PG8_MMA(ai, bj, At, Bt) do { __builtin_amdgcn_s_setprio(1); _Pragma("unroll") for (int m = 0; m < 4; ++m) _Pragma("unroll") for (int n = 0; n < 2; ++n) _Pragma("unroll") for (int k = 0; k < 2; ++k) \
;         acc[ai][bj][m][n] = __builtin_amdgcn_mfma_f32_16x16x32_bf16(Bt[n][k], At[m][k], acc[ai][bj][m][n], 0, 0, 0); __builtin_amdgcn_s_setprio(0); } while (0)
; #define PG8_WAIT_V(n) asm volatile("s_waitcnt vmcnt(" #n ")" ::: "memory")
; #define PG8_WAIT_L(n) asm volatile("s_waitcnt lgkmcnt(" #n ")" ::: "memory")
; #define PG8_BAR __builtin_amdgcn_s_barrier()
; #define PG8_SCHED __builtin_amdgcn_sched_barrier(0)
; template <class Epi, class Sched, bool ALIGN_EPI = false, bool SP2 = false>
; __device__ __forceinline__ void gemm_phase(PG8_LAS unsigned char* lds, const Gemm g, const Sched& S, const Epi& E) {
;     ...
;             PG8_WAIT_V(8); PG8_WAIT_L(0); PG8_BAR; PG8_MMA(1, 0, At, B0); PG8_MMA(1, 1, At, B1); PG8_BAR; PG8_SCHED;
;             PG8_LDB(B0, 1, 0); PG8_LDB(B1, 1, 1); PG8_SCHED; PG8_LDA(At, 1, 0); PG8_STAGE(PG8_SA(0, 1), a2 + hstep, voffA);
;             PG8_WAIT_V(8); PG8_WAIT_L(0); PG8_BAR; PG8_MMA(0, 0, At, B0); PG8_MMA(0, 1, At, B1); PG8_BAR; PG8_SCHED;
	s_setprio 1
	s_nop 0
	s_waitcnt lgkmcnt(0)
	v_mfma_f32_16x16x32_bf16 v[76:79], v[4:7], v[180:183], v[76:79]
	v_mfma_f32_16x16x32_bf16 v[72:75], v[16:19], v[180:183], v[72:75]
	v_mfma_f32_16x16x32_bf16 v[60:63], v[4:7], v[188:191], v[60:63]
	v_mfma_f32_16x16x32_bf16 v[56:59], v[16:19], v[188:191], v[56:59]
	v_mfma_f32_16x16x32_bf16 v[44:47], v[4:7], v[196:199], v[44:47]
	v_mfma_f32_16x16x32_bf16 v[40:43], v[16:19], v[196:199], v[40:43]
	v_mfma_f32_16x16x32_bf16 v[4:7], v[4:7], v[216:219], v[28:31]
	v_mfma_f32_16x16x32_bf16 v[76:79], v[12:15], v[184:187], v[76:79]
	v_mfma_f32_16x16x32_bf16 v[72:75], v[20:23], v[184:187], v[72:75]
	v_mfma_f32_16x16x32_bf16 v[60:63], v[12:15], v[192:195], v[60:63]
	v_mfma_f32_16x16x32_bf16 v[56:59], v[20:23], v[192:195], v[56:59]
	v_mfma_f32_16x16x32_bf16 v[44:47], v[12:15], v[200:203], v[44:47]
	v_mfma_f32_16x16x32_bf16 v[40:43], v[20:23], v[200:203], v[40:43]
	v_mfma_f32_16x16x32_bf16 v[4:7], v[12:15], v[228:231], v[4:7]
	v_mfma_f32_16x16x32_bf16 v[12:15], v[16:19], v[216:219], v[24:27]
	v_mfma_f32_16x16x32_bf16 v[12:15], v[20:23], v[228:231], v[12:15]
	s_setprio 0
	s_setprio 1
	v_mfma_f32_16x16x32_bf16 v[24:27], v[164:167], v[188:191], v[52:55]
	v_mfma_f32_16x16x32_bf16 v[52:55], v[168:171], v[192:195], v[24:27]
	v_mfma_f32_16x16x32_bf16 v[24:27], v[172:175], v[188:191], v[48:51]
	v_mfma_f32_16x16x32_bf16 v[48:51], v[176:179], v[192:195], v[24:27]
	v_mfma_f32_16x16x32_bf16 v[24:27], v[164:167], v[196:199], v[36:39]
	v_mfma_f32_16x16x32_bf16 v[36:39], v[168:171], v[200:203], v[24:27]
	v_mfma_f32_16x16x32_bf16 v[24:27], v[172:175], v[196:199], v[32:35]
	v_mfma_f32_16x16x32_bf16 v[8:11], v[164:167], v[216:219], v[8:11]
	v_mfma_f32_16x16x32_bf16 v[0:3], v[172:175], v[216:219], v[0:3]
	v_mfma_f32_16x16x32_bf16 v[16:19], v[164:167], v[180:183], v[68:71]
	v_mfma_f32_16x16x32_bf16 v[20:23], v[172:175], v[180:183], v[64:67]
	v_mfma_f32_16x16x32_bf16 v[32:35], v[176:179], v[200:203], v[24:27]
	v_mfma_f32_16x16x32_bf16 v[8:11], v[168:171], v[228:231], v[8:11]
	v_mfma_f32_16x16x32_bf16 v[0:3], v[176:179], v[228:231], v[0:3]
	v_mfma_f32_16x16x32_bf16 v[16:19], v[168:171], v[184:187], v[16:19]
	v_mfma_f32_16x16x32_bf16 v[20:23], v[176:179], v[184:187], v[20:23]
	s_setprio 0
	s_barrier
	s_add_i32 s20, 0, 0x18000
	s_add_i32 s33, 0, 0x1c000
	v_add_u32_e32 v68, s20, v206
	v_add_u32_e32 v152, s33, v206
	ds_read_b128 v[24:27], v68
	ds_read_b128 v[28:31], v68 offset:1024
	ds_read_b128 v[64:67], v68 offset:2048
	ds_read_b128 v[68:71], v68 offset:3072
	ds_read_b128 v[164:167], v152
	ds_read_b128 v[168:171], v152 offset:1024
	ds_read_b128 v[172:175], v152 offset:2048
	ds_read_b128 v[176:179], v152 offset:3072
	s_add_u32 s6, s6, 0x80000
	s_addc_u32 s7, s7, 0
	s_mov_b32 m0, s65
	v_lshl_add_u64 v[238:239], s[6:7], 0, v[144:145]
	ds_read_b128 v[180:183], v210 offset:32768
	ds_read_b128 v[184:187], v210 offset:33792
	ds_read_b128 v[188:191], v210 offset:34816
	ds_read_b128 v[192:195], v210 offset:35840
	ds_read_b128 v[196:199], v210 offset:36864
	ds_read_b128 v[200:203], v210 offset:37888
	ds_read_b128 v[216:219], v210 offset:38912
	ds_read_b128 v[228:231], v210 offset:39936
	global_load_lds_dwordx4 v[238:239], off
	v_lshl_add_u64 v[238:239], s[6:7], 0, v[148:149]
	s_mov_b32 m0, s59
	s_nop 0
	global_load_lds_dwordx4 v[238:239], off
	s_waitcnt vmcnt(8)
	s_waitcnt lgkmcnt(0)
	s_barrier
	s_setprio 1
	s_nop 0
	s_waitcnt lgkmcnt(0)
	v_mfma_f32_16x16x32_bf16 v[140:143], v[24:27], v[180:183], v[140:143]
	v_mfma_f32_16x16x32_bf16 v[136:139], v[64:67], v[180:183], v[136:139]
	v_mfma_f32_16x16x32_bf16 v[124:127], v[24:27], v[188:191], v[124:127]
	v_mfma_f32_16x16x32_bf16 v[120:123], v[64:67], v[188:191], v[120:123]
	v_mfma_f32_16x16x32_bf16 v[108:111], v[24:27], v[196:199], v[108:111]
	v_mfma_f32_16x16x32_bf16 v[104:107], v[64:67], v[196:199], v[104:107]
	v_mfma_f32_16x16x32_bf16 v[92:95], v[24:27], v[216:219], v[92:95]
	v_mfma_f32_16x16x32_bf16 v[88:91], v[64:67], v[216:219], v[88:91]
	v_mfma_f32_16x16x32_bf16 v[140:143], v[28:31], v[184:187], v[140:143]
	v_mfma_f32_16x16x32_bf16 v[136:139], v[68:71], v[184:187], v[136:139]
	v_mfma_f32_16x16x32_bf16 v[124:127], v[28:31], v[192:195], v[124:127]
	v_mfma_f32_16x16x32_bf16 v[120:123], v[68:71], v[192:195], v[120:123]
	v_mfma_f32_16x16x32_bf16 v[108:111], v[28:31], v[200:203], v[108:111]
	v_mfma_f32_16x16x32_bf16 v[104:107], v[68:71], v[200:203], v[104:107]
	v_mfma_f32_16x16x32_bf16 v[92:95], v[28:31], v[228:231], v[92:95]
	v_mfma_f32_16x16x32_bf16 v[88:91], v[68:71], v[228:231], v[88:91]
	s_setprio 0
	s_setprio 1
	v_mfma_f32_16x16x32_bf16 v[132:135], v[164:167], v[180:183], v[132:135]
	v_mfma_f32_16x16x32_bf16 v[128:131], v[172:175], v[180:183], v[128:131]
	v_mfma_f32_16x16x32_bf16 v[116:119], v[164:167], v[188:191], v[116:119]
	v_mfma_f32_16x16x32_bf16 v[112:115], v[172:175], v[188:191], v[112:115]
	v_mfma_f32_16x16x32_bf16 v[100:103], v[164:167], v[196:199], v[100:103]
	v_mfma_f32_16x16x32_bf16 v[96:99], v[172:175], v[196:199], v[96:99]
	v_mfma_f32_16x16x32_bf16 v[84:87], v[164:167], v[216:219], v[84:87]
	v_mfma_f32_16x16x32_bf16 v[80:83], v[172:175], v[216:219], v[80:83]
	v_mfma_f32_16x16x32_bf16 v[132:135], v[168:171], v[184:187], v[132:135]
	v_mfma_f32_16x16x32_bf16 v[128:131], v[176:179], v[184:187], v[128:131]
	v_mfma_f32_16x16x32_bf16 v[116:119], v[168:171], v[192:195], v[116:119]
	v_mfma_f32_16x16x32_bf16 v[112:115], v[176:179], v[192:195], v[112:115]
	v_mfma_f32_16x16x32_bf16 v[100:103], v[168:171], v[200:203], v[100:103]
	v_mfma_f32_16x16x32_bf16 v[96:99], v[176:179], v[200:203], v[96:99]
	v_mfma_f32_16x16x32_bf16 v[84:87], v[168:171], v[228:231], v[84:87]
	v_mfma_f32_16x16x32_bf16 v[80:83], v[176:179], v[228:231], v[80:83]
	s_setprio 0
	s_barrier
; #define PG8_STAGE(bufoff, gbase, voff) do { _Pragma("unroll") for (int _i = 0; _i < 2; ++_i) \
;         __builtin_amdgcn_global_load_lds((const unsigned*)((const char*)(gbase) + (voff)[_i]), (PG8_LAS unsigned*)(lds + (bufoff) + ldsw + _i * 8192), 16, 0, 0); } while (0)
; #define PG8_LDA(dst, b, h) do { _Pragma("unroll") for (int m = 0; m < 4; ++m) _Pragma("unroll") for (int k = 0; k < 2; ++k) dst[m][k] = *(const PG8_LAS bf16x8*)(lds + PG8_SA(b, h) + aoff + m * 2048 + k * 1024); } while (0)
; #define PG8_MMA(ai, bj, At, Bt) do { __builtin_amdgcn_s_setprio(1); _Pragma("unroll") for (int m = 0; m < 4; ++m) _Pragma("unroll") for (int n = 0; n < 2; ++n) _Pragma("unroll") for (int k = 0; k < 2; ++k) \
;         acc[ai][bj][m][n] = __builtin_amdgcn_mfma_f32_16x16x32_bf16(Bt[n][k], At[m][k], acc[ai][bj][m][n], 0, 0, 0); __builtin_amdgcn_s_setprio(0); } while (0)
; #define PG8_WAIT_V(n) asm volatile("s_waitcnt vmcnt(" #n ")" ::: "memory")
; #define PG8_WAIT_L(n) asm volatile("s_waitcnt lgkmcnt(" #n ")" ::: "memory")
; #define PG8_BAR __builtin_amdgcn_s_barrier()
; #define PG8_SCHED __builtin_amdgcn_sched_barrier(0)
; template <class Epi, class Sched, bool ALIGN_EPI = false, bool SP2 = false>
; __device__ __forceinline__ void gemm_phase(PG8_LAS unsigned char* lds, const Gemm g, const Sched& S, const Epi& E) {
;     ...
;         for (int t = 0; t < nt; t += 2) {
;     ...
;             PG8_LDA(At, 1, 1); PG8_STAGE(PG8_SB(1, 0), b3, voffB); PG8_STAGE(PG8_SB(1, 1), b3 + hstep, voffB); PG8_STAGE(PG8_SA(1, 0), a3, voffA);
;             PG8_WAIT_V(8); PG8_WAIT_L(0); PG8_BAR; PG8_MMA(1, 0, At, B0); PG8_MMA(1, 1, At, B1); PG8_BAR; PG8_SCHED;
;     ...
;         if constexpr (ALIGN_EPI) { if (wr == 0) PG8_BAR; }
	s_add_i32 s6, s20, s24
	v_lshl_add_u64 v[220:221], v[220:221], 0, s[84:85]
	s_mov_b32 m0, s6
	ds_read_b128 v[180:183], v210 offset:49152
	ds_read_b128 v[184:187], v210 offset:50176
	ds_read_b128 v[188:191], v210 offset:51200
	ds_read_b128 v[192:195], v210 offset:52224
	ds_read_b128 v[196:199], v210 offset:53248
	ds_read_b128 v[200:203], v210 offset:54272
	ds_read_b128 v[216:219], v210 offset:55296
	ds_read_b128 v[228:231], v210 offset:56320
	global_load_lds_dwordx4 v[220:221], off
	s_add_i32 m0, s6, 0x2000
	s_add_u32 s0, s0, 0x80080
	v_lshl_add_u64 v[220:221], v[232:233], 0, s[84:85]
	s_addc_u32 s1, s1, 0
	s_add_i32 s6, s33, s24
	global_load_lds_dwordx4 v[220:221], off
	v_lshl_add_u64 v[220:221], s[0:1], 0, v[146:147]
	s_mov_b32 m0, s6
	s_nop 0
	global_load_lds_dwordx4 v[220:221], off
	v_lshl_add_u64 v[220:221], s[0:1], 0, v[150:151]
	s_add_i32 m0, s6, 0x2000
	s_nop 0
	global_load_lds_dwordx4 v[220:221], off
	v_lshl_add_u64 v[220:221], v[234:235], 0, s[84:85]
	s_mov_b32 m0, s67
	s_nop 0
	global_load_lds_dwordx4 v[220:221], off
	v_lshl_add_u64 v[220:221], v[236:237], 0, s[84:85]
	s_mov_b32 m0, s22
	s_nop 0
	global_load_lds_dwordx4 v[220:221], off
	s_waitcnt vmcnt(8)
	s_waitcnt lgkmcnt(0)
	s_barrier
	s_setprio 1
	s_waitcnt lgkmcnt(0)
	v_mfma_f32_16x16x32_bf16 v[76:79], v[24:27], v[180:183], v[76:79]
	v_mfma_f32_16x16x32_bf16 v[60:63], v[24:27], v[188:191], v[60:63]
	v_mfma_f32_16x16x32_bf16 v[44:47], v[24:27], v[196:199], v[44:47]
	v_mfma_f32_16x16x32_bf16 v[4:7], v[24:27], v[216:219], v[4:7]
	v_mfma_f32_16x16x32_bf16 v[76:79], v[28:31], v[184:187], v[76:79]
	v_mfma_f32_16x16x32_bf16 v[72:75], v[64:67], v[180:183], v[72:75]
	v_mfma_f32_16x16x32_bf16 v[60:63], v[28:31], v[192:195], v[60:63]
	v_mfma_f32_16x16x32_bf16 v[56:59], v[64:67], v[188:191], v[56:59]
	v_mfma_f32_16x16x32_bf16 v[44:47], v[28:31], v[200:203], v[44:47]
	v_mfma_f32_16x16x32_bf16 v[40:43], v[64:67], v[196:199], v[40:43]
	v_mfma_f32_16x16x32_bf16 v[28:31], v[28:31], v[228:231], v[4:7]
	v_mfma_f32_16x16x32_bf16 v[4:7], v[64:67], v[216:219], v[12:15]
	v_mfma_f32_16x16x32_bf16 v[72:75], v[68:71], v[184:187], v[72:75]
	v_mfma_f32_16x16x32_bf16 v[56:59], v[68:71], v[192:195], v[56:59]
	v_mfma_f32_16x16x32_bf16 v[40:43], v[68:71], v[200:203], v[40:43]
	v_mfma_f32_16x16x32_bf16 v[24:27], v[68:71], v[228:231], v[4:7]
	s_setprio 0
	s_setprio 1
	v_mfma_f32_16x16x32_bf16 v[4:7], v[164:167], v[180:183], v[16:19]
	v_mfma_f32_16x16x32_bf16 v[68:71], v[168:171], v[184:187], v[4:7]
	v_mfma_f32_16x16x32_bf16 v[4:7], v[172:175], v[180:183], v[20:23]
	v_mfma_f32_16x16x32_bf16 v[64:67], v[176:179], v[184:187], v[4:7]
	v_mfma_f32_16x16x32_bf16 v[4:7], v[164:167], v[188:191], v[52:55]
	v_mfma_f32_16x16x32_bf16 v[52:55], v[168:171], v[192:195], v[4:7]
	v_mfma_f32_16x16x32_bf16 v[4:7], v[172:175], v[188:191], v[48:51]
	v_mfma_f32_16x16x32_bf16 v[48:51], v[176:179], v[192:195], v[4:7]
	v_mfma_f32_16x16x32_bf16 v[4:7], v[164:167], v[196:199], v[36:39]
	v_mfma_f32_16x16x32_bf16 v[36:39], v[168:171], v[200:203], v[4:7]
	v_mfma_f32_16x16x32_bf16 v[4:7], v[172:175], v[196:199], v[32:35]
	v_mfma_f32_16x16x32_bf16 v[32:35], v[176:179], v[200:203], v[4:7]
	v_mfma_f32_16x16x32_bf16 v[4:7], v[164:167], v[216:219], v[8:11]
	v_mfma_f32_16x16x32_bf16 v[0:3], v[172:175], v[216:219], v[0:3]
	v_mfma_f32_16x16x32_bf16 v[8:11], v[168:171], v[228:231], v[4:7]
	v_mfma_f32_16x16x32_bf16 v[0:3], v[176:179], v[228:231], v[0:3]
	s_setprio 0
	s_barrier
	s_add_i32 s17, s17, 2
	s_add_u32 s4, s4, 0x100
	s_addc_u32 s5, s5, 0
	s_add_u32 s15, s15, 0x100
	s_addc_u32 s16, s16, 0
	s_cmp_gt_u32 s17, 29
	s_cbranch_scc0 .LBB0_263
	s_and_b64 vcc, exec, s[86:87]
	s_cbranch_vccz .LBB0_266
	s_barrier

; #define PG8_STAGE(bufoff, gbase, voff) do { _Pragma("unroll") for (int _i = 0; _i < 2; ++_i) \
;         __builtin_amdgcn_global_load_lds((const unsigned*)((const char*)(gbase) + (voff)[_i]), (PG8_LAS unsigned*)(lds + (bufoff) + ldsw + _i * 8192), 16, 0, 0); } while (0)
; #define PG8_LDA(dst, b, h) do { _Pragma("unroll") for (int m = 0; m < 4; ++m) _Pragma("unroll") for (int k = 0; k < 2; ++k) dst[m][k] = *(const PG8_LAS bf16x8*)(lds + PG8_SA(b, h) + aoff + m * 2048 + k * 1024); } while (0)
; #define PG8_LDB(dst, b, h) do { _Pragma("unroll") for (int n = 0; n < 2; ++n) _Pragma("unroll") for (int k = 0; k < 2; ++k) dst[n][k] = *(const PG8_LAS bf16x8*)(lds + PG8_SB(b, h) + boff + n * 2048 + k * 1024); } while (0)
; #define PG8_MMA(ai, bj, At, Bt) do { __builtin_amdgcn_s_setprio(1); _Pragma("unroll") for (int m = 0; m < 4; ++m) _Pragma("unroll") for (int n = 0; n < 2; ++n) _Pragma("unroll") for (int k = 0; k < 2; ++k) \
;         acc[ai][bj][m][n] = __builtin_amdgcn_mfma_f32_16x16x32_bf16(Bt[n][k], At[m][k], acc[ai][bj][m][n], 0, 0, 0); __builtin_amdgcn_s_setprio(0); } while (0)
; #define PG8_WAIT_V(n) asm volatile("s_waitcnt vmcnt(" #n ")" ::: "memory")
; #define PG8_WAIT_L(n) asm volatile("s_waitcnt lgkmcnt(" #n ")" ::: "memory")
; #define PG8_BAR __builtin_amdgcn_s_barrier()
; #define PG8_SCHED __builtin_amdgcn_sched_barrier(0)
; template <class Epi, class Sched, bool ALIGN_EPI = false, bool SP2 = false>
; __device__ __forceinline__ void gemm_phase(PG8_LAS unsigned char* lds, const Gemm g, const Sched& S, const Epi& E) {
;     ...
;             PG8_LDB(B0, 0, 0); PG8_LDB(B1, 0, 1); PG8_SCHED; PG8_LDA(At, 0, 0); PG8_STAGE(PG8_SA(1, 1), a1 + hstep, voffA);
;             PG8_WAIT_V(8); PG8_WAIT_L(0); PG8_BAR; PG8_MMA(0, 0, At, B0); PG8_MMA(0, 1, At, B1); PG8_BAR; PG8_SCHED;
;             PG8_LDA(At, 0, 1); PG8_STAGE(PG8_SB(0, 0), b2, voffB); PG8_STAGE(PG8_SB(0, 1), b2 + hstep, voffB); PG8_STAGE(PG8_SA(0, 0), a2, voffA);
.LBB0_1678:
	ds_read_b128 v[144:147], v157
	ds_read_b128 v[148:151], v157 offset:1024
	ds_read_b128 v[160:163], v157 offset:2048
	ds_read_b128 v[164:167], v157 offset:3072
	ds_read_b128 v[168:171], v158
	ds_read_b128 v[172:175], v158 offset:1024
	ds_read_b128 v[176:179], v158 offset:2048
	ds_read_b128 v[180:183], v158 offset:3072
	s_add_u32 s0, s36, 0xfffc0080
	s_addc_u32 s1, s37, -1
	s_cmp_eq_u32 s55, 12
	s_cselect_b32 s25, s21, s1
	s_cselect_b32 s24, s51, s0
	s_cselect_b32 s1, s19, s54
	s_cselect_b32 s0, s52, s53
	v_lshl_add_u64 v[152:153], s[36:37], 0, v[136:137]
	s_add_i32 m0, s31, 0xc000
	ds_read_b128 v[184:187], v159
	ds_read_b128 v[188:191], v159 offset:1024
	ds_read_b128 v[192:195], v159 offset:2048
	ds_read_b128 v[196:199], v159 offset:3072
	ds_read_b128 v[200:203], v159 offset:4096
	ds_read_b128 v[204:207], v159 offset:5120
	ds_read_b128 v[208:211], v159 offset:6144
	ds_read_b128 v[212:215], v159 offset:7168
	global_load_lds_dwordx4 v[152:153], off
	v_lshl_add_u64 v[152:153], s[36:37], 0, v[138:139]
	s_add_i32 m0, s31, 0xe000
	s_nop 0
	global_load_lds_dwordx4 v[152:153], off
	s_waitcnt vmcnt(8)
	s_waitcnt lgkmcnt(0)
	s_barrier
	s_setprio 1
	s_waitcnt lgkmcnt(0)
	v_mfma_f32_16x16x32_bf16 v[124:127], v[144:147], v[184:187], v[124:127]
	v_mfma_f32_16x16x32_bf16 v[120:123], v[160:163], v[184:187], v[120:123]
	v_mfma_f32_16x16x32_bf16 v[116:119], v[144:147], v[192:195], v[116:119]
	v_mfma_f32_16x16x32_bf16 v[108:111], v[160:163], v[192:195], v[108:111]
	v_mfma_f32_16x16x32_bf16 v[96:99], v[144:147], v[200:203], v[96:99]
	v_mfma_f32_16x16x32_bf16 v[88:91], v[160:163], v[200:203], v[88:91]
	v_mfma_f32_16x16x32_bf16 v[80:83], v[144:147], v[208:211], v[80:83]
	v_mfma_f32_16x16x32_bf16 v[72:75], v[160:163], v[208:211], v[72:75]
	v_mfma_f32_16x16x32_bf16 v[124:127], v[148:151], v[188:191], v[124:127]
	v_mfma_f32_16x16x32_bf16 v[120:123], v[164:167], v[188:191], v[120:123]
	v_mfma_f32_16x16x32_bf16 v[116:119], v[148:151], v[196:199], v[116:119]
	v_mfma_f32_16x16x32_bf16 v[108:111], v[164:167], v[196:199], v[108:111]
	v_mfma_f32_16x16x32_bf16 v[96:99], v[148:151], v[204:207], v[96:99]
	v_mfma_f32_16x16x32_bf16 v[88:91], v[164:167], v[204:207], v[88:91]
	v_mfma_f32_16x16x32_bf16 v[80:83], v[148:151], v[212:215], v[80:83]
	v_mfma_f32_16x16x32_bf16 v[72:75], v[164:167], v[212:215], v[72:75]
	s_setprio 0
	s_setprio 1
	v_mfma_f32_16x16x32_bf16 v[112:115], v[168:171], v[184:187], v[112:115]
	v_mfma_f32_16x16x32_bf16 v[104:107], v[176:179], v[184:187], v[104:107]
	v_mfma_f32_16x16x32_bf16 v[100:103], v[168:171], v[192:195], v[100:103]
	v_mfma_f32_16x16x32_bf16 v[92:95], v[176:179], v[192:195], v[92:95]
	v_mfma_f32_16x16x32_bf16 v[84:87], v[168:171], v[200:203], v[84:87]
	v_mfma_f32_16x16x32_bf16 v[76:79], v[176:179], v[200:203], v[76:79]
	v_mfma_f32_16x16x32_bf16 v[68:71], v[168:171], v[208:211], v[68:71]
	v_mfma_f32_16x16x32_bf16 v[64:67], v[176:179], v[208:211], v[64:67]
	v_mfma_f32_16x16x32_bf16 v[112:115], v[172:175], v[188:191], v[112:115]
	v_mfma_f32_16x16x32_bf16 v[104:107], v[180:183], v[188:191], v[104:107]
	v_mfma_f32_16x16x32_bf16 v[100:103], v[172:175], v[196:199], v[100:103]
	v_mfma_f32_16x16x32_bf16 v[92:95], v[180:183], v[196:199], v[92:95]
	v_mfma_f32_16x16x32_bf16 v[84:87], v[172:175], v[204:207], v[84:87]
	v_mfma_f32_16x16x32_bf16 v[76:79], v[180:183], v[204:207], v[76:79]
	v_mfma_f32_16x16x32_bf16 v[68:71], v[172:175], v[212:215], v[68:71]
	v_mfma_f32_16x16x32_bf16 v[64:67], v[180:183], v[212:215], v[64:67]
	s_setprio 0
	s_barrier
	s_add_i32 s56, s44, s17
	v_lshl_add_u64 v[152:153], s[0:1], 0, v[130:131]
	s_mov_b32 m0, s56
	ds_read_b128 v[184:187], v159 offset:16384
	ds_read_b128 v[188:191], v159 offset:17408
	ds_read_b128 v[192:195], v159 offset:18432
	ds_read_b128 v[196:199], v159 offset:19456
	ds_read_b128 v[200:203], v159 offset:20480
	ds_read_b128 v[204:207], v159 offset:21504
	ds_read_b128 v[208:211], v159 offset:22528
	ds_read_b128 v[212:215], v159 offset:23552
	global_load_lds_dwordx4 v[152:153], off
	s_add_i32 m0, s56, 0x2000
	s_add_u32 s56, s0, 0x40000
	v_lshl_add_u64 v[216:217], s[0:1], 0, v[134:135]
	s_addc_u32 s57, s1, 0
	s_add_i32 s58, s45, s17
	global_load_lds_dwordx4 v[216:217], off
	v_lshl_add_u64 v[218:219], s[56:57], 0, v[130:131]
	s_mov_b32 m0, s58
	v_lshl_add_u64 v[220:221], s[24:25], 0, v[132:133]
	global_load_lds_dwordx4 v[218:219], off
	v_lshl_add_u64 v[218:219], s[56:57], 0, v[134:135]
	s_add_i32 m0, s58, 0x2000
	s_nop 0
	global_load_lds_dwordx4 v[218:219], off
	v_lshl_add_u64 v[218:219], s[24:25], 0, v[128:129]
	s_mov_b32 m0, s31
	s_nop 0
	global_load_lds_dwordx4 v[218:219], off
	s_mov_b32 m0, s33
	s_nop 0
	global_load_lds_dwordx4 v[220:221], off
	s_waitcnt vmcnt(8)
	s_waitcnt lgkmcnt(0)
	s_barrier
; #define PG8_STAGE(bufoff, gbase, voff) do { _Pragma("unroll") for (int _i = 0; _i < 2; ++_i) \
;         __builtin_amdgcn_global_load_lds((const unsigned*)((const char*)(gbase) + (voff)[_i]), (PG8_LAS unsigned*)(lds + (bufoff) + ldsw + _i * 8192), 16, 0, 0); } while (0)
; #define PG8_LDA(dst, b, h) do { _Pragma("unroll") for (int m = 0; m < 4; ++m) _Pragma("unroll") for (int k = 0; k < 2; ++k) dst[m][k] = *(const PG8_LAS bf16x8*)(lds + PG8_SA(b, h) + aoff + m * 2048 + k * 1024); } while (0)
; #define PG8_LDB(dst, b, h) do { _Pragma("unroll") for (int n = 0; n < 2; ++n) _Pragma("unroll") for (int k = 0; k < 2; ++k) dst[n][k] = *(const PG8_LAS bf16x8*)(lds + PG8_SB(b, h) + boff + n * 2048 + k * 1024); } while (0)
; #define PG8_MMA(ai, bj, At, Bt) do { __builtin_amdgcn_s_setprio(1); _Pragma("unroll") for (int m = 0; m < 4; ++m) _Pragma("unroll") for (int n = 0; n < 2; ++n) _Pragma("unroll") for (int k = 0; k < 2; ++k) \
;         acc[ai][bj][m][n] = __builtin_amdgcn_mfma_f32_16x16x32_bf16(Bt[n][k], At[m][k], acc[ai][bj][m][n], 0, 0, 0); __builtin_amdgcn_s_setprio(0); } while (0)
; #define PG8_WAIT_V(n) asm volatile("s_waitcnt vmcnt(" #n ")" ::: "memory")
; #define PG8_WAIT_L(n) asm volatile("s_waitcnt lgkmcnt(" #n ")" ::: "memory")
; #define PG8_BAR __builtin_amdgcn_s_barrier()
; #define PG8_SCHED __builtin_amdgcn_sched_barrier(0)
; template <class Epi, class Sched, bool ALIGN_EPI = false, bool SP2 = false>
; __device__ __forceinline__ void gemm_phase(PG8_LAS unsigned char* lds, const Gemm g, const Sched& S, const Epi& E) {
;     ...
;             PG8_WAIT_V(8); PG8_WAIT_L(0); PG8_BAR; PG8_MMA(1, 0, At, B0); PG8_MMA(1, 1, At, B1); PG8_BAR; PG8_SCHED;
;             PG8_LDB(B0, 1, 0); PG8_LDB(B1, 1, 1); PG8_SCHED; PG8_LDA(At, 1, 0); PG8_STAGE(PG8_SA(0, 1), a2 + hstep, voffA);
;             PG8_WAIT_V(8); PG8_WAIT_L(0); PG8_BAR; PG8_MMA(0, 0, At, B0); PG8_MMA(0, 1, At, B1); PG8_BAR; PG8_SCHED;
	s_setprio 1
	s_nop 0
	s_waitcnt lgkmcnt(0)
	v_mfma_f32_16x16x32_bf16 v[60:63], v[144:147], v[184:187], v[60:63]
	v_mfma_f32_16x16x32_bf16 v[56:59], v[160:163], v[184:187], v[56:59]
	v_mfma_f32_16x16x32_bf16 v[48:51], v[144:147], v[192:195], v[48:51]
	v_mfma_f32_16x16x32_bf16 v[40:43], v[160:163], v[192:195], v[40:43]
	v_mfma_f32_16x16x32_bf16 v[32:35], v[144:147], v[200:203], v[32:35]
	v_mfma_f32_16x16x32_bf16 v[24:27], v[160:163], v[200:203], v[24:27]
	v_mfma_f32_16x16x32_bf16 v[16:19], v[144:147], v[208:211], v[16:19]
	v_mfma_f32_16x16x32_bf16 v[8:11], v[160:163], v[208:211], v[8:11]
	v_mfma_f32_16x16x32_bf16 v[60:63], v[148:151], v[188:191], v[60:63]
	v_mfma_f32_16x16x32_bf16 v[56:59], v[164:167], v[188:191], v[56:59]
	v_mfma_f32_16x16x32_bf16 v[48:51], v[148:151], v[196:199], v[48:51]
	v_mfma_f32_16x16x32_bf16 v[40:43], v[164:167], v[196:199], v[40:43]
	v_mfma_f32_16x16x32_bf16 v[32:35], v[148:151], v[204:207], v[32:35]
	v_mfma_f32_16x16x32_bf16 v[24:27], v[164:167], v[204:207], v[24:27]
	v_mfma_f32_16x16x32_bf16 v[16:19], v[148:151], v[212:215], v[16:19]
	v_mfma_f32_16x16x32_bf16 v[8:11], v[164:167], v[212:215], v[8:11]
	s_setprio 0
	s_setprio 1
	v_mfma_f32_16x16x32_bf16 v[52:55], v[168:171], v[184:187], v[52:55]
	v_mfma_f32_16x16x32_bf16 v[44:47], v[176:179], v[184:187], v[44:47]
	v_mfma_f32_16x16x32_bf16 v[36:39], v[168:171], v[192:195], v[36:39]
	v_mfma_f32_16x16x32_bf16 v[28:31], v[176:179], v[192:195], v[28:31]
	v_mfma_f32_16x16x32_bf16 v[20:23], v[168:171], v[200:203], v[20:23]
	v_mfma_f32_16x16x32_bf16 v[12:15], v[176:179], v[200:203], v[12:15]
	v_mfma_f32_16x16x32_bf16 v[4:7], v[168:171], v[208:211], v[4:7]
	v_mfma_f32_16x16x32_bf16 v[0:3], v[176:179], v[208:211], v[0:3]
	v_mfma_f32_16x16x32_bf16 v[52:55], v[172:175], v[188:191], v[52:55]
	v_mfma_f32_16x16x32_bf16 v[44:47], v[180:183], v[188:191], v[44:47]
	v_mfma_f32_16x16x32_bf16 v[36:39], v[172:175], v[196:199], v[36:39]
	v_mfma_f32_16x16x32_bf16 v[28:31], v[180:183], v[196:199], v[28:31]
	v_mfma_f32_16x16x32_bf16 v[20:23], v[172:175], v[204:207], v[20:23]
	v_mfma_f32_16x16x32_bf16 v[12:15], v[180:183], v[204:207], v[12:15]
	v_mfma_f32_16x16x32_bf16 v[4:7], v[172:175], v[212:215], v[4:7]
	v_mfma_f32_16x16x32_bf16 v[0:3], v[180:183], v[212:215], v[0:3]
	s_setprio 0
	s_barrier
	s_add_i32 s56, 0, 0x18000
	s_add_i32 s57, 0, 0x1c000
	v_add_u32_e32 v164, s56, v155
	v_add_u32_e32 v180, s57, v155
	ds_read_b128 v[144:147], v164
	ds_read_b128 v[148:151], v164 offset:1024
	ds_read_b128 v[160:163], v164 offset:2048
	ds_read_b128 v[164:167], v164 offset:3072
	ds_read_b128 v[168:171], v180
	ds_read_b128 v[172:175], v180 offset:1024
	ds_read_b128 v[176:179], v180 offset:2048
	ds_read_b128 v[180:183], v180 offset:3072
	s_add_u32 s24, s24, 0x40000
	s_addc_u32 s25, s25, 0
	s_mov_b32 m0, s35
	v_lshl_add_u64 v[228:229], s[24:25], 0, v[128:129]
	ds_read_b128 v[184:187], v159 offset:32768
	ds_read_b128 v[188:191], v159 offset:33792
	ds_read_b128 v[192:195], v159 offset:34816
	ds_read_b128 v[196:199], v159 offset:35840
	ds_read_b128 v[200:203], v159 offset:36864
	ds_read_b128 v[204:207], v159 offset:37888
	ds_read_b128 v[208:211], v159 offset:38912
	ds_read_b128 v[212:215], v159 offset:39936
	global_load_lds_dwordx4 v[228:229], off
	v_lshl_add_u64 v[228:229], s[24:25], 0, v[132:133]
	s_mov_b32 m0, s38
	s_nop 0
	global_load_lds_dwordx4 v[228:229], off
	s_waitcnt vmcnt(8)
	s_waitcnt lgkmcnt(0)
	s_barrier
	s_setprio 1
	s_nop 0
	s_waitcnt lgkmcnt(0)
	v_mfma_f32_16x16x32_bf16 v[124:127], v[144:147], v[184:187], v[124:127]
	v_mfma_f32_16x16x32_bf16 v[120:123], v[160:163], v[184:187], v[120:123]
	v_mfma_f32_16x16x32_bf16 v[116:119], v[144:147], v[192:195], v[116:119]
	v_mfma_f32_16x16x32_bf16 v[108:111], v[160:163], v[192:195], v[108:111]
	v_mfma_f32_16x16x32_bf16 v[96:99], v[144:147], v[200:203], v[96:99]
	v_mfma_f32_16x16x32_bf16 v[88:91], v[160:163], v[200:203], v[88:91]
	v_mfma_f32_16x16x32_bf16 v[80:83], v[144:147], v[208:211], v[80:83]
	v_mfma_f32_16x16x32_bf16 v[72:75], v[160:163], v[208:211], v[72:75]
	v_mfma_f32_16x16x32_bf16 v[124:127], v[148:151], v[188:191], v[124:127]
	v_mfma_f32_16x16x32_bf16 v[120:123], v[164:167], v[188:191], v[120:123]
	v_mfma_f32_16x16x32_bf16 v[116:119], v[148:151], v[196:199], v[116:119]
	v_mfma_f32_16x16x32_bf16 v[108:111], v[164:167], v[196:199], v[108:111]
	v_mfma_f32_16x16x32_bf16 v[96:99], v[148:151], v[204:207], v[96:99]
	v_mfma_f32_16x16x32_bf16 v[88:91], v[164:167], v[204:207], v[88:91]
	v_mfma_f32_16x16x32_bf16 v[80:83], v[148:151], v[212:215], v[80:83]
	v_mfma_f32_16x16x32_bf16 v[72:75], v[164:167], v[212:215], v[72:75]
	s_setprio 0
	s_setprio 1
	v_mfma_f32_16x16x32_bf16 v[112:115], v[168:171], v[184:187], v[112:115]
	v_mfma_f32_16x16x32_bf16 v[104:107], v[176:179], v[184:187], v[104:107]
	v_mfma_f32_16x16x32_bf16 v[100:103], v[168:171], v[192:195], v[100:103]
	v_mfma_f32_16x16x32_bf16 v[92:95], v[176:179], v[192:195], v[92:95]
	v_mfma_f32_16x16x32_bf16 v[84:87], v[168:171], v[200:203], v[84:87]
	v_mfma_f32_16x16x32_bf16 v[76:79], v[176:179], v[200:203], v[76:79]
	v_mfma_f32_16x16x32_bf16 v[68:71], v[168:171], v[208:211], v[68:71]
	v_mfma_f32_16x16x32_bf16 v[64:67], v[176:179], v[208:211], v[64:67]
	v_mfma_f32_16x16x32_bf16 v[112:115], v[172:175], v[188:191], v[112:115]
	v_mfma_f32_16x16x32_bf16 v[104:107], v[180:183], v[188:191], v[104:107]
	v_mfma_f32_16x16x32_bf16 v[100:103], v[172:175], v[196:199], v[100:103]
	v_mfma_f32_16x16x32_bf16 v[92:95], v[180:183], v[196:199], v[92:95]
	v_mfma_f32_16x16x32_bf16 v[84:87], v[172:175], v[204:207], v[84:87]
	v_mfma_f32_16x16x32_bf16 v[76:79], v[180:183], v[204:207], v[76:79]
	v_mfma_f32_16x16x32_bf16 v[68:71], v[172:175], v[212:215], v[68:71]
	v_mfma_f32_16x16x32_bf16 v[64:67], v[180:183], v[212:215], v[64:67]
	s_setprio 0
	s_barrier
; #define PG8_STAGE(bufoff, gbase, voff) do { _Pragma("unroll") for (int _i = 0; _i < 2; ++_i) \
;         __builtin_amdgcn_global_load_lds((const unsigned*)((const char*)(gbase) + (voff)[_i]), (PG8_LAS unsigned*)(lds + (bufoff) + ldsw + _i * 8192), 16, 0, 0); } while (0)
; #define PG8_LDA(dst, b, h) do { _Pragma("unroll") for (int m = 0; m < 4; ++m) _Pragma("unroll") for (int k = 0; k < 2; ++k) dst[m][k] = *(const PG8_LAS bf16x8*)(lds + PG8_SA(b, h) + aoff + m * 2048 + k * 1024); } while (0)
; #define PG8_MMA(ai, bj, At, Bt) do { __builtin_amdgcn_s_setprio(1); _Pragma("unroll") for (int m = 0; m < 4; ++m) _Pragma("unroll") for (int n = 0; n < 2; ++n) _Pragma("unroll") for (int k = 0; k < 2; ++k) \
;         acc[ai][bj][m][n] = __builtin_amdgcn_mfma_f32_16x16x32_bf16(Bt[n][k], At[m][k], acc[ai][bj][m][n], 0, 0, 0); __builtin_amdgcn_s_setprio(0); } while (0)
; #define PG8_WAIT_V(n) asm volatile("s_waitcnt vmcnt(" #n ")" ::: "memory")
; #define PG8_WAIT_L(n) asm volatile("s_waitcnt lgkmcnt(" #n ")" ::: "memory")
; #define PG8_BAR __builtin_amdgcn_s_barrier()
; #define PG8_SCHED __builtin_amdgcn_sched_barrier(0)
; template <class Epi, class Sched, bool ALIGN_EPI = false, bool SP2 = false>
; __device__ __forceinline__ void gemm_phase(PG8_LAS unsigned char* lds, const Gemm g, const Sched& S, const Epi& E) {
;     ...
;         for (int t = 0; t < nt; t += 2) {
;     ...
;             PG8_LDA(At, 1, 1); PG8_STAGE(PG8_SB(1, 0), b3, voffB); PG8_STAGE(PG8_SB(1, 1), b3 + hstep, voffB); PG8_STAGE(PG8_SA(1, 0), a3, voffA);
;             PG8_WAIT_V(8); PG8_WAIT_L(0); PG8_BAR; PG8_MMA(1, 0, At, B0); PG8_MMA(1, 1, At, B1); PG8_BAR; PG8_SCHED;
;     ...
;         if constexpr (ALIGN_EPI) { if (wr == 0) PG8_BAR; }
	s_add_i32 s24, s56, s17
	v_lshl_add_u64 v[152:153], v[152:153], 0, s[12:13]
	s_mov_b32 m0, s24
	ds_read_b128 v[184:187], v159 offset:49152
	ds_read_b128 v[188:191], v159 offset:50176
	ds_read_b128 v[192:195], v159 offset:51200
	ds_read_b128 v[196:199], v159 offset:52224
	ds_read_b128 v[200:203], v159 offset:53248
	ds_read_b128 v[204:207], v159 offset:54272
	ds_read_b128 v[208:211], v159 offset:55296
	ds_read_b128 v[212:215], v159 offset:56320
	global_load_lds_dwordx4 v[152:153], off
	s_add_i32 m0, s24, 0x2000
	s_add_u32 s0, s0, 0x40080
	v_lshl_add_u64 v[152:153], v[216:217], 0, s[12:13]
	s_addc_u32 s1, s1, 0
	s_add_i32 s24, s57, s17
	global_load_lds_dwordx4 v[152:153], off
	v_lshl_add_u64 v[152:153], s[0:1], 0, v[130:131]
	s_mov_b32 m0, s24
	s_nop 0
	global_load_lds_dwordx4 v[152:153], off
	v_lshl_add_u64 v[152:153], s[0:1], 0, v[134:135]
	s_add_i32 m0, s24, 0x2000
	s_nop 0
	global_load_lds_dwordx4 v[152:153], off
	v_lshl_add_u64 v[152:153], v[218:219], 0, s[12:13]
	s_mov_b32 m0, s40
	s_nop 0
	global_load_lds_dwordx4 v[152:153], off
	v_lshl_add_u64 v[152:153], v[220:221], 0, s[12:13]
	s_mov_b32 m0, s41
	s_nop 0
	global_load_lds_dwordx4 v[152:153], off
	s_waitcnt vmcnt(8)
	s_waitcnt lgkmcnt(0)
	s_barrier
	s_setprio 1
	s_waitcnt lgkmcnt(0)
	v_mfma_f32_16x16x32_bf16 v[60:63], v[144:147], v[184:187], v[60:63]
	v_mfma_f32_16x16x32_bf16 v[56:59], v[160:163], v[184:187], v[56:59]
	v_mfma_f32_16x16x32_bf16 v[48:51], v[144:147], v[192:195], v[48:51]
	v_mfma_f32_16x16x32_bf16 v[40:43], v[160:163], v[192:195], v[40:43]
	v_mfma_f32_16x16x32_bf16 v[32:35], v[144:147], v[200:203], v[32:35]
	v_mfma_f32_16x16x32_bf16 v[24:27], v[160:163], v[200:203], v[24:27]
	v_mfma_f32_16x16x32_bf16 v[16:19], v[144:147], v[208:211], v[16:19]
	v_mfma_f32_16x16x32_bf16 v[8:11], v[160:163], v[208:211], v[8:11]
	v_mfma_f32_16x16x32_bf16 v[60:63], v[148:151], v[188:191], v[60:63]
	v_mfma_f32_16x16x32_bf16 v[56:59], v[164:167], v[188:191], v[56:59]
	v_mfma_f32_16x16x32_bf16 v[48:51], v[148:151], v[196:199], v[48:51]
	v_mfma_f32_16x16x32_bf16 v[40:43], v[164:167], v[196:199], v[40:43]
	v_mfma_f32_16x16x32_bf16 v[32:35], v[148:151], v[204:207], v[32:35]
	v_mfma_f32_16x16x32_bf16 v[24:27], v[164:167], v[204:207], v[24:27]
	v_mfma_f32_16x16x32_bf16 v[16:19], v[148:151], v[212:215], v[16:19]
	v_mfma_f32_16x16x32_bf16 v[8:11], v[164:167], v[212:215], v[8:11]
	s_setprio 0
	s_setprio 1
	v_mfma_f32_16x16x32_bf16 v[52:55], v[168:171], v[184:187], v[52:55]
	v_mfma_f32_16x16x32_bf16 v[44:47], v[176:179], v[184:187], v[44:47]
	v_mfma_f32_16x16x32_bf16 v[36:39], v[168:171], v[192:195], v[36:39]
	v_mfma_f32_16x16x32_bf16 v[28:31], v[176:179], v[192:195], v[28:31]
	v_mfma_f32_16x16x32_bf16 v[20:23], v[168:171], v[200:203], v[20:23]
	v_mfma_f32_16x16x32_bf16 v[12:15], v[176:179], v[200:203], v[12:15]
	v_mfma_f32_16x16x32_bf16 v[4:7], v[168:171], v[208:211], v[4:7]
	v_mfma_f32_16x16x32_bf16 v[0:3], v[176:179], v[208:211], v[0:3]
	v_mfma_f32_16x16x32_bf16 v[52:55], v[172:175], v[188:191], v[52:55]
	v_mfma_f32_16x16x32_bf16 v[44:47], v[180:183], v[188:191], v[44:47]
	v_mfma_f32_16x16x32_bf16 v[36:39], v[172:175], v[196:199], v[36:39]
	v_mfma_f32_16x16x32_bf16 v[28:31], v[180:183], v[196:199], v[28:31]
	v_mfma_f32_16x16x32_bf16 v[20:23], v[172:175], v[204:207], v[20:23]
	v_mfma_f32_16x16x32_bf16 v[12:15], v[180:183], v[204:207], v[12:15]
	v_mfma_f32_16x16x32_bf16 v[4:7], v[172:175], v[212:215], v[4:7]
	v_mfma_f32_16x16x32_bf16 v[0:3], v[180:183], v[212:215], v[0:3]
	s_setprio 0
	s_barrier
	s_add_i32 s55, s55, 2
	s_add_u32 s36, s36, 0x100
	s_addc_u32 s37, s37, 0
	s_add_u32 s53, s53, 0x100
	s_addc_u32 s54, s54, 0
	s_cmp_gt_u32 s55, 13
	s_cbranch_scc0 .LBB0_1678
	s_and_b64 vcc, exec, s[14:15]
	s_cbranch_vccz .LBB0_1681
	s_barrier

; #define PG8_STAGE(bufoff, gbase, voff) do { _Pragma("unroll") for (int _i = 0; _i < 2; ++_i) \
;         __builtin_amdgcn_global_load_lds((const unsigned*)((const char*)(gbase) + (voff)[_i]), (PG8_LAS unsigned*)(lds + (bufoff) + ldsw + _i * 8192), 16, 0, 0); } while (0)
; #define PG8_LDA(dst, b, h) do { _Pragma("unroll") for (int m = 0; m < 4; ++m) _Pragma("unroll") for (int k = 0; k < 2; ++k) dst[m][k] = *(const PG8_LAS bf16x8*)(lds + PG8_SA(b, h) + aoff + m * 2048 + k * 1024); } while (0)
; #define PG8_LDB(dst, b, h) do { _Pragma("unroll") for (int n = 0; n < 2; ++n) _Pragma("unroll") for (int k = 0; k < 2; ++k) dst[n][k] = *(const PG8_LAS bf16x8*)(lds + PG8_SB(b, h) + boff + n * 2048 + k * 1024); } while (0)
; #define PG8_MMA(ai, bj, At, Bt) do { __builtin_amdgcn_s_setprio(1); _Pragma("unroll") for (int m = 0; m < 4; ++m) _Pragma("unroll") for (int n = 0; n < 2; ++n) _Pragma("unroll") for (int k = 0; k < 2; ++k) \
;         acc[ai][bj][m][n] = __builtin_amdgcn_mfma_f32_16x16x32_bf16(Bt[n][k], At[m][k], acc[ai][bj][m][n], 0, 0, 0); __builtin_amdgcn_s_setprio(0); } while (0)
; #define PG8_WAIT_V(n) asm volatile("s_waitcnt vmcnt(" #n ")" ::: "memory")
; #define PG8_WAIT_L(n) asm volatile("s_waitcnt lgkmcnt(" #n ")" ::: "memory")
; #define PG8_BAR __builtin_amdgcn_s_barrier()
; #define PG8_SCHED __builtin_amdgcn_sched_barrier(0)
; template <class Epi, class Sched, bool ALIGN_EPI = false, bool SP2 = false>
; __device__ __forceinline__ void gemm_phase(PG8_LAS unsigned char* lds, const Gemm g, const Sched& S, const Epi& E) {
;     ...
;             PG8_LDB(B0, 0, 0); PG8_LDB(B1, 0, 1); PG8_SCHED; PG8_LDA(At, 0, 0); PG8_STAGE(PG8_SA(1, 1), a1 + hstep, voffA);
;             PG8_WAIT_V(8); PG8_WAIT_L(0); PG8_BAR; PG8_MMA(0, 0, At, B0); PG8_MMA(0, 1, At, B1); PG8_BAR; PG8_SCHED;
;             PG8_LDA(At, 0, 1); PG8_STAGE(PG8_SB(0, 0), b2, voffB); PG8_STAGE(PG8_SB(0, 1), b2 + hstep, voffB); PG8_STAGE(PG8_SA(0, 0), a2, voffA);
.LBB0_1702:
	ds_read_b128 v[128:131], v175
	ds_read_b128 v[132:135], v175 offset:1024
	ds_read_b128 v[136:139], v175 offset:2048
	ds_read_b128 v[156:159], v175 offset:3072
	ds_read_b128 v[160:163], v176
	ds_read_b128 v[164:167], v176 offset:1024
	ds_read_b128 v[168:171], v176 offset:2048
	ds_read_b128 v[178:181], v176 offset:3072
	s_add_u32 s0, s38, 0xfffc0080
	s_addc_u32 s1, s39, -1
	s_cmp_eq_u32 s57, 12
	s_cselect_b32 s25, s23, s1
	s_cselect_b32 s24, s53, s0
	s_cselect_b32 s1, s21, s56
	s_cselect_b32 s0, s54, s55
	v_lshl_add_u64 v[214:215], s[38:39], 0, v[148:149]
	s_add_i32 m0, s33, 0xc000
	ds_read_b128 v[182:185], v177
	ds_read_b128 v[186:189], v177 offset:1024
	ds_read_b128 v[190:193], v177 offset:2048
	ds_read_b128 v[194:197], v177 offset:3072
	ds_read_b128 v[198:201], v177 offset:4096
	ds_read_b128 v[202:205], v177 offset:5120
	ds_read_b128 v[206:209], v177 offset:6144
	ds_read_b128 v[210:213], v177 offset:7168
	global_load_lds_dwordx4 v[214:215], off
	v_lshl_add_u64 v[214:215], s[38:39], 0, v[150:151]
	s_add_i32 m0, s33, 0xe000
	s_nop 0
	global_load_lds_dwordx4 v[214:215], off
	s_waitcnt vmcnt(8)
	s_waitcnt lgkmcnt(0)
	s_barrier
	s_setprio 1
	s_waitcnt lgkmcnt(0)
	v_mfma_f32_16x16x32_bf16 v[124:127], v[128:131], v[182:185], v[124:127]
	v_mfma_f32_16x16x32_bf16 v[120:123], v[136:139], v[182:185], v[120:123]
	v_mfma_f32_16x16x32_bf16 v[108:111], v[128:131], v[190:193], v[108:111]
	v_mfma_f32_16x16x32_bf16 v[104:107], v[136:139], v[190:193], v[104:107]
	v_mfma_f32_16x16x32_bf16 v[92:95], v[128:131], v[198:201], v[92:95]
	v_mfma_f32_16x16x32_bf16 v[88:91], v[136:139], v[198:201], v[88:91]
	v_mfma_f32_16x16x32_bf16 v[76:79], v[128:131], v[206:209], v[76:79]
	v_mfma_f32_16x16x32_bf16 v[72:75], v[136:139], v[206:209], v[72:75]
	v_mfma_f32_16x16x32_bf16 v[124:127], v[132:135], v[186:189], v[124:127]
	v_mfma_f32_16x16x32_bf16 v[120:123], v[156:159], v[186:189], v[120:123]
	v_mfma_f32_16x16x32_bf16 v[108:111], v[132:135], v[194:197], v[108:111]
	v_mfma_f32_16x16x32_bf16 v[104:107], v[156:159], v[194:197], v[104:107]
	v_mfma_f32_16x16x32_bf16 v[92:95], v[132:135], v[202:205], v[92:95]
	v_mfma_f32_16x16x32_bf16 v[88:91], v[156:159], v[202:205], v[88:91]
	v_mfma_f32_16x16x32_bf16 v[76:79], v[132:135], v[210:213], v[76:79]
	v_mfma_f32_16x16x32_bf16 v[72:75], v[156:159], v[210:213], v[72:75]
	s_setprio 0
	s_setprio 1
	v_mfma_f32_16x16x32_bf16 v[116:119], v[160:163], v[182:185], v[116:119]
	v_mfma_f32_16x16x32_bf16 v[112:115], v[168:171], v[182:185], v[112:115]
	v_mfma_f32_16x16x32_bf16 v[100:103], v[160:163], v[190:193], v[100:103]
	v_mfma_f32_16x16x32_bf16 v[96:99], v[168:171], v[190:193], v[96:99]
	v_mfma_f32_16x16x32_bf16 v[84:87], v[160:163], v[198:201], v[84:87]
	v_mfma_f32_16x16x32_bf16 v[80:83], v[168:171], v[198:201], v[80:83]
	v_mfma_f32_16x16x32_bf16 v[68:71], v[160:163], v[206:209], v[68:71]
	v_mfma_f32_16x16x32_bf16 v[64:67], v[168:171], v[206:209], v[64:67]
	v_mfma_f32_16x16x32_bf16 v[116:119], v[164:167], v[186:189], v[116:119]
	v_mfma_f32_16x16x32_bf16 v[112:115], v[178:181], v[186:189], v[112:115]
	v_mfma_f32_16x16x32_bf16 v[100:103], v[164:167], v[194:197], v[100:103]
	v_mfma_f32_16x16x32_bf16 v[96:99], v[178:181], v[194:197], v[96:99]
	v_mfma_f32_16x16x32_bf16 v[84:87], v[164:167], v[202:205], v[84:87]
	v_mfma_f32_16x16x32_bf16 v[80:83], v[178:181], v[202:205], v[80:83]
	v_mfma_f32_16x16x32_bf16 v[68:71], v[164:167], v[210:213], v[68:71]
	v_mfma_f32_16x16x32_bf16 v[64:67], v[178:181], v[210:213], v[64:67]
	s_setprio 0
	s_barrier
	s_add_i32 s58, s50, s19
	v_lshl_add_u64 v[214:215], s[0:1], 0, v[142:143]
	s_mov_b32 m0, s58
	ds_read_b128 v[182:185], v177 offset:16384
	ds_read_b128 v[186:189], v177 offset:17408
	ds_read_b128 v[190:193], v177 offset:18432
	ds_read_b128 v[194:197], v177 offset:19456
	ds_read_b128 v[198:201], v177 offset:20480
	ds_read_b128 v[202:205], v177 offset:21504
	ds_read_b128 v[206:209], v177 offset:22528
	ds_read_b128 v[210:213], v177 offset:23552
	global_load_lds_dwordx4 v[214:215], off
	s_add_i32 m0, s58, 0x2000
	s_add_u32 s58, s0, 0x40000
	v_lshl_add_u64 v[216:217], s[0:1], 0, v[146:147]
	s_addc_u32 s59, s1, 0
	s_add_i32 s65, s51, s19
	global_load_lds_dwordx4 v[216:217], off
	v_lshl_add_u64 v[218:219], s[58:59], 0, v[142:143]
	s_mov_b32 m0, s65
	v_lshl_add_u64 v[220:221], s[24:25], 0, v[144:145]
	global_load_lds_dwordx4 v[218:219], off
	v_lshl_add_u64 v[218:219], s[58:59], 0, v[146:147]
	s_add_i32 m0, s65, 0x2000
	s_nop 0
	global_load_lds_dwordx4 v[218:219], off
	v_lshl_add_u64 v[218:219], s[24:25], 0, v[140:141]
	s_mov_b32 m0, s33
	s_nop 0
	global_load_lds_dwordx4 v[218:219], off
	s_mov_b32 m0, s35
	s_nop 0
	global_load_lds_dwordx4 v[220:221], off
	s_waitcnt vmcnt(8)
	s_waitcnt lgkmcnt(0)
	s_barrier
; #define PG8_STAGE(bufoff, gbase, voff) do { _Pragma("unroll") for (int _i = 0; _i < 2; ++_i) \
;         __builtin_amdgcn_global_load_lds((const unsigned*)((const char*)(gbase) + (voff)[_i]), (PG8_LAS unsigned*)(lds + (bufoff) + ldsw + _i * 8192), 16, 0, 0); } while (0)
; #define PG8_LDA(dst, b, h) do { _Pragma("unroll") for (int m = 0; m < 4; ++m) _Pragma("unroll") for (int k = 0; k < 2; ++k) dst[m][k] = *(const PG8_LAS bf16x8*)(lds + PG8_SA(b, h) + aoff + m * 2048 + k * 1024); } while (0)
; #define PG8_LDB(dst, b, h) do { _Pragma("unroll") for (int n = 0; n < 2; ++n) _Pragma("unroll") for (int k = 0; k < 2; ++k) dst[n][k] = *(const PG8_LAS bf16x8*)(lds + PG8_SB(b, h) + boff + n * 2048 + k * 1024); } while (0)
; #define PG8_MMA(ai, bj, At, Bt) do { __builtin_amdgcn_s_setprio(1); _Pragma("unroll") for (int m = 0; m < 4; ++m) _Pragma("unroll") for (int n = 0; n < 2; ++n) _Pragma("unroll") for (int k = 0; k < 2; ++k) \
;         acc[ai][bj][m][n] = __builtin_amdgcn_mfma_f32_16x16x32_bf16(Bt[n][k], At[m][k], acc[ai][bj][m][n], 0, 0, 0); __builtin_amdgcn_s_setprio(0); } while (0)
; #define PG8_WAIT_V(n) asm volatile("s_waitcnt vmcnt(" #n ")" ::: "memory")
; #define PG8_WAIT_L(n) asm volatile("s_waitcnt lgkmcnt(" #n ")" ::: "memory")
; #define PG8_BAR __builtin_amdgcn_s_barrier()
; #define PG8_SCHED __builtin_amdgcn_sched_barrier(0)
; template <class Epi, class Sched, bool ALIGN_EPI = false, bool SP2 = false>
; __device__ __forceinline__ void gemm_phase(PG8_LAS unsigned char* lds, const Gemm g, const Sched& S, const Epi& E) {
;     ...
;             PG8_WAIT_V(8); PG8_WAIT_L(0); PG8_BAR; PG8_MMA(1, 0, At, B0); PG8_MMA(1, 1, At, B1); PG8_BAR; PG8_SCHED;
;             PG8_LDB(B0, 1, 0); PG8_LDB(B1, 1, 1); PG8_SCHED; PG8_LDA(At, 1, 0); PG8_STAGE(PG8_SA(0, 1), a2 + hstep, voffA);
;             PG8_WAIT_V(8); PG8_WAIT_L(0); PG8_BAR; PG8_MMA(0, 0, At, B0); PG8_MMA(0, 1, At, B1); PG8_BAR; PG8_SCHED;
	s_setprio 1
	s_nop 0
	s_waitcnt lgkmcnt(0)
	v_mfma_f32_16x16x32_bf16 v[60:63], v[128:131], v[182:185], v[60:63]
	v_mfma_f32_16x16x32_bf16 v[56:59], v[136:139], v[182:185], v[56:59]
	v_mfma_f32_16x16x32_bf16 v[44:47], v[128:131], v[190:193], v[44:47]
	v_mfma_f32_16x16x32_bf16 v[40:43], v[136:139], v[190:193], v[40:43]
	v_mfma_f32_16x16x32_bf16 v[28:31], v[128:131], v[198:201], v[28:31]
	v_mfma_f32_16x16x32_bf16 v[24:27], v[136:139], v[198:201], v[24:27]
	v_mfma_f32_16x16x32_bf16 v[12:15], v[128:131], v[206:209], v[12:15]
	v_mfma_f32_16x16x32_bf16 v[8:11], v[136:139], v[206:209], v[8:11]
	v_mfma_f32_16x16x32_bf16 v[60:63], v[132:135], v[186:189], v[60:63]
	v_mfma_f32_16x16x32_bf16 v[56:59], v[156:159], v[186:189], v[56:59]
	v_mfma_f32_16x16x32_bf16 v[44:47], v[132:135], v[194:197], v[44:47]
	v_mfma_f32_16x16x32_bf16 v[40:43], v[156:159], v[194:197], v[40:43]
	v_mfma_f32_16x16x32_bf16 v[28:31], v[132:135], v[202:205], v[28:31]
	v_mfma_f32_16x16x32_bf16 v[24:27], v[156:159], v[202:205], v[24:27]
	v_mfma_f32_16x16x32_bf16 v[12:15], v[132:135], v[210:213], v[12:15]
	v_mfma_f32_16x16x32_bf16 v[8:11], v[156:159], v[210:213], v[8:11]
	s_setprio 0
	s_setprio 1
	v_mfma_f32_16x16x32_bf16 v[52:55], v[160:163], v[182:185], v[52:55]
	v_mfma_f32_16x16x32_bf16 v[48:51], v[168:171], v[182:185], v[48:51]
	v_mfma_f32_16x16x32_bf16 v[36:39], v[160:163], v[190:193], v[36:39]
	v_mfma_f32_16x16x32_bf16 v[32:35], v[168:171], v[190:193], v[32:35]
	v_mfma_f32_16x16x32_bf16 v[20:23], v[160:163], v[198:201], v[20:23]
	v_mfma_f32_16x16x32_bf16 v[16:19], v[168:171], v[198:201], v[16:19]
	v_mfma_f32_16x16x32_bf16 v[4:7], v[160:163], v[206:209], v[4:7]
	v_mfma_f32_16x16x32_bf16 v[0:3], v[168:171], v[206:209], v[0:3]
	v_mfma_f32_16x16x32_bf16 v[52:55], v[164:167], v[186:189], v[52:55]
	v_mfma_f32_16x16x32_bf16 v[48:51], v[178:181], v[186:189], v[48:51]
	v_mfma_f32_16x16x32_bf16 v[36:39], v[164:167], v[194:197], v[36:39]
	v_mfma_f32_16x16x32_bf16 v[32:35], v[178:181], v[194:197], v[32:35]
	v_mfma_f32_16x16x32_bf16 v[20:23], v[164:167], v[202:205], v[20:23]
	v_mfma_f32_16x16x32_bf16 v[16:19], v[178:181], v[202:205], v[16:19]
	v_mfma_f32_16x16x32_bf16 v[4:7], v[164:167], v[210:213], v[4:7]
	v_mfma_f32_16x16x32_bf16 v[0:3], v[178:181], v[210:213], v[0:3]
	s_setprio 0
	s_barrier
	s_add_i32 s58, 0, 0x18000
	s_add_i32 s59, 0, 0x1c000
	v_add_u32_e32 v156, s58, v173
	v_add_u32_e32 v178, s59, v173
	ds_read_b128 v[128:131], v156
	ds_read_b128 v[132:135], v156 offset:1024
	ds_read_b128 v[136:139], v156 offset:2048
	ds_read_b128 v[156:159], v156 offset:3072
	ds_read_b128 v[160:163], v178
	ds_read_b128 v[164:167], v178 offset:1024
	ds_read_b128 v[168:171], v178 offset:2048
	ds_read_b128 v[178:181], v178 offset:3072
	s_add_u32 s24, s24, 0x40000
	s_addc_u32 s25, s25, 0
	s_mov_b32 m0, s37
	v_lshl_add_u64 v[228:229], s[24:25], 0, v[140:141]
	ds_read_b128 v[182:185], v177 offset:32768
	ds_read_b128 v[186:189], v177 offset:33792
	ds_read_b128 v[190:193], v177 offset:34816
	ds_read_b128 v[194:197], v177 offset:35840
	ds_read_b128 v[198:201], v177 offset:36864
	ds_read_b128 v[202:205], v177 offset:37888
	ds_read_b128 v[206:209], v177 offset:38912
	ds_read_b128 v[210:213], v177 offset:39936
	global_load_lds_dwordx4 v[228:229], off
	v_lshl_add_u64 v[228:229], s[24:25], 0, v[144:145]
	s_mov_b32 m0, s40
	s_nop 0
	global_load_lds_dwordx4 v[228:229], off
	s_waitcnt vmcnt(8)
	s_waitcnt lgkmcnt(0)
	s_barrier
	s_setprio 1
	s_nop 0
	s_waitcnt lgkmcnt(0)
	v_mfma_f32_16x16x32_bf16 v[124:127], v[128:131], v[182:185], v[124:127]
	v_mfma_f32_16x16x32_bf16 v[120:123], v[136:139], v[182:185], v[120:123]
	v_mfma_f32_16x16x32_bf16 v[108:111], v[128:131], v[190:193], v[108:111]
	v_mfma_f32_16x16x32_bf16 v[104:107], v[136:139], v[190:193], v[104:107]
	v_mfma_f32_16x16x32_bf16 v[92:95], v[128:131], v[198:201], v[92:95]
	v_mfma_f32_16x16x32_bf16 v[88:91], v[136:139], v[198:201], v[88:91]
	v_mfma_f32_16x16x32_bf16 v[76:79], v[128:131], v[206:209], v[76:79]
	v_mfma_f32_16x16x32_bf16 v[72:75], v[136:139], v[206:209], v[72:75]
	v_mfma_f32_16x16x32_bf16 v[124:127], v[132:135], v[186:189], v[124:127]
	v_mfma_f32_16x16x32_bf16 v[120:123], v[156:159], v[186:189], v[120:123]
	v_mfma_f32_16x16x32_bf16 v[108:111], v[132:135], v[194:197], v[108:111]
	v_mfma_f32_16x16x32_bf16 v[104:107], v[156:159], v[194:197], v[104:107]
	v_mfma_f32_16x16x32_bf16 v[92:95], v[132:135], v[202:205], v[92:95]
	v_mfma_f32_16x16x32_bf16 v[88:91], v[156:159], v[202:205], v[88:91]
	v_mfma_f32_16x16x32_bf16 v[76:79], v[132:135], v[210:213], v[76:79]
	v_mfma_f32_16x16x32_bf16 v[72:75], v[156:159], v[210:213], v[72:75]
	s_setprio 0
	s_setprio 1
	v_mfma_f32_16x16x32_bf16 v[116:119], v[160:163], v[182:185], v[116:119]
	v_mfma_f32_16x16x32_bf16 v[112:115], v[168:171], v[182:185], v[112:115]
	v_mfma_f32_16x16x32_bf16 v[100:103], v[160:163], v[190:193], v[100:103]
	v_mfma_f32_16x16x32_bf16 v[96:99], v[168:171], v[190:193], v[96:99]
	v_mfma_f32_16x16x32_bf16 v[84:87], v[160:163], v[198:201], v[84:87]
	v_mfma_f32_16x16x32_bf16 v[80:83], v[168:171], v[198:201], v[80:83]
	v_mfma_f32_16x16x32_bf16 v[68:71], v[160:163], v[206:209], v[68:71]
	v_mfma_f32_16x16x32_bf16 v[64:67], v[168:171], v[206:209], v[64:67]
	v_mfma_f32_16x16x32_bf16 v[116:119], v[164:167], v[186:189], v[116:119]
	v_mfma_f32_16x16x32_bf16 v[112:115], v[178:181], v[186:189], v[112:115]
	v_mfma_f32_16x16x32_bf16 v[100:103], v[164:167], v[194:197], v[100:103]
	v_mfma_f32_16x16x32_bf16 v[96:99], v[178:181], v[194:197], v[96:99]
	v_mfma_f32_16x16x32_bf16 v[84:87], v[164:167], v[202:205], v[84:87]
	v_mfma_f32_16x16x32_bf16 v[80:83], v[178:181], v[202:205], v[80:83]
	v_mfma_f32_16x16x32_bf16 v[68:71], v[164:167], v[210:213], v[68:71]
	v_mfma_f32_16x16x32_bf16 v[64:67], v[178:181], v[210:213], v[64:67]
	s_setprio 0
	s_barrier
; #define PG8_STAGE(bufoff, gbase, voff) do { _Pragma("unroll") for (int _i = 0; _i < 2; ++_i) \
;         __builtin_amdgcn_global_load_lds((const unsigned*)((const char*)(gbase) + (voff)[_i]), (PG8_LAS unsigned*)(lds + (bufoff) + ldsw + _i * 8192), 16, 0, 0); } while (0)
; #define PG8_LDA(dst, b, h) do { _Pragma("unroll") for (int m = 0; m < 4; ++m) _Pragma("unroll") for (int k = 0; k < 2; ++k) dst[m][k] = *(const PG8_LAS bf16x8*)(lds + PG8_SA(b, h) + aoff + m * 2048 + k * 1024); } while (0)
; #define PG8_MMA(ai, bj, At, Bt) do { __builtin_amdgcn_s_setprio(1); _Pragma("unroll") for (int m = 0; m < 4; ++m) _Pragma("unroll") for (int n = 0; n < 2; ++n) _Pragma("unroll") for (int k = 0; k < 2; ++k) \
;         acc[ai][bj][m][n] = __builtin_amdgcn_mfma_f32_16x16x32_bf16(Bt[n][k], At[m][k], acc[ai][bj][m][n], 0, 0, 0); __builtin_amdgcn_s_setprio(0); } while (0)
; #define PG8_WAIT_V(n) asm volatile("s_waitcnt vmcnt(" #n ")" ::: "memory")
; #define PG8_WAIT_L(n) asm volatile("s_waitcnt lgkmcnt(" #n ")" ::: "memory")
; #define PG8_BAR __builtin_amdgcn_s_barrier()
; #define PG8_SCHED __builtin_amdgcn_sched_barrier(0)
; template <class Epi, class Sched, bool ALIGN_EPI = false, bool SP2 = false>
; __device__ __forceinline__ void gemm_phase(PG8_LAS unsigned char* lds, const Gemm g, const Sched& S, const Epi& E) {
;     ...
;         for (int t = 0; t < nt; t += 2) {
;     ...
;             PG8_LDA(At, 1, 1); PG8_STAGE(PG8_SB(1, 0), b3, voffB); PG8_STAGE(PG8_SB(1, 1), b3 + hstep, voffB); PG8_STAGE(PG8_SA(1, 0), a3, voffA);
;             PG8_WAIT_V(8); PG8_WAIT_L(0); PG8_BAR; PG8_MMA(1, 0, At, B0); PG8_MMA(1, 1, At, B1); PG8_BAR; PG8_SCHED;
;     ...
;         if constexpr (ALIGN_EPI) { if (wr == 0) PG8_BAR; }
	s_add_i32 s24, s58, s19
	v_lshl_add_u64 v[214:215], v[214:215], 0, s[14:15]
	s_mov_b32 m0, s24
	ds_read_b128 v[182:185], v177 offset:49152
	ds_read_b128 v[186:189], v177 offset:50176
	ds_read_b128 v[190:193], v177 offset:51200
	ds_read_b128 v[194:197], v177 offset:52224
	ds_read_b128 v[198:201], v177 offset:53248
	ds_read_b128 v[202:205], v177 offset:54272
	ds_read_b128 v[206:209], v177 offset:55296
	ds_read_b128 v[210:213], v177 offset:56320
	global_load_lds_dwordx4 v[214:215], off
	s_add_i32 m0, s24, 0x2000
	s_add_u32 s0, s0, 0x40080
	v_lshl_add_u64 v[214:215], v[216:217], 0, s[14:15]
	s_addc_u32 s1, s1, 0
	s_add_i32 s24, s59, s19
	global_load_lds_dwordx4 v[214:215], off
	v_lshl_add_u64 v[214:215], s[0:1], 0, v[142:143]
	s_mov_b32 m0, s24
	s_nop 0
	global_load_lds_dwordx4 v[214:215], off
	v_lshl_add_u64 v[214:215], s[0:1], 0, v[146:147]
	s_add_i32 m0, s24, 0x2000
	s_nop 0
	global_load_lds_dwordx4 v[214:215], off
	v_lshl_add_u64 v[214:215], v[218:219], 0, s[14:15]
	s_mov_b32 m0, s42
	s_nop 0
	global_load_lds_dwordx4 v[214:215], off
	v_lshl_add_u64 v[214:215], v[220:221], 0, s[14:15]
	s_mov_b32 m0, s43
	s_nop 0
	global_load_lds_dwordx4 v[214:215], off
	s_waitcnt vmcnt(8)
	s_waitcnt lgkmcnt(0)
	s_barrier
	s_setprio 1
	s_waitcnt lgkmcnt(0)
	v_mfma_f32_16x16x32_bf16 v[60:63], v[128:131], v[182:185], v[60:63]
	v_mfma_f32_16x16x32_bf16 v[56:59], v[136:139], v[182:185], v[56:59]
	v_mfma_f32_16x16x32_bf16 v[44:47], v[128:131], v[190:193], v[44:47]
	v_mfma_f32_16x16x32_bf16 v[40:43], v[136:139], v[190:193], v[40:43]
	v_mfma_f32_16x16x32_bf16 v[28:31], v[128:131], v[198:201], v[28:31]
	v_mfma_f32_16x16x32_bf16 v[24:27], v[136:139], v[198:201], v[24:27]
	v_mfma_f32_16x16x32_bf16 v[12:15], v[128:131], v[206:209], v[12:15]
	v_mfma_f32_16x16x32_bf16 v[8:11], v[136:139], v[206:209], v[8:11]
	v_mfma_f32_16x16x32_bf16 v[60:63], v[132:135], v[186:189], v[60:63]
	v_mfma_f32_16x16x32_bf16 v[56:59], v[156:159], v[186:189], v[56:59]
	v_mfma_f32_16x16x32_bf16 v[44:47], v[132:135], v[194:197], v[44:47]
	v_mfma_f32_16x16x32_bf16 v[40:43], v[156:159], v[194:197], v[40:43]
	v_mfma_f32_16x16x32_bf16 v[28:31], v[132:135], v[202:205], v[28:31]
	v_mfma_f32_16x16x32_bf16 v[24:27], v[156:159], v[202:205], v[24:27]
	v_mfma_f32_16x16x32_bf16 v[12:15], v[132:135], v[210:213], v[12:15]
	v_mfma_f32_16x16x32_bf16 v[8:11], v[156:159], v[210:213], v[8:11]
	s_setprio 0
	s_setprio 1
	v_mfma_f32_16x16x32_bf16 v[52:55], v[160:163], v[182:185], v[52:55]
	v_mfma_f32_16x16x32_bf16 v[48:51], v[168:171], v[182:185], v[48:51]
	v_mfma_f32_16x16x32_bf16 v[36:39], v[160:163], v[190:193], v[36:39]
	v_mfma_f32_16x16x32_bf16 v[32:35], v[168:171], v[190:193], v[32:35]
	v_mfma_f32_16x16x32_bf16 v[20:23], v[160:163], v[198:201], v[20:23]
	v_mfma_f32_16x16x32_bf16 v[16:19], v[168:171], v[198:201], v[16:19]
	v_mfma_f32_16x16x32_bf16 v[4:7], v[160:163], v[206:209], v[4:7]
	v_mfma_f32_16x16x32_bf16 v[0:3], v[168:171], v[206:209], v[0:3]
	v_mfma_f32_16x16x32_bf16 v[52:55], v[164:167], v[186:189], v[52:55]
	v_mfma_f32_16x16x32_bf16 v[48:51], v[178:181], v[186:189], v[48:51]
	v_mfma_f32_16x16x32_bf16 v[36:39], v[164:167], v[194:197], v[36:39]
	v_mfma_f32_16x16x32_bf16 v[32:35], v[178:181], v[194:197], v[32:35]
	v_mfma_f32_16x16x32_bf16 v[20:23], v[164:167], v[202:205], v[20:23]
	v_mfma_f32_16x16x32_bf16 v[16:19], v[178:181], v[202:205], v[16:19]
	v_mfma_f32_16x16x32_bf16 v[4:7], v[164:167], v[210:213], v[4:7]
	v_mfma_f32_16x16x32_bf16 v[0:3], v[178:181], v[210:213], v[0:3]
	s_setprio 0
	s_barrier
	s_add_i32 s57, s57, 2
	s_add_u32 s38, s38, 0x100
	s_addc_u32 s39, s39, 0
	s_add_u32 s55, s55, 0x100
	s_addc_u32 s56, s56, 0
	s_cmp_gt_u32 s57, 13
	s_cbranch_scc0 .LBB0_1702
	s_and_b64 vcc, exec, s[16:17]
	s_cbranch_vccz .LBB0_1705
	s_barrier

; #define PG8_STAGE(bufoff, gbase, voff) do { _Pragma("unroll") for (int _i = 0; _i < 2; ++_i) \
;         __builtin_amdgcn_global_load_lds((const unsigned*)((const char*)(gbase) + (voff)[_i]), (PG8_LAS unsigned*)(lds + (bufoff) + ldsw + _i * 8192), 16, 0, 0); } while (0)
; #define PG8_LDA(dst, b, h) do { _Pragma("unroll") for (int m = 0; m < 4; ++m) _Pragma("unroll") for (int k = 0; k < 2; ++k) dst[m][k] = *(const PG8_LAS bf16x8*)(lds + PG8_SA(b, h) + aoff + m * 2048 + k * 1024); } while (0)
; #define PG8_LDB(dst, b, h) do { _Pragma("unroll") for (int n = 0; n < 2; ++n) _Pragma("unroll") for (int k = 0; k < 2; ++k) dst[n][k] = *(const PG8_LAS bf16x8*)(lds + PG8_SB(b, h) + boff + n * 2048 + k * 1024); } while (0)
; #define PG8_MMA(ai, bj, At, Bt) do { __builtin_amdgcn_s_setprio(1); _Pragma("unroll") for (int m = 0; m < 4; ++m) _Pragma("unroll") for (int n = 0; n < 2; ++n) _Pragma("unroll") for (int k = 0; k < 2; ++k) \
;         acc[ai][bj][m][n] = __builtin_amdgcn_mfma_f32_16x16x32_bf16(Bt[n][k], At[m][k], acc[ai][bj][m][n], 0, 0, 0); __builtin_amdgcn_s_setprio(0); } while (0)
; #define PG8_WAIT_V(n) asm volatile("s_waitcnt vmcnt(" #n ")" ::: "memory")
; #define PG8_WAIT_L(n) asm volatile("s_waitcnt lgkmcnt(" #n ")" ::: "memory")
; #define PG8_BAR __builtin_amdgcn_s_barrier()
; #define PG8_SCHED __builtin_amdgcn_sched_barrier(0)
; template <class Epi, class Sched, bool ALIGN_EPI = false, bool SP2 = false>
; __device__ __forceinline__ void gemm_phase(PG8_LAS unsigned char* lds, const Gemm g, const Sched& S, const Epi& E) {
;     ...
;             PG8_LDB(B0, 0, 0); PG8_LDB(B1, 0, 1); PG8_SCHED; PG8_LDA(At, 0, 0); PG8_STAGE(PG8_SA(1, 1), a1 + hstep, voffA);
;             PG8_WAIT_V(8); PG8_WAIT_L(0); PG8_BAR; PG8_MMA(0, 0, At, B0); PG8_MMA(0, 1, At, B1); PG8_BAR; PG8_SCHED;
;             PG8_LDA(At, 0, 1); PG8_STAGE(PG8_SB(0, 0), b2, voffB); PG8_STAGE(PG8_SB(0, 1), b2 + hstep, voffB); PG8_STAGE(PG8_SA(0, 0), a2, voffA);
.LBB0_1798:
	ds_read_b128 v[128:131], v209
	ds_read_b128 v[132:135], v209 offset:1024
	ds_read_b128 v[136:139], v209 offset:2048
	ds_read_b128 v[140:143], v209 offset:3072
	ds_read_b128 v[144:147], v210
	ds_read_b128 v[148:151], v210 offset:1024
	ds_read_b128 v[152:155], v210 offset:2048
	ds_read_b128 v[156:159], v210 offset:3072
	s_add_u32 s0, s40, 0xfff80080
	s_addc_u32 s1, s41, -1
	s_cmp_eq_u32 s56, 28
	s_cselect_b32 s25, s23, s1
	s_cselect_b32 s24, s52, s0
	s_cselect_b32 s1, s21, s55
	s_cselect_b32 s0, s53, s54
	v_lshl_add_u64 v[204:205], s[40:41], 0, v[180:181]
	s_add_i32 m0, s33, 0xc000
	ds_read_b128 v[160:163], v211
	ds_read_b128 v[164:167], v211 offset:1024
	ds_read_b128 v[168:171], v211 offset:2048
	ds_read_b128 v[172:175], v211 offset:3072
	ds_read_b128 v[188:191], v211 offset:4096
	ds_read_b128 v[192:195], v211 offset:5120
	ds_read_b128 v[196:199], v211 offset:6144
	ds_read_b128 v[200:203], v211 offset:7168
	global_load_lds_dwordx4 v[204:205], off
	v_lshl_add_u64 v[204:205], s[40:41], 0, v[182:183]
	s_add_i32 m0, s33, 0xe000
	s_nop 0
	global_load_lds_dwordx4 v[204:205], off
	s_waitcnt vmcnt(8)
	s_waitcnt lgkmcnt(0)
	s_barrier
	s_setprio 1
	s_waitcnt lgkmcnt(0)
	v_mfma_f32_16x16x32_bf16 v[124:127], v[128:131], v[160:163], v[124:127]
	v_mfma_f32_16x16x32_bf16 v[120:123], v[136:139], v[160:163], v[120:123]
	v_mfma_f32_16x16x32_bf16 v[108:111], v[128:131], v[168:171], v[108:111]
	v_mfma_f32_16x16x32_bf16 v[104:107], v[136:139], v[168:171], v[104:107]
	v_mfma_f32_16x16x32_bf16 v[92:95], v[128:131], v[188:191], v[92:95]
	v_mfma_f32_16x16x32_bf16 v[88:91], v[136:139], v[188:191], v[88:91]
	v_mfma_f32_16x16x32_bf16 v[76:79], v[128:131], v[196:199], v[76:79]
	v_mfma_f32_16x16x32_bf16 v[72:75], v[136:139], v[196:199], v[72:75]
	v_mfma_f32_16x16x32_bf16 v[124:127], v[132:135], v[164:167], v[124:127]
	v_mfma_f32_16x16x32_bf16 v[120:123], v[140:143], v[164:167], v[120:123]
	v_mfma_f32_16x16x32_bf16 v[108:111], v[132:135], v[172:175], v[108:111]
	v_mfma_f32_16x16x32_bf16 v[104:107], v[140:143], v[172:175], v[104:107]
	v_mfma_f32_16x16x32_bf16 v[92:95], v[132:135], v[192:195], v[92:95]
	v_mfma_f32_16x16x32_bf16 v[88:91], v[140:143], v[192:195], v[88:91]
	v_mfma_f32_16x16x32_bf16 v[76:79], v[132:135], v[200:203], v[76:79]
	v_mfma_f32_16x16x32_bf16 v[72:75], v[140:143], v[200:203], v[72:75]
	s_setprio 0
	s_setprio 1
	v_mfma_f32_16x16x32_bf16 v[116:119], v[144:147], v[160:163], v[116:119]
	v_mfma_f32_16x16x32_bf16 v[112:115], v[152:155], v[160:163], v[112:115]
	v_mfma_f32_16x16x32_bf16 v[100:103], v[144:147], v[168:171], v[100:103]
	v_mfma_f32_16x16x32_bf16 v[96:99], v[152:155], v[168:171], v[96:99]
	v_mfma_f32_16x16x32_bf16 v[84:87], v[144:147], v[188:191], v[84:87]
	v_mfma_f32_16x16x32_bf16 v[80:83], v[152:155], v[188:191], v[80:83]
	v_mfma_f32_16x16x32_bf16 v[68:71], v[144:147], v[196:199], v[68:71]
	v_mfma_f32_16x16x32_bf16 v[64:67], v[152:155], v[196:199], v[64:67]
	v_mfma_f32_16x16x32_bf16 v[116:119], v[148:151], v[164:167], v[116:119]
	v_mfma_f32_16x16x32_bf16 v[112:115], v[156:159], v[164:167], v[112:115]
	v_mfma_f32_16x16x32_bf16 v[100:103], v[148:151], v[172:175], v[100:103]
	v_mfma_f32_16x16x32_bf16 v[96:99], v[156:159], v[172:175], v[96:99]
	v_mfma_f32_16x16x32_bf16 v[84:87], v[148:151], v[192:195], v[84:87]
	v_mfma_f32_16x16x32_bf16 v[80:83], v[156:159], v[192:195], v[80:83]
	v_mfma_f32_16x16x32_bf16 v[68:71], v[148:151], v[200:203], v[68:71]
	v_mfma_f32_16x16x32_bf16 v[64:67], v[156:159], v[200:203], v[64:67]
	s_setprio 0
	s_barrier
	s_add_i32 s57, s50, s3
	v_lshl_add_u64 v[204:205], s[0:1], 0, v[176:177]
	s_mov_b32 m0, s57
	ds_read_b128 v[160:163], v211 offset:16384
	ds_read_b128 v[164:167], v211 offset:17408
	ds_read_b128 v[168:171], v211 offset:18432
	ds_read_b128 v[172:175], v211 offset:19456
	ds_read_b128 v[188:191], v211 offset:20480
	ds_read_b128 v[192:195], v211 offset:21504
	ds_read_b128 v[196:199], v211 offset:22528
	ds_read_b128 v[200:203], v211 offset:23552
	global_load_lds_dwordx4 v[204:205], off
	s_add_i32 m0, s57, 0x2000
	s_add_u32 s58, s0, 0x80000
	v_lshl_add_u64 v[212:213], s[0:1], 0, v[178:179]
	s_addc_u32 s59, s1, 0
	s_add_i32 s57, s51, s3
	global_load_lds_dwordx4 v[212:213], off
	v_lshl_add_u64 v[214:215], s[58:59], 0, v[176:177]
	s_mov_b32 m0, s57
	v_lshl_add_u64 v[216:217], s[24:25], 0, v[178:179]
	global_load_lds_dwordx4 v[214:215], off
	v_lshl_add_u64 v[214:215], s[58:59], 0, v[178:179]
	s_add_i32 m0, s57, 0x2000
	s_nop 0
	global_load_lds_dwordx4 v[214:215], off
	v_lshl_add_u64 v[214:215], s[24:25], 0, v[176:177]
	s_mov_b32 m0, s33
	s_nop 0
	global_load_lds_dwordx4 v[214:215], off
	s_mov_b32 m0, s35
	s_nop 0
	global_load_lds_dwordx4 v[216:217], off
	s_waitcnt vmcnt(8)
	s_waitcnt lgkmcnt(0)
	s_barrier
; #define PG8_STAGE(bufoff, gbase, voff) do { _Pragma("unroll") for (int _i = 0; _i < 2; ++_i) \
;         __builtin_amdgcn_global_load_lds((const unsigned*)((const char*)(gbase) + (voff)[_i]), (PG8_LAS unsigned*)(lds + (bufoff) + ldsw + _i * 8192), 16, 0, 0); } while (0)
; #define PG8_LDA(dst, b, h) do { _Pragma("unroll") for (int m = 0; m < 4; ++m) _Pragma("unroll") for (int k = 0; k < 2; ++k) dst[m][k] = *(const PG8_LAS bf16x8*)(lds + PG8_SA(b, h) + aoff + m * 2048 + k * 1024); } while (0)
; #define PG8_LDB(dst, b, h) do { _Pragma("unroll") for (int n = 0; n < 2; ++n) _Pragma("unroll") for (int k = 0; k < 2; ++k) dst[n][k] = *(const PG8_LAS bf16x8*)(lds + PG8_SB(b, h) + boff + n * 2048 + k * 1024); } while (0)
; #define PG8_MMA(ai, bj, At, Bt) do { __builtin_amdgcn_s_setprio(1); _Pragma("unroll") for (int m = 0; m < 4; ++m) _Pragma("unroll") for (int n = 0; n < 2; ++n) _Pragma("unroll") for (int k = 0; k < 2; ++k) \
;         acc[ai][bj][m][n] = __builtin_amdgcn_mfma_f32_16x16x32_bf16(Bt[n][k], At[m][k], acc[ai][bj][m][n], 0, 0, 0); __builtin_amdgcn_s_setprio(0); } while (0)
; #define PG8_WAIT_V(n) asm volatile("s_waitcnt vmcnt(" #n ")" ::: "memory")
; #define PG8_WAIT_L(n) asm volatile("s_waitcnt lgkmcnt(" #n ")" ::: "memory")
; #define PG8_BAR __builtin_amdgcn_s_barrier()
; #define PG8_SCHED __builtin_amdgcn_sched_barrier(0)
; template <class Epi, class Sched, bool ALIGN_EPI = false, bool SP2 = false>
; __device__ __forceinline__ void gemm_phase(PG8_LAS unsigned char* lds, const Gemm g, const Sched& S, const Epi& E) {
;     ...
;             PG8_WAIT_V(8); PG8_WAIT_L(0); PG8_BAR; PG8_MMA(1, 0, At, B0); PG8_MMA(1, 1, At, B1); PG8_BAR; PG8_SCHED;
;             PG8_LDB(B0, 1, 0); PG8_LDB(B1, 1, 1); PG8_SCHED; PG8_LDA(At, 1, 0); PG8_STAGE(PG8_SA(0, 1), a2 + hstep, voffA);
;             PG8_WAIT_V(8); PG8_WAIT_L(0); PG8_BAR; PG8_MMA(0, 0, At, B0); PG8_MMA(0, 1, At, B1); PG8_BAR; PG8_SCHED;
	s_setprio 1
	s_nop 0
	s_waitcnt lgkmcnt(0)
	v_mfma_f32_16x16x32_bf16 v[60:63], v[128:131], v[160:163], v[60:63]
	v_mfma_f32_16x16x32_bf16 v[56:59], v[136:139], v[160:163], v[56:59]
	v_mfma_f32_16x16x32_bf16 v[44:47], v[128:131], v[168:171], v[44:47]
	v_mfma_f32_16x16x32_bf16 v[40:43], v[136:139], v[168:171], v[40:43]
	v_mfma_f32_16x16x32_bf16 v[28:31], v[128:131], v[188:191], v[28:31]
	v_mfma_f32_16x16x32_bf16 v[24:27], v[136:139], v[188:191], v[24:27]
	v_mfma_f32_16x16x32_bf16 v[12:15], v[128:131], v[196:199], v[12:15]
	v_mfma_f32_16x16x32_bf16 v[8:11], v[136:139], v[196:199], v[8:11]
	v_mfma_f32_16x16x32_bf16 v[60:63], v[132:135], v[164:167], v[60:63]
	v_mfma_f32_16x16x32_bf16 v[56:59], v[140:143], v[164:167], v[56:59]
	v_mfma_f32_16x16x32_bf16 v[44:47], v[132:135], v[172:175], v[44:47]
	v_mfma_f32_16x16x32_bf16 v[40:43], v[140:143], v[172:175], v[40:43]
	v_mfma_f32_16x16x32_bf16 v[28:31], v[132:135], v[192:195], v[28:31]
	v_mfma_f32_16x16x32_bf16 v[24:27], v[140:143], v[192:195], v[24:27]
	v_mfma_f32_16x16x32_bf16 v[12:15], v[132:135], v[200:203], v[12:15]
	v_mfma_f32_16x16x32_bf16 v[8:11], v[140:143], v[200:203], v[8:11]
	s_setprio 0
	s_setprio 1
	v_mfma_f32_16x16x32_bf16 v[52:55], v[144:147], v[160:163], v[52:55]
	v_mfma_f32_16x16x32_bf16 v[48:51], v[152:155], v[160:163], v[48:51]
	v_mfma_f32_16x16x32_bf16 v[36:39], v[144:147], v[168:171], v[36:39]
	v_mfma_f32_16x16x32_bf16 v[32:35], v[152:155], v[168:171], v[32:35]
	v_mfma_f32_16x16x32_bf16 v[20:23], v[144:147], v[188:191], v[20:23]
	v_mfma_f32_16x16x32_bf16 v[16:19], v[152:155], v[188:191], v[16:19]
	v_mfma_f32_16x16x32_bf16 v[4:7], v[144:147], v[196:199], v[4:7]
	v_mfma_f32_16x16x32_bf16 v[0:3], v[152:155], v[196:199], v[0:3]
	v_mfma_f32_16x16x32_bf16 v[52:55], v[148:151], v[164:167], v[52:55]
	v_mfma_f32_16x16x32_bf16 v[48:51], v[156:159], v[164:167], v[48:51]
	v_mfma_f32_16x16x32_bf16 v[36:39], v[148:151], v[172:175], v[36:39]
	v_mfma_f32_16x16x32_bf16 v[32:35], v[156:159], v[172:175], v[32:35]
	v_mfma_f32_16x16x32_bf16 v[20:23], v[148:151], v[192:195], v[20:23]
	v_mfma_f32_16x16x32_bf16 v[16:19], v[156:159], v[192:195], v[16:19]
	v_mfma_f32_16x16x32_bf16 v[4:7], v[148:151], v[200:203], v[4:7]
	v_mfma_f32_16x16x32_bf16 v[0:3], v[156:159], v[200:203], v[0:3]
	s_setprio 0
	s_barrier
	s_add_i32 s57, 0, 0x18000
	s_add_i32 s58, 0, 0x1c000
	v_add_u32_e32 v140, s57, v207
	v_add_u32_e32 v156, s58, v207
	ds_read_b128 v[128:131], v140
	ds_read_b128 v[132:135], v140 offset:1024
	ds_read_b128 v[136:139], v140 offset:2048
	ds_read_b128 v[140:143], v140 offset:3072
	ds_read_b128 v[144:147], v156
	ds_read_b128 v[148:151], v156 offset:1024
	ds_read_b128 v[152:155], v156 offset:2048
	ds_read_b128 v[156:159], v156 offset:3072
	s_add_u32 s24, s24, 0x80000
	s_addc_u32 s25, s25, 0
	s_mov_b32 m0, s37
	v_lshl_add_u64 v[218:219], s[24:25], 0, v[176:177]
	ds_read_b128 v[160:163], v211 offset:32768
	ds_read_b128 v[164:167], v211 offset:33792
	ds_read_b128 v[168:171], v211 offset:34816
	ds_read_b128 v[172:175], v211 offset:35840
	ds_read_b128 v[188:191], v211 offset:36864
	ds_read_b128 v[192:195], v211 offset:37888
	ds_read_b128 v[196:199], v211 offset:38912
	ds_read_b128 v[200:203], v211 offset:39936
	global_load_lds_dwordx4 v[218:219], off
	v_lshl_add_u64 v[218:219], s[24:25], 0, v[178:179]
	s_mov_b32 m0, s39
	s_nop 0
	global_load_lds_dwordx4 v[218:219], off
	s_waitcnt vmcnt(8)
	s_waitcnt lgkmcnt(0)
	s_barrier
	s_setprio 1
	s_nop 0
	s_waitcnt lgkmcnt(0)
	v_mfma_f32_16x16x32_bf16 v[124:127], v[128:131], v[160:163], v[124:127]
	v_mfma_f32_16x16x32_bf16 v[120:123], v[136:139], v[160:163], v[120:123]
	v_mfma_f32_16x16x32_bf16 v[108:111], v[128:131], v[168:171], v[108:111]
	v_mfma_f32_16x16x32_bf16 v[104:107], v[136:139], v[168:171], v[104:107]
	v_mfma_f32_16x16x32_bf16 v[92:95], v[128:131], v[188:191], v[92:95]
	v_mfma_f32_16x16x32_bf16 v[88:91], v[136:139], v[188:191], v[88:91]
	v_mfma_f32_16x16x32_bf16 v[76:79], v[128:131], v[196:199], v[76:79]
	v_mfma_f32_16x16x32_bf16 v[72:75], v[136:139], v[196:199], v[72:75]
	v_mfma_f32_16x16x32_bf16 v[124:127], v[132:135], v[164:167], v[124:127]
	v_mfma_f32_16x16x32_bf16 v[120:123], v[140:143], v[164:167], v[120:123]
	v_mfma_f32_16x16x32_bf16 v[108:111], v[132:135], v[172:175], v[108:111]
	v_mfma_f32_16x16x32_bf16 v[104:107], v[140:143], v[172:175], v[104:107]
	v_mfma_f32_16x16x32_bf16 v[92:95], v[132:135], v[192:195], v[92:95]
	v_mfma_f32_16x16x32_bf16 v[88:91], v[140:143], v[192:195], v[88:91]
	v_mfma_f32_16x16x32_bf16 v[76:79], v[132:135], v[200:203], v[76:79]
	v_mfma_f32_16x16x32_bf16 v[72:75], v[140:143], v[200:203], v[72:75]
	s_setprio 0
	s_setprio 1
	v_mfma_f32_16x16x32_bf16 v[116:119], v[144:147], v[160:163], v[116:119]
	v_mfma_f32_16x16x32_bf16 v[112:115], v[152:155], v[160:163], v[112:115]
	v_mfma_f32_16x16x32_bf16 v[100:103], v[144:147], v[168:171], v[100:103]
	v_mfma_f32_16x16x32_bf16 v[96:99], v[152:155], v[168:171], v[96:99]
	v_mfma_f32_16x16x32_bf16 v[84:87], v[144:147], v[188:191], v[84:87]
	v_mfma_f32_16x16x32_bf16 v[80:83], v[152:155], v[188:191], v[80:83]
	v_mfma_f32_16x16x32_bf16 v[68:71], v[144:147], v[196:199], v[68:71]
	v_mfma_f32_16x16x32_bf16 v[64:67], v[152:155], v[196:199], v[64:67]
	v_mfma_f32_16x16x32_bf16 v[116:119], v[148:151], v[164:167], v[116:119]
	v_mfma_f32_16x16x32_bf16 v[112:115], v[156:159], v[164:167], v[112:115]
	v_mfma_f32_16x16x32_bf16 v[100:103], v[148:151], v[172:175], v[100:103]
	v_mfma_f32_16x16x32_bf16 v[96:99], v[156:159], v[172:175], v[96:99]
	v_mfma_f32_16x16x32_bf16 v[84:87], v[148:151], v[192:195], v[84:87]
	v_mfma_f32_16x16x32_bf16 v[80:83], v[156:159], v[192:195], v[80:83]
	v_mfma_f32_16x16x32_bf16 v[68:71], v[148:151], v[200:203], v[68:71]
	v_mfma_f32_16x16x32_bf16 v[64:67], v[156:159], v[200:203], v[64:67]
	s_setprio 0
	s_barrier
; #define PG8_STAGE(bufoff, gbase, voff) do { _Pragma("unroll") for (int _i = 0; _i < 2; ++_i) \
;         __builtin_amdgcn_global_load_lds((const unsigned*)((const char*)(gbase) + (voff)[_i]), (PG8_LAS unsigned*)(lds + (bufoff) + ldsw + _i * 8192), 16, 0, 0); } while (0)
; #define PG8_LDA(dst, b, h) do { _Pragma("unroll") for (int m = 0; m < 4; ++m) _Pragma("unroll") for (int k = 0; k < 2; ++k) dst[m][k] = *(const PG8_LAS bf16x8*)(lds + PG8_SA(b, h) + aoff + m * 2048 + k * 1024); } while (0)
; #define PG8_MMA(ai, bj, At, Bt) do { __builtin_amdgcn_s_setprio(1); _Pragma("unroll") for (int m = 0; m < 4; ++m) _Pragma("unroll") for (int n = 0; n < 2; ++n) _Pragma("unroll") for (int k = 0; k < 2; ++k) \
;         acc[ai][bj][m][n] = __builtin_amdgcn_mfma_f32_16x16x32_bf16(Bt[n][k], At[m][k], acc[ai][bj][m][n], 0, 0, 0); __builtin_amdgcn_s_setprio(0); } while (0)
; #define PG8_WAIT_V(n) asm volatile("s_waitcnt vmcnt(" #n ")" ::: "memory")
; #define PG8_WAIT_L(n) asm volatile("s_waitcnt lgkmcnt(" #n ")" ::: "memory")
; #define PG8_BAR __builtin_amdgcn_s_barrier()
; #define PG8_SCHED __builtin_amdgcn_sched_barrier(0)
; template <class Epi, class Sched, bool ALIGN_EPI = false, bool SP2 = false>
; __device__ __forceinline__ void gemm_phase(PG8_LAS unsigned char* lds, const Gemm g, const Sched& S, const Epi& E) {
;     ...
;         for (int t = 0; t < nt; t += 2) {
;     ...
;             PG8_LDA(At, 1, 1); PG8_STAGE(PG8_SB(1, 0), b3, voffB); PG8_STAGE(PG8_SB(1, 1), b3 + hstep, voffB); PG8_STAGE(PG8_SA(1, 0), a3, voffA);
;             PG8_WAIT_V(8); PG8_WAIT_L(0); PG8_BAR; PG8_MMA(1, 0, At, B0); PG8_MMA(1, 1, At, B1); PG8_BAR; PG8_SCHED;
;     ...
;         if constexpr (ALIGN_EPI) { if (wr == 0) PG8_BAR; }
	s_add_i32 s24, s57, s3
	v_lshl_add_u64 v[204:205], v[204:205], 0, s[16:17]
	s_mov_b32 m0, s24
	ds_read_b128 v[160:163], v211 offset:49152
	ds_read_b128 v[164:167], v211 offset:50176
	ds_read_b128 v[168:171], v211 offset:51200
	ds_read_b128 v[172:175], v211 offset:52224
	ds_read_b128 v[188:191], v211 offset:53248
	ds_read_b128 v[192:195], v211 offset:54272
	ds_read_b128 v[196:199], v211 offset:55296
	ds_read_b128 v[200:203], v211 offset:56320
	global_load_lds_dwordx4 v[204:205], off
	s_add_i32 m0, s24, 0x2000
	s_add_u32 s0, s0, 0x80080
	v_lshl_add_u64 v[204:205], v[212:213], 0, s[16:17]
	s_addc_u32 s1, s1, 0
	s_add_i32 s24, s58, s3
	global_load_lds_dwordx4 v[204:205], off
	v_lshl_add_u64 v[204:205], s[0:1], 0, v[176:177]
	s_mov_b32 m0, s24
	s_nop 0
	global_load_lds_dwordx4 v[204:205], off
	v_lshl_add_u64 v[204:205], s[0:1], 0, v[178:179]
	s_add_i32 m0, s24, 0x2000
	s_nop 0
	global_load_lds_dwordx4 v[204:205], off
	v_lshl_add_u64 v[204:205], v[214:215], 0, s[16:17]
	s_mov_b32 m0, s43
	s_nop 0
	global_load_lds_dwordx4 v[204:205], off
	v_lshl_add_u64 v[204:205], v[216:217], 0, s[16:17]
	s_mov_b32 m0, s44
	s_nop 0
	global_load_lds_dwordx4 v[204:205], off
	s_waitcnt vmcnt(8)
	s_waitcnt lgkmcnt(0)
	s_barrier
	s_setprio 1
	s_waitcnt lgkmcnt(0)
	v_mfma_f32_16x16x32_bf16 v[60:63], v[128:131], v[160:163], v[60:63]
	v_mfma_f32_16x16x32_bf16 v[56:59], v[136:139], v[160:163], v[56:59]
	v_mfma_f32_16x16x32_bf16 v[44:47], v[128:131], v[168:171], v[44:47]
	v_mfma_f32_16x16x32_bf16 v[40:43], v[136:139], v[168:171], v[40:43]
	v_mfma_f32_16x16x32_bf16 v[28:31], v[128:131], v[188:191], v[28:31]
	v_mfma_f32_16x16x32_bf16 v[24:27], v[136:139], v[188:191], v[24:27]
	v_mfma_f32_16x16x32_bf16 v[12:15], v[128:131], v[196:199], v[12:15]
	v_mfma_f32_16x16x32_bf16 v[8:11], v[136:139], v[196:199], v[8:11]
	v_mfma_f32_16x16x32_bf16 v[60:63], v[132:135], v[164:167], v[60:63]
	v_mfma_f32_16x16x32_bf16 v[56:59], v[140:143], v[164:167], v[56:59]
	v_mfma_f32_16x16x32_bf16 v[44:47], v[132:135], v[172:175], v[44:47]
	v_mfma_f32_16x16x32_bf16 v[40:43], v[140:143], v[172:175], v[40:43]
	v_mfma_f32_16x16x32_bf16 v[28:31], v[132:135], v[192:195], v[28:31]
	v_mfma_f32_16x16x32_bf16 v[24:27], v[140:143], v[192:195], v[24:27]
	v_mfma_f32_16x16x32_bf16 v[12:15], v[132:135], v[200:203], v[12:15]
	v_mfma_f32_16x16x32_bf16 v[8:11], v[140:143], v[200:203], v[8:11]
	s_setprio 0
	s_setprio 1
	v_mfma_f32_16x16x32_bf16 v[52:55], v[144:147], v[160:163], v[52:55]
	v_mfma_f32_16x16x32_bf16 v[48:51], v[152:155], v[160:163], v[48:51]
	v_mfma_f32_16x16x32_bf16 v[36:39], v[144:147], v[168:171], v[36:39]
	v_mfma_f32_16x16x32_bf16 v[32:35], v[152:155], v[168:171], v[32:35]
	v_mfma_f32_16x16x32_bf16 v[20:23], v[144:147], v[188:191], v[20:23]
	v_mfma_f32_16x16x32_bf16 v[16:19], v[152:155], v[188:191], v[16:19]
	v_mfma_f32_16x16x32_bf16 v[4:7], v[144:147], v[196:199], v[4:7]
	v_mfma_f32_16x16x32_bf16 v[0:3], v[152:155], v[196:199], v[0:3]
	v_mfma_f32_16x16x32_bf16 v[52:55], v[148:151], v[164:167], v[52:55]
	v_mfma_f32_16x16x32_bf16 v[48:51], v[156:159], v[164:167], v[48:51]
	v_mfma_f32_16x16x32_bf16 v[36:39], v[148:151], v[172:175], v[36:39]
	v_mfma_f32_16x16x32_bf16 v[32:35], v[156:159], v[172:175], v[32:35]
	v_mfma_f32_16x16x32_bf16 v[20:23], v[148:151], v[192:195], v[20:23]
	v_mfma_f32_16x16x32_bf16 v[16:19], v[156:159], v[192:195], v[16:19]
	v_mfma_f32_16x16x32_bf16 v[4:7], v[148:151], v[200:203], v[4:7]
	v_mfma_f32_16x16x32_bf16 v[0:3], v[156:159], v[200:203], v[0:3]
	s_setprio 0
	s_barrier
	s_add_i32 s56, s56, 2
	s_add_u32 s40, s40, 0x100
	s_addc_u32 s41, s41, 0
	s_add_u32 s54, s54, 0x100
	s_addc_u32 s55, s55, 0
	s_cmp_gt_u32 s56, 29
	s_cbranch_scc0 .LBB0_1798
	s_and_b64 vcc, exec, s[18:19]
	s_cbranch_vccz .LBB0_1801
	s_barrier

; #define PG8_STAGE(bufoff, gbase, voff) do { _Pragma("unroll") for (int _i = 0; _i < 2; ++_i) \
;         __builtin_amdgcn_global_load_lds((const unsigned*)((const char*)(gbase) + (voff)[_i]), (PG8_LAS unsigned*)(lds + (bufoff) + ldsw + _i * 8192), 16, 0, 0); } while (0)
; #define PG8_LDA(dst, b, h) do { _Pragma("unroll") for (int m = 0; m < 4; ++m) _Pragma("unroll") for (int k = 0; k < 2; ++k) dst[m][k] = *(const PG8_LAS bf16x8*)(lds + PG8_SA(b, h) + aoff + m * 2048 + k * 1024); } while (0)
; #define PG8_LDB(dst, b, h) do { _Pragma("unroll") for (int n = 0; n < 2; ++n) _Pragma("unroll") for (int k = 0; k < 2; ++k) dst[n][k] = *(const PG8_LAS bf16x8*)(lds + PG8_SB(b, h) + boff + n * 2048 + k * 1024); } while (0)
; #define PG8_MMA(ai, bj, At, Bt) do { __builtin_amdgcn_s_setprio(1); _Pragma("unroll") for (int m = 0; m < 4; ++m) _Pragma("unroll") for (int n = 0; n < 2; ++n) _Pragma("unroll") for (int k = 0; k < 2; ++k) \
;         acc[ai][bj][m][n] = __builtin_amdgcn_mfma_f32_16x16x32_bf16(Bt[n][k], At[m][k], acc[ai][bj][m][n], 0, 0, 0); __builtin_amdgcn_s_setprio(0); } while (0)
; #define PG8_WAIT_V(n) asm volatile("s_waitcnt vmcnt(" #n ")" ::: "memory")
; #define PG8_WAIT_L(n) asm volatile("s_waitcnt lgkmcnt(" #n ")" ::: "memory")
; #define PG8_BAR __builtin_amdgcn_s_barrier()
; #define PG8_SCHED __builtin_amdgcn_sched_barrier(0)
; template <class Epi, class Sched, bool ALIGN_EPI = false, bool SP2 = false>
; __device__ __forceinline__ void gemm_phase(PG8_LAS unsigned char* lds, const Gemm g, const Sched& S, const Epi& E) {
;     ...
;             PG8_LDB(B0, 0, 0); PG8_LDB(B1, 0, 1); PG8_SCHED; PG8_LDA(At, 0, 0); PG8_STAGE(PG8_SA(1, 1), a1 + hstep, voffA);
;             PG8_WAIT_V(8); PG8_WAIT_L(0); PG8_BAR; PG8_MMA(0, 0, At, B0); PG8_MMA(0, 1, At, B1); PG8_BAR; PG8_SCHED;
;             PG8_LDA(At, 0, 1); PG8_STAGE(PG8_SB(0, 0), b2, voffB); PG8_STAGE(PG8_SB(0, 1), b2 + hstep, voffB); PG8_STAGE(PG8_SA(0, 0), a2, voffA);
.LBB0_1882:
	ds_read_b128 v[144:147], v155
	ds_read_b128 v[148:151], v155 offset:1024
	ds_read_b128 v[160:163], v155 offset:2048
	ds_read_b128 v[164:167], v155 offset:3072
	ds_read_b128 v[168:171], v156
	ds_read_b128 v[172:175], v156 offset:1024
	ds_read_b128 v[176:179], v156 offset:2048
	ds_read_b128 v[180:183], v156 offset:3072
	s_add_u32 s0, s30, 0xfff80080
	s_addc_u32 s1, s31, -1
	s_cmp_eq_u32 s55, 28
	s_cselect_b32 s25, s21, s1
	s_cselect_b32 s24, s51, s0
	s_cselect_b32 s1, s19, s54
	s_cselect_b32 s0, s52, s53
	v_lshl_add_u64 v[216:217], s[30:31], 0, v[136:137]
	s_add_i32 m0, s36, 0xc000
	ds_read_b128 v[184:187], v157
	ds_read_b128 v[188:191], v157 offset:1024
	ds_read_b128 v[192:195], v157 offset:2048
	ds_read_b128 v[196:199], v157 offset:3072
	ds_read_b128 v[200:203], v157 offset:4096
	ds_read_b128 v[204:207], v157 offset:5120
	ds_read_b128 v[208:211], v157 offset:6144
	ds_read_b128 v[212:215], v157 offset:7168
	global_load_lds_dwordx4 v[216:217], off
	v_lshl_add_u64 v[216:217], s[30:31], 0, v[138:139]
	s_add_i32 m0, s36, 0xe000
	s_nop 0
	global_load_lds_dwordx4 v[216:217], off
	s_waitcnt vmcnt(8)
	s_waitcnt lgkmcnt(0)
	s_barrier
	s_setprio 1
	s_waitcnt lgkmcnt(0)
	v_mfma_f32_16x16x32_bf16 v[124:127], v[144:147], v[184:187], v[124:127]
	v_mfma_f32_16x16x32_bf16 v[120:123], v[160:163], v[184:187], v[120:123]
	v_mfma_f32_16x16x32_bf16 v[108:111], v[144:147], v[192:195], v[108:111]
	v_mfma_f32_16x16x32_bf16 v[104:107], v[160:163], v[192:195], v[104:107]
	v_mfma_f32_16x16x32_bf16 v[92:95], v[144:147], v[200:203], v[92:95]
	v_mfma_f32_16x16x32_bf16 v[88:91], v[160:163], v[200:203], v[88:91]
	v_mfma_f32_16x16x32_bf16 v[76:79], v[144:147], v[208:211], v[76:79]
	v_mfma_f32_16x16x32_bf16 v[72:75], v[160:163], v[208:211], v[72:75]
	v_mfma_f32_16x16x32_bf16 v[124:127], v[148:151], v[188:191], v[124:127]
	v_mfma_f32_16x16x32_bf16 v[120:123], v[164:167], v[188:191], v[120:123]
	v_mfma_f32_16x16x32_bf16 v[108:111], v[148:151], v[196:199], v[108:111]
	v_mfma_f32_16x16x32_bf16 v[104:107], v[164:167], v[196:199], v[104:107]
	v_mfma_f32_16x16x32_bf16 v[92:95], v[148:151], v[204:207], v[92:95]
	v_mfma_f32_16x16x32_bf16 v[88:91], v[164:167], v[204:207], v[88:91]
	v_mfma_f32_16x16x32_bf16 v[76:79], v[148:151], v[212:215], v[76:79]
	v_mfma_f32_16x16x32_bf16 v[72:75], v[164:167], v[212:215], v[72:75]
	s_setprio 0
	s_setprio 1
	v_mfma_f32_16x16x32_bf16 v[116:119], v[168:171], v[184:187], v[116:119]
	v_mfma_f32_16x16x32_bf16 v[112:115], v[176:179], v[184:187], v[112:115]
	v_mfma_f32_16x16x32_bf16 v[100:103], v[168:171], v[192:195], v[100:103]
	v_mfma_f32_16x16x32_bf16 v[96:99], v[176:179], v[192:195], v[96:99]
	v_mfma_f32_16x16x32_bf16 v[84:87], v[168:171], v[200:203], v[84:87]
	v_mfma_f32_16x16x32_bf16 v[80:83], v[176:179], v[200:203], v[80:83]
	v_mfma_f32_16x16x32_bf16 v[68:71], v[168:171], v[208:211], v[68:71]
	v_mfma_f32_16x16x32_bf16 v[64:67], v[176:179], v[208:211], v[64:67]
	v_mfma_f32_16x16x32_bf16 v[116:119], v[172:175], v[188:191], v[116:119]
	v_mfma_f32_16x16x32_bf16 v[112:115], v[180:183], v[188:191], v[112:115]
	v_mfma_f32_16x16x32_bf16 v[100:103], v[172:175], v[196:199], v[100:103]
	v_mfma_f32_16x16x32_bf16 v[96:99], v[180:183], v[196:199], v[96:99]
	v_mfma_f32_16x16x32_bf16 v[84:87], v[172:175], v[204:207], v[84:87]
	v_mfma_f32_16x16x32_bf16 v[80:83], v[180:183], v[204:207], v[80:83]
	v_mfma_f32_16x16x32_bf16 v[68:71], v[172:175], v[212:215], v[68:71]
	v_mfma_f32_16x16x32_bf16 v[64:67], v[180:183], v[212:215], v[64:67]
	s_setprio 0
	s_barrier
	s_add_i32 s56, s45, s3
	v_lshl_add_u64 v[216:217], s[0:1], 0, v[132:133]
	s_mov_b32 m0, s56
	ds_read_b128 v[184:187], v157 offset:16384
	ds_read_b128 v[188:191], v157 offset:17408
	ds_read_b128 v[192:195], v157 offset:18432
	ds_read_b128 v[196:199], v157 offset:19456
	ds_read_b128 v[200:203], v157 offset:20480
	ds_read_b128 v[204:207], v157 offset:21504
	ds_read_b128 v[208:211], v157 offset:22528
	ds_read_b128 v[212:215], v157 offset:23552
	global_load_lds_dwordx4 v[216:217], off
	s_add_i32 m0, s56, 0x2000
	s_add_u32 s56, s0, 0x80000
	v_lshl_add_u64 v[218:219], s[0:1], 0, v[128:129]
	s_addc_u32 s57, s1, 0
	s_add_i32 s58, s46, s3
	global_load_lds_dwordx4 v[218:219], off
	v_lshl_add_u64 v[220:221], s[56:57], 0, v[132:133]
	s_mov_b32 m0, s58
	v_lshl_add_u64 v[224:225], s[24:25], 0, v[130:131]
	global_load_lds_dwordx4 v[220:221], off
	v_lshl_add_u64 v[220:221], s[56:57], 0, v[128:129]
	s_add_i32 m0, s58, 0x2000
	s_nop 0
	global_load_lds_dwordx4 v[220:221], off
	v_lshl_add_u64 v[220:221], s[24:25], 0, v[134:135]
	s_mov_b32 m0, s36
	s_nop 0
	global_load_lds_dwordx4 v[220:221], off
	s_mov_b32 m0, s37
	s_nop 0
	global_load_lds_dwordx4 v[224:225], off
	s_waitcnt vmcnt(8)
	s_waitcnt lgkmcnt(0)
	s_barrier
; #define PG8_STAGE(bufoff, gbase, voff) do { _Pragma("unroll") for (int _i = 0; _i < 2; ++_i) \
;         __builtin_amdgcn_global_load_lds((const unsigned*)((const char*)(gbase) + (voff)[_i]), (PG8_LAS unsigned*)(lds + (bufoff) + ldsw + _i * 8192), 16, 0, 0); } while (0)
; #define PG8_LDA(dst, b, h) do { _Pragma("unroll") for (int m = 0; m < 4; ++m) _Pragma("unroll") for (int k = 0; k < 2; ++k) dst[m][k] = *(const PG8_LAS bf16x8*)(lds + PG8_SA(b, h) + aoff + m * 2048 + k * 1024); } while (0)
; #define PG8_LDB(dst, b, h) do { _Pragma("unroll") for (int n = 0; n < 2; ++n) _Pragma("unroll") for (int k = 0; k < 2; ++k) dst[n][k] = *(const PG8_LAS bf16x8*)(lds + PG8_SB(b, h) + boff + n * 2048 + k * 1024); } while (0)
; #define PG8_MMA(ai, bj, At, Bt) do { __builtin_amdgcn_s_setprio(1); _Pragma("unroll") for (int m = 0; m < 4; ++m) _Pragma("unroll") for (int n = 0; n < 2; ++n) _Pragma("unroll") for (int k = 0; k < 2; ++k) \
;         acc[ai][bj][m][n] = __builtin_amdgcn_mfma_f32_16x16x32_bf16(Bt[n][k], At[m][k], acc[ai][bj][m][n], 0, 0, 0); __builtin_amdgcn_s_setprio(0); } while (0)
; #define PG8_WAIT_V(n) asm volatile("s_waitcnt vmcnt(" #n ")" ::: "memory")
; #define PG8_WAIT_L(n) asm volatile("s_waitcnt lgkmcnt(" #n ")" ::: "memory")
; #define PG8_BAR __builtin_amdgcn_s_barrier()
; #define PG8_SCHED __builtin_amdgcn_sched_barrier(0)
; template <class Epi, class Sched, bool ALIGN_EPI = false, bool SP2 = false>
; __device__ __forceinline__ void gemm_phase(PG8_LAS unsigned char* lds, const Gemm g, const Sched& S, const Epi& E) {
;     ...
;             PG8_WAIT_V(8); PG8_WAIT_L(0); PG8_BAR; PG8_MMA(1, 0, At, B0); PG8_MMA(1, 1, At, B1); PG8_BAR; PG8_SCHED;
;             PG8_LDB(B0, 1, 0); PG8_LDB(B1, 1, 1); PG8_SCHED; PG8_LDA(At, 1, 0); PG8_STAGE(PG8_SA(0, 1), a2 + hstep, voffA);
;             PG8_WAIT_V(8); PG8_WAIT_L(0); PG8_BAR; PG8_MMA(0, 0, At, B0); PG8_MMA(0, 1, At, B1); PG8_BAR; PG8_SCHED;
	s_setprio 1
	s_nop 0
	s_waitcnt lgkmcnt(0)
	v_mfma_f32_16x16x32_bf16 v[60:63], v[144:147], v[184:187], v[60:63]
	v_mfma_f32_16x16x32_bf16 v[56:59], v[160:163], v[184:187], v[56:59]
	v_mfma_f32_16x16x32_bf16 v[44:47], v[144:147], v[192:195], v[44:47]
	v_mfma_f32_16x16x32_bf16 v[40:43], v[160:163], v[192:195], v[40:43]
	v_mfma_f32_16x16x32_bf16 v[28:31], v[144:147], v[200:203], v[28:31]
	v_mfma_f32_16x16x32_bf16 v[24:27], v[160:163], v[200:203], v[24:27]
	v_mfma_f32_16x16x32_bf16 v[12:15], v[144:147], v[208:211], v[12:15]
	v_mfma_f32_16x16x32_bf16 v[8:11], v[160:163], v[208:211], v[8:11]
	v_mfma_f32_16x16x32_bf16 v[60:63], v[148:151], v[188:191], v[60:63]
	v_mfma_f32_16x16x32_bf16 v[56:59], v[164:167], v[188:191], v[56:59]
	v_mfma_f32_16x16x32_bf16 v[44:47], v[148:151], v[196:199], v[44:47]
	v_mfma_f32_16x16x32_bf16 v[40:43], v[164:167], v[196:199], v[40:43]
	v_mfma_f32_16x16x32_bf16 v[28:31], v[148:151], v[204:207], v[28:31]
	v_mfma_f32_16x16x32_bf16 v[24:27], v[164:167], v[204:207], v[24:27]
	v_mfma_f32_16x16x32_bf16 v[12:15], v[148:151], v[212:215], v[12:15]
	v_mfma_f32_16x16x32_bf16 v[8:11], v[164:167], v[212:215], v[8:11]
	s_setprio 0
	s_setprio 1
	v_mfma_f32_16x16x32_bf16 v[52:55], v[168:171], v[184:187], v[52:55]
	v_mfma_f32_16x16x32_bf16 v[48:51], v[176:179], v[184:187], v[48:51]
	v_mfma_f32_16x16x32_bf16 v[36:39], v[168:171], v[192:195], v[36:39]
	v_mfma_f32_16x16x32_bf16 v[32:35], v[176:179], v[192:195], v[32:35]
	v_mfma_f32_16x16x32_bf16 v[20:23], v[168:171], v[200:203], v[20:23]
	v_mfma_f32_16x16x32_bf16 v[16:19], v[176:179], v[200:203], v[16:19]
	v_mfma_f32_16x16x32_bf16 v[4:7], v[168:171], v[208:211], v[4:7]
	v_mfma_f32_16x16x32_bf16 v[0:3], v[176:179], v[208:211], v[0:3]
	v_mfma_f32_16x16x32_bf16 v[52:55], v[172:175], v[188:191], v[52:55]
	v_mfma_f32_16x16x32_bf16 v[48:51], v[180:183], v[188:191], v[48:51]
	v_mfma_f32_16x16x32_bf16 v[36:39], v[172:175], v[196:199], v[36:39]
	v_mfma_f32_16x16x32_bf16 v[32:35], v[180:183], v[196:199], v[32:35]
	v_mfma_f32_16x16x32_bf16 v[20:23], v[172:175], v[204:207], v[20:23]
	v_mfma_f32_16x16x32_bf16 v[16:19], v[180:183], v[204:207], v[16:19]
	v_mfma_f32_16x16x32_bf16 v[4:7], v[172:175], v[212:215], v[4:7]
	v_mfma_f32_16x16x32_bf16 v[0:3], v[180:183], v[212:215], v[0:3]
	s_setprio 0
	s_barrier
	s_add_i32 s56, 0, 0x18000
	s_add_i32 s57, 0, 0x1c000
	v_add_u32_e32 v164, s56, v153
	v_add_u32_e32 v180, s57, v153
	ds_read_b128 v[144:147], v164
	ds_read_b128 v[148:151], v164 offset:1024
	ds_read_b128 v[160:163], v164 offset:2048
	ds_read_b128 v[164:167], v164 offset:3072
	ds_read_b128 v[168:171], v180
	ds_read_b128 v[172:175], v180 offset:1024
	ds_read_b128 v[176:179], v180 offset:2048
	ds_read_b128 v[180:183], v180 offset:3072
	s_add_u32 s24, s24, 0x80000
	s_addc_u32 s25, s25, 0
	s_mov_b32 m0, s38
	v_lshl_add_u64 v[228:229], s[24:25], 0, v[134:135]
	ds_read_b128 v[184:187], v157 offset:32768
	ds_read_b128 v[188:191], v157 offset:33792
	ds_read_b128 v[192:195], v157 offset:34816
	ds_read_b128 v[196:199], v157 offset:35840
	ds_read_b128 v[200:203], v157 offset:36864
	ds_read_b128 v[204:207], v157 offset:37888
	ds_read_b128 v[208:211], v157 offset:38912
	ds_read_b128 v[212:215], v157 offset:39936
	global_load_lds_dwordx4 v[228:229], off
	v_lshl_add_u64 v[228:229], s[24:25], 0, v[130:131]
	s_mov_b32 m0, s39
	s_nop 0
	global_load_lds_dwordx4 v[228:229], off
	s_waitcnt vmcnt(8)
	s_waitcnt lgkmcnt(0)
	s_barrier
	s_setprio 1
	s_nop 0
	s_waitcnt lgkmcnt(0)
	v_mfma_f32_16x16x32_bf16 v[124:127], v[144:147], v[184:187], v[124:127]
	v_mfma_f32_16x16x32_bf16 v[120:123], v[160:163], v[184:187], v[120:123]
	v_mfma_f32_16x16x32_bf16 v[108:111], v[144:147], v[192:195], v[108:111]
	v_mfma_f32_16x16x32_bf16 v[104:107], v[160:163], v[192:195], v[104:107]
	v_mfma_f32_16x16x32_bf16 v[92:95], v[144:147], v[200:203], v[92:95]
	v_mfma_f32_16x16x32_bf16 v[88:91], v[160:163], v[200:203], v[88:91]
	v_mfma_f32_16x16x32_bf16 v[76:79], v[144:147], v[208:211], v[76:79]
	v_mfma_f32_16x16x32_bf16 v[72:75], v[160:163], v[208:211], v[72:75]
	v_mfma_f32_16x16x32_bf16 v[124:127], v[148:151], v[188:191], v[124:127]
	v_mfma_f32_16x16x32_bf16 v[120:123], v[164:167], v[188:191], v[120:123]
	v_mfma_f32_16x16x32_bf16 v[108:111], v[148:151], v[196:199], v[108:111]
	v_mfma_f32_16x16x32_bf16 v[104:107], v[164:167], v[196:199], v[104:107]
	v_mfma_f32_16x16x32_bf16 v[92:95], v[148:151], v[204:207], v[92:95]
	v_mfma_f32_16x16x32_bf16 v[88:91], v[164:167], v[204:207], v[88:91]
	v_mfma_f32_16x16x32_bf16 v[76:79], v[148:151], v[212:215], v[76:79]
	v_mfma_f32_16x16x32_bf16 v[72:75], v[164:167], v[212:215], v[72:75]
	s_setprio 0
	s_setprio 1
	v_mfma_f32_16x16x32_bf16 v[116:119], v[168:171], v[184:187], v[116:119]
	v_mfma_f32_16x16x32_bf16 v[112:115], v[176:179], v[184:187], v[112:115]
	v_mfma_f32_16x16x32_bf16 v[100:103], v[168:171], v[192:195], v[100:103]
	v_mfma_f32_16x16x32_bf16 v[96:99], v[176:179], v[192:195], v[96:99]
	v_mfma_f32_16x16x32_bf16 v[84:87], v[168:171], v[200:203], v[84:87]
	v_mfma_f32_16x16x32_bf16 v[80:83], v[176:179], v[200:203], v[80:83]
	v_mfma_f32_16x16x32_bf16 v[68:71], v[168:171], v[208:211], v[68:71]
	v_mfma_f32_16x16x32_bf16 v[64:67], v[176:179], v[208:211], v[64:67]
	v_mfma_f32_16x16x32_bf16 v[116:119], v[172:175], v[188:191], v[116:119]
	v_mfma_f32_16x16x32_bf16 v[112:115], v[180:183], v[188:191], v[112:115]
	v_mfma_f32_16x16x32_bf16 v[100:103], v[172:175], v[196:199], v[100:103]
	v_mfma_f32_16x16x32_bf16 v[96:99], v[180:183], v[196:199], v[96:99]
	v_mfma_f32_16x16x32_bf16 v[84:87], v[172:175], v[204:207], v[84:87]
	v_mfma_f32_16x16x32_bf16 v[80:83], v[180:183], v[204:207], v[80:83]
	v_mfma_f32_16x16x32_bf16 v[68:71], v[172:175], v[212:215], v[68:71]
	v_mfma_f32_16x16x32_bf16 v[64:67], v[180:183], v[212:215], v[64:67]
	s_setprio 0
	s_barrier
; #define PG8_STAGE(bufoff, gbase, voff) do { _Pragma("unroll") for (int _i = 0; _i < 2; ++_i) \
;         __builtin_amdgcn_global_load_lds((const unsigned*)((const char*)(gbase) + (voff)[_i]), (PG8_LAS unsigned*)(lds + (bufoff) + ldsw + _i * 8192), 16, 0, 0); } while (0)
; #define PG8_LDA(dst, b, h) do { _Pragma("unroll") for (int m = 0; m < 4; ++m) _Pragma("unroll") for (int k = 0; k < 2; ++k) dst[m][k] = *(const PG8_LAS bf16x8*)(lds + PG8_SA(b, h) + aoff + m * 2048 + k * 1024); } while (0)
; #define PG8_MMA(ai, bj, At, Bt) do { __builtin_amdgcn_s_setprio(1); _Pragma("unroll") for (int m = 0; m < 4; ++m) _Pragma("unroll") for (int n = 0; n < 2; ++n) _Pragma("unroll") for (int k = 0; k < 2; ++k) \
;         acc[ai][bj][m][n] = __builtin_amdgcn_mfma_f32_16x16x32_bf16(Bt[n][k], At[m][k], acc[ai][bj][m][n], 0, 0, 0); __builtin_amdgcn_s_setprio(0); } while (0)
; #define PG8_WAIT_V(n) asm volatile("s_waitcnt vmcnt(" #n ")" ::: "memory")
; #define PG8_WAIT_L(n) asm volatile("s_waitcnt lgkmcnt(" #n ")" ::: "memory")
; #define PG8_BAR __builtin_amdgcn_s_barrier()
; #define PG8_SCHED __builtin_amdgcn_sched_barrier(0)
; template <class Epi, class Sched, bool ALIGN_EPI = false, bool SP2 = false>
; __device__ __forceinline__ void gemm_phase(PG8_LAS unsigned char* lds, const Gemm g, const Sched& S, const Epi& E) {
;     ...
;         for (int t = 0; t < nt; t += 2) {
;     ...
;             PG8_LDA(At, 1, 1); PG8_STAGE(PG8_SB(1, 0), b3, voffB); PG8_STAGE(PG8_SB(1, 1), b3 + hstep, voffB); PG8_STAGE(PG8_SA(1, 0), a3, voffA);
;             PG8_WAIT_V(8); PG8_WAIT_L(0); PG8_BAR; PG8_MMA(1, 0, At, B0); PG8_MMA(1, 1, At, B1); PG8_BAR; PG8_SCHED;
;     ...
;         if constexpr (ALIGN_EPI) { if (wr == 0) PG8_BAR; }
	s_add_i32 s24, s56, s3
	v_lshl_add_u64 v[216:217], v[216:217], 0, s[14:15]
	s_mov_b32 m0, s24
	ds_read_b128 v[184:187], v157 offset:49152
	ds_read_b128 v[188:191], v157 offset:50176
	ds_read_b128 v[192:195], v157 offset:51200
	ds_read_b128 v[196:199], v157 offset:52224
	ds_read_b128 v[200:203], v157 offset:53248
	ds_read_b128 v[204:207], v157 offset:54272
	ds_read_b128 v[208:211], v157 offset:55296
	ds_read_b128 v[212:215], v157 offset:56320
	global_load_lds_dwordx4 v[216:217], off
	s_add_i32 m0, s24, 0x2000
	s_add_u32 s0, s0, 0x80080
	v_lshl_add_u64 v[216:217], v[218:219], 0, s[14:15]
	s_addc_u32 s1, s1, 0
	s_add_i32 s24, s57, s3
	global_load_lds_dwordx4 v[216:217], off
	v_lshl_add_u64 v[216:217], s[0:1], 0, v[132:133]
	s_mov_b32 m0, s24
	s_nop 0
	global_load_lds_dwordx4 v[216:217], off
	v_lshl_add_u64 v[216:217], s[0:1], 0, v[128:129]
	s_add_i32 m0, s24, 0x2000
	s_nop 0
	global_load_lds_dwordx4 v[216:217], off
	v_lshl_add_u64 v[216:217], v[220:221], 0, s[14:15]
	s_mov_b32 m0, s41
	s_nop 0
	global_load_lds_dwordx4 v[216:217], off
	v_lshl_add_u64 v[216:217], v[224:225], 0, s[14:15]
	s_mov_b32 m0, s42
	s_nop 0
	global_load_lds_dwordx4 v[216:217], off
	s_waitcnt vmcnt(8)
	s_waitcnt lgkmcnt(0)
	s_barrier
	s_setprio 1
	s_waitcnt lgkmcnt(0)
	v_mfma_f32_16x16x32_bf16 v[60:63], v[144:147], v[184:187], v[60:63]
	v_mfma_f32_16x16x32_bf16 v[56:59], v[160:163], v[184:187], v[56:59]
	v_mfma_f32_16x16x32_bf16 v[44:47], v[144:147], v[192:195], v[44:47]
	v_mfma_f32_16x16x32_bf16 v[40:43], v[160:163], v[192:195], v[40:43]
	v_mfma_f32_16x16x32_bf16 v[28:31], v[144:147], v[200:203], v[28:31]
	v_mfma_f32_16x16x32_bf16 v[24:27], v[160:163], v[200:203], v[24:27]
	v_mfma_f32_16x16x32_bf16 v[12:15], v[144:147], v[208:211], v[12:15]
	v_mfma_f32_16x16x32_bf16 v[8:11], v[160:163], v[208:211], v[8:11]
	v_mfma_f32_16x16x32_bf16 v[60:63], v[148:151], v[188:191], v[60:63]
	v_mfma_f32_16x16x32_bf16 v[56:59], v[164:167], v[188:191], v[56:59]
	v_mfma_f32_16x16x32_bf16 v[44:47], v[148:151], v[196:199], v[44:47]
	v_mfma_f32_16x16x32_bf16 v[40:43], v[164:167], v[196:199], v[40:43]
	v_mfma_f32_16x16x32_bf16 v[28:31], v[148:151], v[204:207], v[28:31]
	v_mfma_f32_16x16x32_bf16 v[24:27], v[164:167], v[204:207], v[24:27]
	v_mfma_f32_16x16x32_bf16 v[12:15], v[148:151], v[212:215], v[12:15]
	v_mfma_f32_16x16x32_bf16 v[8:11], v[164:167], v[212:215], v[8:11]
	s_setprio 0
	s_setprio 1
	v_mfma_f32_16x16x32_bf16 v[52:55], v[168:171], v[184:187], v[52:55]
	v_mfma_f32_16x16x32_bf16 v[48:51], v[176:179], v[184:187], v[48:51]
	v_mfma_f32_16x16x32_bf16 v[36:39], v[168:171], v[192:195], v[36:39]
	v_mfma_f32_16x16x32_bf16 v[32:35], v[176:179], v[192:195], v[32:35]
	v_mfma_f32_16x16x32_bf16 v[20:23], v[168:171], v[200:203], v[20:23]
	v_mfma_f32_16x16x32_bf16 v[16:19], v[176:179], v[200:203], v[16:19]
	v_mfma_f32_16x16x32_bf16 v[4:7], v[168:171], v[208:211], v[4:7]
	v_mfma_f32_16x16x32_bf16 v[0:3], v[176:179], v[208:211], v[0:3]
	v_mfma_f32_16x16x32_bf16 v[52:55], v[172:175], v[188:191], v[52:55]
	v_mfma_f32_16x16x32_bf16 v[48:51], v[180:183], v[188:191], v[48:51]
	v_mfma_f32_16x16x32_bf16 v[36:39], v[172:175], v[196:199], v[36:39]
	v_mfma_f32_16x16x32_bf16 v[32:35], v[180:183], v[196:199], v[32:35]
	v_mfma_f32_16x16x32_bf16 v[20:23], v[172:175], v[204:207], v[20:23]
	v_mfma_f32_16x16x32_bf16 v[16:19], v[180:183], v[204:207], v[16:19]
	v_mfma_f32_16x16x32_bf16 v[4:7], v[172:175], v[212:215], v[4:7]
	v_mfma_f32_16x16x32_bf16 v[0:3], v[180:183], v[212:215], v[0:3]
	s_setprio 0
	s_barrier
	s_add_i32 s55, s55, 2
	s_add_u32 s30, s30, 0x100
	s_addc_u32 s31, s31, 0
	s_add_u32 s53, s53, 0x100
	s_addc_u32 s54, s54, 0
	s_cmp_gt_u32 s55, 29
	s_cbranch_scc0 .LBB0_1882
	s_and_b64 vcc, exec, s[16:17]
	s_cbranch_vccz .LBB0_1885
	s_barrier

; #define PG8_STAGE(bufoff, gbase, voff) do { _Pragma("unroll") for (int _i = 0; _i < 2; ++_i) \
;         __builtin_amdgcn_global_load_lds((const unsigned*)((const char*)(gbase) + (voff)[_i]), (PG8_LAS unsigned*)(lds + (bufoff) + ldsw + _i * 8192), 16, 0, 0); } while (0)
; #define PG8_LDA(dst, b, h) do { _Pragma("unroll") for (int m = 0; m < 4; ++m) _Pragma("unroll") for (int k = 0; k < 2; ++k) dst[m][k] = *(const PG8_LAS bf16x8*)(lds + PG8_SA(b, h) + aoff + m * 2048 + k * 1024); } while (0)
; #define PG8_LDB(dst, b, h) do { _Pragma("unroll") for (int n = 0; n < 2; ++n) _Pragma("unroll") for (int k = 0; k < 2; ++k) dst[n][k] = *(const PG8_LAS bf16x8*)(lds + PG8_SB(b, h) + boff + n * 2048 + k * 1024); } while (0)
; #define PG8_MMA(ai, bj, At, Bt) do { __builtin_amdgcn_s_setprio(1); _Pragma("unroll") for (int m = 0; m < 4; ++m) _Pragma("unroll") for (int n = 0; n < 2; ++n) _Pragma("unroll") for (int k = 0; k < 2; ++k) \
;         acc[ai][bj][m][n] = __builtin_amdgcn_mfma_f32_16x16x32_bf16(Bt[n][k], At[m][k], acc[ai][bj][m][n], 0, 0, 0); __builtin_amdgcn_s_setprio(0); } while (0)
; #define PG8_WAIT_V(n) asm volatile("s_waitcnt vmcnt(" #n ")" ::: "memory")
; #define PG8_WAIT_L(n) asm volatile("s_waitcnt lgkmcnt(" #n ")" ::: "memory")
; #define PG8_BAR __builtin_amdgcn_s_barrier()
; #define PG8_SCHED __builtin_amdgcn_sched_barrier(0)
; template <class Epi, class Sched, bool ALIGN_EPI = false, bool SP2 = false>
; __device__ __forceinline__ void gemm_phase(PG8_LAS unsigned char* lds, const Gemm g, const Sched& S, const Epi& E) {
;     ...
;             PG8_LDB(B0, 0, 0); PG8_LDB(B1, 0, 1); PG8_SCHED; PG8_LDA(At, 0, 0); PG8_STAGE(PG8_SA(1, 1), a1 + hstep, voffA);
;             PG8_WAIT_V(8); PG8_WAIT_L(0); PG8_BAR; PG8_MMA(0, 0, At, B0); PG8_MMA(0, 1, At, B1); PG8_BAR; PG8_SCHED;
;             PG8_LDA(At, 0, 1); PG8_STAGE(PG8_SB(0, 0), b2, voffB); PG8_STAGE(PG8_SB(0, 1), b2 + hstep, voffB); PG8_STAGE(PG8_SA(0, 0), a2, voffA);
.LBB0_1965:
	ds_read_b128 v[128:131], v209
	ds_read_b128 v[132:135], v209 offset:1024
	ds_read_b128 v[136:139], v209 offset:2048
	ds_read_b128 v[140:143], v209 offset:3072
	ds_read_b128 v[144:147], v210
	ds_read_b128 v[148:151], v210 offset:1024
	ds_read_b128 v[152:155], v210 offset:2048
	ds_read_b128 v[156:159], v210 offset:3072
	s_add_u32 s0, s22, 0x100
	s_addc_u32 s1, s23, 0
	s_cmpk_eq_i32 s50, 0x54
	s_cselect_b32 s29, s7, s1
	s_cselect_b32 s28, s6, s0
	s_cselect_b32 s25, s21, s49
	s_cselect_b32 s24, s20, s48
	v_lshl_add_u64 v[204:205], s[22:23], 0, v[180:181]
	s_add_i32 m0, s30, 0xc000
	ds_read_b128 v[160:163], v211
	ds_read_b128 v[164:167], v211 offset:1024
	ds_read_b128 v[168:171], v211 offset:2048
	ds_read_b128 v[172:175], v211 offset:3072
	ds_read_b128 v[188:191], v211 offset:4096
	ds_read_b128 v[192:195], v211 offset:5120
	ds_read_b128 v[196:199], v211 offset:6144
	ds_read_b128 v[200:203], v211 offset:7168
	global_load_lds_dwordx4 v[204:205], off
	v_lshl_add_u64 v[204:205], s[22:23], 0, v[182:183]
	s_add_i32 m0, s30, 0xe000
	s_nop 0
	global_load_lds_dwordx4 v[204:205], off
	s_waitcnt vmcnt(8)
	s_waitcnt lgkmcnt(0)
	s_barrier
	s_setprio 1
	s_nop 0
	s_waitcnt lgkmcnt(0)
	v_mfma_f32_16x16x32_bf16 v[124:127], v[128:131], v[160:163], v[124:127]
	v_mfma_f32_16x16x32_bf16 v[120:123], v[136:139], v[160:163], v[120:123]
	v_mfma_f32_16x16x32_bf16 v[108:111], v[128:131], v[168:171], v[108:111]
	v_mfma_f32_16x16x32_bf16 v[104:107], v[136:139], v[168:171], v[104:107]
	v_mfma_f32_16x16x32_bf16 v[92:95], v[128:131], v[188:191], v[92:95]
	v_mfma_f32_16x16x32_bf16 v[88:91], v[136:139], v[188:191], v[88:91]
	v_mfma_f32_16x16x32_bf16 v[76:79], v[128:131], v[196:199], v[76:79]
	v_mfma_f32_16x16x32_bf16 v[72:75], v[136:139], v[196:199], v[72:75]
	v_mfma_f32_16x16x32_bf16 v[124:127], v[132:135], v[164:167], v[124:127]
	v_mfma_f32_16x16x32_bf16 v[120:123], v[140:143], v[164:167], v[120:123]
	v_mfma_f32_16x16x32_bf16 v[108:111], v[132:135], v[172:175], v[108:111]
	v_mfma_f32_16x16x32_bf16 v[104:107], v[140:143], v[172:175], v[104:107]
	v_mfma_f32_16x16x32_bf16 v[92:95], v[132:135], v[192:195], v[92:95]
	v_mfma_f32_16x16x32_bf16 v[88:91], v[140:143], v[192:195], v[88:91]
	v_mfma_f32_16x16x32_bf16 v[76:79], v[132:135], v[200:203], v[76:79]
	v_mfma_f32_16x16x32_bf16 v[72:75], v[140:143], v[200:203], v[72:75]
	s_setprio 0
	s_setprio 1
	v_mfma_f32_16x16x32_bf16 v[116:119], v[144:147], v[160:163], v[116:119]
	v_mfma_f32_16x16x32_bf16 v[112:115], v[152:155], v[160:163], v[112:115]
	v_mfma_f32_16x16x32_bf16 v[100:103], v[144:147], v[168:171], v[100:103]
	v_mfma_f32_16x16x32_bf16 v[96:99], v[152:155], v[168:171], v[96:99]
	v_mfma_f32_16x16x32_bf16 v[84:87], v[144:147], v[188:191], v[84:87]
	v_mfma_f32_16x16x32_bf16 v[80:83], v[152:155], v[188:191], v[80:83]
	v_mfma_f32_16x16x32_bf16 v[68:71], v[144:147], v[196:199], v[68:71]
	v_mfma_f32_16x16x32_bf16 v[64:67], v[152:155], v[196:199], v[64:67]
	v_mfma_f32_16x16x32_bf16 v[116:119], v[148:151], v[164:167], v[116:119]
	v_mfma_f32_16x16x32_bf16 v[112:115], v[156:159], v[164:167], v[112:115]
	v_mfma_f32_16x16x32_bf16 v[100:103], v[148:151], v[172:175], v[100:103]
	v_mfma_f32_16x16x32_bf16 v[96:99], v[156:159], v[172:175], v[96:99]
	v_mfma_f32_16x16x32_bf16 v[84:87], v[148:151], v[192:195], v[84:87]
	v_mfma_f32_16x16x32_bf16 v[80:83], v[156:159], v[192:195], v[80:83]
	v_mfma_f32_16x16x32_bf16 v[68:71], v[148:151], v[200:203], v[68:71]
	v_mfma_f32_16x16x32_bf16 v[64:67], v[156:159], v[200:203], v[64:67]
	s_setprio 0
	s_barrier
	s_add_i32 s22, s42, s3
	v_lshl_add_u64 v[204:205], s[24:25], 0, v[176:177]
	s_mov_b32 m0, s22
	ds_read_b128 v[160:163], v211 offset:16384
	ds_read_b128 v[164:167], v211 offset:17408
	ds_read_b128 v[168:171], v211 offset:18432
	ds_read_b128 v[172:175], v211 offset:19456
	ds_read_b128 v[188:191], v211 offset:20480
	ds_read_b128 v[192:195], v211 offset:21504
	ds_read_b128 v[196:199], v211 offset:22528
	ds_read_b128 v[200:203], v211 offset:23552
	global_load_lds_dwordx4 v[204:205], off
	s_add_i32 m0, s22, 0x2000
	s_add_u32 s22, s24, 0x160000
	v_lshl_add_u64 v[212:213], s[24:25], 0, v[178:179]
	s_addc_u32 s23, s25, 0
	s_add_i32 s51, s43, s3
	global_load_lds_dwordx4 v[212:213], off
	v_lshl_add_u64 v[214:215], s[22:23], 0, v[176:177]
	s_mov_b32 m0, s51
	v_lshl_add_u64 v[216:217], s[28:29], 0, v[178:179]
	global_load_lds_dwordx4 v[214:215], off
	v_lshl_add_u64 v[214:215], s[22:23], 0, v[178:179]
	s_add_i32 m0, s51, 0x2000
	s_nop 0
	global_load_lds_dwordx4 v[214:215], off
	v_lshl_add_u64 v[214:215], s[28:29], 0, v[176:177]
	s_mov_b32 m0, s30
	s_nop 0
	global_load_lds_dwordx4 v[214:215], off
	s_mov_b32 m0, s31
	s_nop 0
	global_load_lds_dwordx4 v[216:217], off
	s_waitcnt vmcnt(8)
	s_waitcnt lgkmcnt(0)
	s_barrier
; #define PG8_STAGE(bufoff, gbase, voff) do { _Pragma("unroll") for (int _i = 0; _i < 2; ++_i) \
;         __builtin_amdgcn_global_load_lds((const unsigned*)((const char*)(gbase) + (voff)[_i]), (PG8_LAS unsigned*)(lds + (bufoff) + ldsw + _i * 8192), 16, 0, 0); } while (0)
; #define PG8_LDA(dst, b, h) do { _Pragma("unroll") for (int m = 0; m < 4; ++m) _Pragma("unroll") for (int k = 0; k < 2; ++k) dst[m][k] = *(const PG8_LAS bf16x8*)(lds + PG8_SA(b, h) + aoff + m * 2048 + k * 1024); } while (0)
; #define PG8_LDB(dst, b, h) do { _Pragma("unroll") for (int n = 0; n < 2; ++n) _Pragma("unroll") for (int k = 0; k < 2; ++k) dst[n][k] = *(const PG8_LAS bf16x8*)(lds + PG8_SB(b, h) + boff + n * 2048 + k * 1024); } while (0)
; #define PG8_MMA(ai, bj, At, Bt) do { __builtin_amdgcn_s_setprio(1); _Pragma("unroll") for (int m = 0; m < 4; ++m) _Pragma("unroll") for (int n = 0; n < 2; ++n) _Pragma("unroll") for (int k = 0; k < 2; ++k) \
;         acc[ai][bj][m][n] = __builtin_amdgcn_mfma_f32_16x16x32_bf16(Bt[n][k], At[m][k], acc[ai][bj][m][n], 0, 0, 0); __builtin_amdgcn_s_setprio(0); } while (0)
; #define PG8_WAIT_V(n) asm volatile("s_waitcnt vmcnt(" #n ")" ::: "memory")
; #define PG8_WAIT_L(n) asm volatile("s_waitcnt lgkmcnt(" #n ")" ::: "memory")
; #define PG8_BAR __builtin_amdgcn_s_barrier()
; #define PG8_SCHED __builtin_amdgcn_sched_barrier(0)
; template <class Epi, class Sched, bool ALIGN_EPI = false, bool SP2 = false>
; __device__ __forceinline__ void gemm_phase(PG8_LAS unsigned char* lds, const Gemm g, const Sched& S, const Epi& E) {
;     ...
;             PG8_WAIT_V(8); PG8_WAIT_L(0); PG8_BAR; PG8_MMA(1, 0, At, B0); PG8_MMA(1, 1, At, B1); PG8_BAR; PG8_SCHED;
;             PG8_LDB(B0, 1, 0); PG8_LDB(B1, 1, 1); PG8_SCHED; PG8_LDA(At, 1, 0); PG8_STAGE(PG8_SA(0, 1), a2 + hstep, voffA);
;             PG8_WAIT_V(8); PG8_WAIT_L(0); PG8_BAR; PG8_MMA(0, 0, At, B0); PG8_MMA(0, 1, At, B1); PG8_BAR; PG8_SCHED;
	s_setprio 1
	s_nop 0
	s_waitcnt lgkmcnt(0)
	v_mfma_f32_16x16x32_bf16 v[60:63], v[128:131], v[160:163], v[60:63]
	v_mfma_f32_16x16x32_bf16 v[56:59], v[136:139], v[160:163], v[56:59]
	v_mfma_f32_16x16x32_bf16 v[44:47], v[128:131], v[168:171], v[44:47]
	v_mfma_f32_16x16x32_bf16 v[40:43], v[136:139], v[168:171], v[40:43]
	v_mfma_f32_16x16x32_bf16 v[28:31], v[128:131], v[188:191], v[28:31]
	v_mfma_f32_16x16x32_bf16 v[24:27], v[136:139], v[188:191], v[24:27]
	v_mfma_f32_16x16x32_bf16 v[12:15], v[128:131], v[196:199], v[12:15]
	v_mfma_f32_16x16x32_bf16 v[8:11], v[136:139], v[196:199], v[8:11]
	v_mfma_f32_16x16x32_bf16 v[60:63], v[132:135], v[164:167], v[60:63]
	v_mfma_f32_16x16x32_bf16 v[56:59], v[140:143], v[164:167], v[56:59]
	v_mfma_f32_16x16x32_bf16 v[44:47], v[132:135], v[172:175], v[44:47]
	v_mfma_f32_16x16x32_bf16 v[40:43], v[140:143], v[172:175], v[40:43]
	v_mfma_f32_16x16x32_bf16 v[28:31], v[132:135], v[192:195], v[28:31]
	v_mfma_f32_16x16x32_bf16 v[24:27], v[140:143], v[192:195], v[24:27]
	v_mfma_f32_16x16x32_bf16 v[12:15], v[132:135], v[200:203], v[12:15]
	v_mfma_f32_16x16x32_bf16 v[8:11], v[140:143], v[200:203], v[8:11]
	s_setprio 0
	s_setprio 1
	v_mfma_f32_16x16x32_bf16 v[52:55], v[144:147], v[160:163], v[52:55]
	v_mfma_f32_16x16x32_bf16 v[48:51], v[152:155], v[160:163], v[48:51]
	v_mfma_f32_16x16x32_bf16 v[36:39], v[144:147], v[168:171], v[36:39]
	v_mfma_f32_16x16x32_bf16 v[32:35], v[152:155], v[168:171], v[32:35]
	v_mfma_f32_16x16x32_bf16 v[20:23], v[144:147], v[188:191], v[20:23]
	v_mfma_f32_16x16x32_bf16 v[16:19], v[152:155], v[188:191], v[16:19]
	v_mfma_f32_16x16x32_bf16 v[4:7], v[144:147], v[196:199], v[4:7]
	v_mfma_f32_16x16x32_bf16 v[0:3], v[152:155], v[196:199], v[0:3]
	v_mfma_f32_16x16x32_bf16 v[52:55], v[148:151], v[164:167], v[52:55]
	v_mfma_f32_16x16x32_bf16 v[48:51], v[156:159], v[164:167], v[48:51]
	v_mfma_f32_16x16x32_bf16 v[36:39], v[148:151], v[172:175], v[36:39]
	v_mfma_f32_16x16x32_bf16 v[32:35], v[156:159], v[172:175], v[32:35]
	v_mfma_f32_16x16x32_bf16 v[20:23], v[148:151], v[192:195], v[20:23]
	v_mfma_f32_16x16x32_bf16 v[16:19], v[156:159], v[192:195], v[16:19]
	v_mfma_f32_16x16x32_bf16 v[4:7], v[148:151], v[200:203], v[4:7]
	v_mfma_f32_16x16x32_bf16 v[0:3], v[156:159], v[200:203], v[0:3]
	s_setprio 0
	s_barrier
	s_add_i32 s51, 0, 0x18000
	s_add_i32 s52, 0, 0x1c000
	v_add_u32_e32 v140, s51, v207
	v_add_u32_e32 v156, s52, v207
	ds_read_b128 v[128:131], v140
	ds_read_b128 v[132:135], v140 offset:1024
	ds_read_b128 v[136:139], v140 offset:2048
	ds_read_b128 v[140:143], v140 offset:3072
	ds_read_b128 v[144:147], v156
	ds_read_b128 v[148:151], v156 offset:1024
	ds_read_b128 v[152:155], v156 offset:2048
	ds_read_b128 v[156:159], v156 offset:3072
	s_add_u32 s22, s28, 0x160000
	s_addc_u32 s23, s29, 0
	s_mov_b32 m0, s33
	v_lshl_add_u64 v[218:219], s[22:23], 0, v[176:177]
	ds_read_b128 v[160:163], v211 offset:32768
	ds_read_b128 v[164:167], v211 offset:33792
	ds_read_b128 v[168:171], v211 offset:34816
	ds_read_b128 v[172:175], v211 offset:35840
	ds_read_b128 v[188:191], v211 offset:36864
	ds_read_b128 v[192:195], v211 offset:37888
	ds_read_b128 v[196:199], v211 offset:38912
	ds_read_b128 v[200:203], v211 offset:39936
	global_load_lds_dwordx4 v[218:219], off
	v_lshl_add_u64 v[218:219], s[22:23], 0, v[178:179]
	s_mov_b32 m0, s35
	s_nop 0
	global_load_lds_dwordx4 v[218:219], off
	s_waitcnt vmcnt(8)
	s_waitcnt lgkmcnt(0)
	s_barrier
	s_setprio 1
	s_nop 0
	s_waitcnt lgkmcnt(0)
	v_mfma_f32_16x16x32_bf16 v[124:127], v[128:131], v[160:163], v[124:127]
	v_mfma_f32_16x16x32_bf16 v[120:123], v[136:139], v[160:163], v[120:123]
	v_mfma_f32_16x16x32_bf16 v[108:111], v[128:131], v[168:171], v[108:111]
	v_mfma_f32_16x16x32_bf16 v[104:107], v[136:139], v[168:171], v[104:107]
	v_mfma_f32_16x16x32_bf16 v[92:95], v[128:131], v[188:191], v[92:95]
	v_mfma_f32_16x16x32_bf16 v[88:91], v[136:139], v[188:191], v[88:91]
	v_mfma_f32_16x16x32_bf16 v[76:79], v[128:131], v[196:199], v[76:79]
	v_mfma_f32_16x16x32_bf16 v[72:75], v[136:139], v[196:199], v[72:75]
	v_mfma_f32_16x16x32_bf16 v[124:127], v[132:135], v[164:167], v[124:127]
	v_mfma_f32_16x16x32_bf16 v[120:123], v[140:143], v[164:167], v[120:123]
	v_mfma_f32_16x16x32_bf16 v[108:111], v[132:135], v[172:175], v[108:111]
	v_mfma_f32_16x16x32_bf16 v[104:107], v[140:143], v[172:175], v[104:107]
	v_mfma_f32_16x16x32_bf16 v[92:95], v[132:135], v[192:195], v[92:95]
	v_mfma_f32_16x16x32_bf16 v[88:91], v[140:143], v[192:195], v[88:91]
	v_mfma_f32_16x16x32_bf16 v[76:79], v[132:135], v[200:203], v[76:79]
	v_mfma_f32_16x16x32_bf16 v[72:75], v[140:143], v[200:203], v[72:75]
	s_setprio 0
	s_setprio 1
	v_mfma_f32_16x16x32_bf16 v[116:119], v[144:147], v[160:163], v[116:119]
	v_mfma_f32_16x16x32_bf16 v[112:115], v[152:155], v[160:163], v[112:115]
	v_mfma_f32_16x16x32_bf16 v[100:103], v[144:147], v[168:171], v[100:103]
	v_mfma_f32_16x16x32_bf16 v[96:99], v[152:155], v[168:171], v[96:99]
	v_mfma_f32_16x16x32_bf16 v[84:87], v[144:147], v[188:191], v[84:87]
	v_mfma_f32_16x16x32_bf16 v[80:83], v[152:155], v[188:191], v[80:83]
	v_mfma_f32_16x16x32_bf16 v[68:71], v[144:147], v[196:199], v[68:71]
	v_mfma_f32_16x16x32_bf16 v[64:67], v[152:155], v[196:199], v[64:67]
	v_mfma_f32_16x16x32_bf16 v[116:119], v[148:151], v[164:167], v[116:119]
	v_mfma_f32_16x16x32_bf16 v[112:115], v[156:159], v[164:167], v[112:115]
	v_mfma_f32_16x16x32_bf16 v[100:103], v[148:151], v[172:175], v[100:103]
	v_mfma_f32_16x16x32_bf16 v[96:99], v[156:159], v[172:175], v[96:99]
	v_mfma_f32_16x16x32_bf16 v[84:87], v[148:151], v[192:195], v[84:87]
	v_mfma_f32_16x16x32_bf16 v[80:83], v[156:159], v[192:195], v[80:83]
	v_mfma_f32_16x16x32_bf16 v[68:71], v[148:151], v[200:203], v[68:71]
	v_mfma_f32_16x16x32_bf16 v[64:67], v[156:159], v[200:203], v[64:67]
	s_setprio 0
	s_barrier
; #define PG8_STAGE(bufoff, gbase, voff) do { _Pragma("unroll") for (int _i = 0; _i < 2; ++_i) \
;         __builtin_amdgcn_global_load_lds((const unsigned*)((const char*)(gbase) + (voff)[_i]), (PG8_LAS unsigned*)(lds + (bufoff) + ldsw + _i * 8192), 16, 0, 0); } while (0)
; #define PG8_LDA(dst, b, h) do { _Pragma("unroll") for (int m = 0; m < 4; ++m) _Pragma("unroll") for (int k = 0; k < 2; ++k) dst[m][k] = *(const PG8_LAS bf16x8*)(lds + PG8_SA(b, h) + aoff + m * 2048 + k * 1024); } while (0)
; #define PG8_MMA(ai, bj, At, Bt) do { __builtin_amdgcn_s_setprio(1); _Pragma("unroll") for (int m = 0; m < 4; ++m) _Pragma("unroll") for (int n = 0; n < 2; ++n) _Pragma("unroll") for (int k = 0; k < 2; ++k) \
;         acc[ai][bj][m][n] = __builtin_amdgcn_mfma_f32_16x16x32_bf16(Bt[n][k], At[m][k], acc[ai][bj][m][n], 0, 0, 0); __builtin_amdgcn_s_setprio(0); } while (0)
; #define PG8_WAIT_V(n) asm volatile("s_waitcnt vmcnt(" #n ")" ::: "memory")
; #define PG8_WAIT_L(n) asm volatile("s_waitcnt lgkmcnt(" #n ")" ::: "memory")
; #define PG8_BAR __builtin_amdgcn_s_barrier()
; #define PG8_SCHED __builtin_amdgcn_sched_barrier(0)
; template <class Epi, class Sched, bool ALIGN_EPI = false, bool SP2 = false>
; __device__ __forceinline__ void gemm_phase(PG8_LAS unsigned char* lds, const Gemm g, const Sched& S, const Epi& E) {
;     ...
;         for (int t = 0; t < nt; t += 2) {
;     ...
;             PG8_LDA(At, 1, 1); PG8_STAGE(PG8_SB(1, 0), b3, voffB); PG8_STAGE(PG8_SB(1, 1), b3 + hstep, voffB); PG8_STAGE(PG8_SA(1, 0), a3, voffA);
;             PG8_WAIT_V(8); PG8_WAIT_L(0); PG8_BAR; PG8_MMA(1, 0, At, B0); PG8_MMA(1, 1, At, B1); PG8_BAR; PG8_SCHED;
;     ...
;         if constexpr (ALIGN_EPI) { if (wr == 0) PG8_BAR; }
	s_add_i32 s22, s51, s3
	v_lshl_add_u64 v[204:205], v[204:205], 0, s[16:17]
	s_mov_b32 m0, s22
	ds_read_b128 v[160:163], v211 offset:49152
	ds_read_b128 v[164:167], v211 offset:50176
	ds_read_b128 v[168:171], v211 offset:51200
	ds_read_b128 v[172:175], v211 offset:52224
	ds_read_b128 v[188:191], v211 offset:53248
	ds_read_b128 v[192:195], v211 offset:54272
	ds_read_b128 v[196:199], v211 offset:55296
	ds_read_b128 v[200:203], v211 offset:56320
	global_load_lds_dwordx4 v[204:205], off
	s_add_i32 m0, s22, 0x2000
	s_add_u32 s22, s24, 0x160080
	v_lshl_add_u64 v[204:205], v[212:213], 0, s[16:17]
	s_addc_u32 s23, s25, 0
	s_add_i32 s24, s52, s3
	global_load_lds_dwordx4 v[204:205], off
	v_lshl_add_u64 v[204:205], s[22:23], 0, v[176:177]
	s_mov_b32 m0, s24
	s_nop 0
	global_load_lds_dwordx4 v[204:205], off
	v_lshl_add_u64 v[204:205], s[22:23], 0, v[178:179]
	s_add_i32 m0, s24, 0x2000
	s_nop 0
	global_load_lds_dwordx4 v[204:205], off
	v_lshl_add_u64 v[204:205], v[214:215], 0, s[16:17]
	s_mov_b32 m0, s37
	s_nop 0
	global_load_lds_dwordx4 v[204:205], off
	v_lshl_add_u64 v[204:205], v[216:217], 0, s[16:17]
	s_mov_b32 m0, s38
	s_nop 0
	global_load_lds_dwordx4 v[204:205], off
	s_waitcnt vmcnt(8)
	s_waitcnt lgkmcnt(0)
	s_barrier
	s_setprio 1
	s_waitcnt lgkmcnt(0)
	v_mfma_f32_16x16x32_bf16 v[60:63], v[128:131], v[160:163], v[60:63]
	v_mfma_f32_16x16x32_bf16 v[56:59], v[136:139], v[160:163], v[56:59]
	v_mfma_f32_16x16x32_bf16 v[44:47], v[128:131], v[168:171], v[44:47]
	v_mfma_f32_16x16x32_bf16 v[40:43], v[136:139], v[168:171], v[40:43]
	v_mfma_f32_16x16x32_bf16 v[28:31], v[128:131], v[188:191], v[28:31]
	v_mfma_f32_16x16x32_bf16 v[24:27], v[136:139], v[188:191], v[24:27]
	v_mfma_f32_16x16x32_bf16 v[12:15], v[128:131], v[196:199], v[12:15]
	v_mfma_f32_16x16x32_bf16 v[8:11], v[136:139], v[196:199], v[8:11]
	v_mfma_f32_16x16x32_bf16 v[60:63], v[132:135], v[164:167], v[60:63]
	v_mfma_f32_16x16x32_bf16 v[56:59], v[140:143], v[164:167], v[56:59]
	v_mfma_f32_16x16x32_bf16 v[44:47], v[132:135], v[172:175], v[44:47]
	v_mfma_f32_16x16x32_bf16 v[40:43], v[140:143], v[172:175], v[40:43]
	v_mfma_f32_16x16x32_bf16 v[28:31], v[132:135], v[192:195], v[28:31]
	v_mfma_f32_16x16x32_bf16 v[24:27], v[140:143], v[192:195], v[24:27]
	v_mfma_f32_16x16x32_bf16 v[12:15], v[132:135], v[200:203], v[12:15]
	v_mfma_f32_16x16x32_bf16 v[8:11], v[140:143], v[200:203], v[8:11]
	s_setprio 0
	s_setprio 1
	v_mfma_f32_16x16x32_bf16 v[52:55], v[144:147], v[160:163], v[52:55]
	v_mfma_f32_16x16x32_bf16 v[48:51], v[152:155], v[160:163], v[48:51]
	v_mfma_f32_16x16x32_bf16 v[36:39], v[144:147], v[168:171], v[36:39]
	v_mfma_f32_16x16x32_bf16 v[32:35], v[152:155], v[168:171], v[32:35]
	v_mfma_f32_16x16x32_bf16 v[20:23], v[144:147], v[188:191], v[20:23]
	v_mfma_f32_16x16x32_bf16 v[16:19], v[152:155], v[188:191], v[16:19]
	v_mfma_f32_16x16x32_bf16 v[4:7], v[144:147], v[196:199], v[4:7]
	v_mfma_f32_16x16x32_bf16 v[0:3], v[152:155], v[196:199], v[0:3]
	v_mfma_f32_16x16x32_bf16 v[52:55], v[148:151], v[164:167], v[52:55]
	v_mfma_f32_16x16x32_bf16 v[48:51], v[156:159], v[164:167], v[48:51]
	v_mfma_f32_16x16x32_bf16 v[36:39], v[148:151], v[172:175], v[36:39]
	v_mfma_f32_16x16x32_bf16 v[32:35], v[156:159], v[172:175], v[32:35]
	v_mfma_f32_16x16x32_bf16 v[20:23], v[148:151], v[192:195], v[20:23]
	v_mfma_f32_16x16x32_bf16 v[16:19], v[156:159], v[192:195], v[16:19]
	v_mfma_f32_16x16x32_bf16 v[4:7], v[148:151], v[200:203], v[4:7]
	v_mfma_f32_16x16x32_bf16 v[0:3], v[156:159], v[200:203], v[0:3]
	s_setprio 0
	s_barrier
	s_add_i32 s50, s50, 2
	s_add_u32 s48, s48, 0x100
	s_addc_u32 s49, s49, 0
	s_cmpk_gt_u32 s50, 0x55
	s_mov_b64 s[22:23], s[0:1]
	s_cbranch_scc0 .LBB0_1965
	s_and_b64 vcc, exec, s[18:19]
	s_cbranch_vccz .LBB0_1968
	s_barrier

; #define PG8_STAGE(bufoff, gbase, voff) do { _Pragma("unroll") for (int _i = 0; _i < 2; ++_i) \
;         __builtin_amdgcn_global_load_lds((const unsigned*)((const char*)(gbase) + (voff)[_i]), (PG8_LAS unsigned*)(lds + (bufoff) + ldsw + _i * 8192), 16, 0, 0); } while (0)
; #define PG8_LDA(dst, b, h) do { _Pragma("unroll") for (int m = 0; m < 4; ++m) _Pragma("unroll") for (int k = 0; k < 2; ++k) dst[m][k] = *(const PG8_LAS bf16x8*)(lds + PG8_SA(b, h) + aoff + m * 2048 + k * 1024); } while (0)
; #define PG8_LDB(dst, b, h) do { _Pragma("unroll") for (int n = 0; n < 2; ++n) _Pragma("unroll") for (int k = 0; k < 2; ++k) dst[n][k] = *(const PG8_LAS bf16x8*)(lds + PG8_SB(b, h) + boff + n * 2048 + k * 1024); } while (0)
; #define PG8_MMA(ai, bj, At, Bt) do { __builtin_amdgcn_s_setprio(1); _Pragma("unroll") for (int m = 0; m < 4; ++m) _Pragma("unroll") for (int n = 0; n < 2; ++n) _Pragma("unroll") for (int k = 0; k < 2; ++k) \
;         acc[ai][bj][m][n] = __builtin_amdgcn_mfma_f32_16x16x32_bf16(Bt[n][k], At[m][k], acc[ai][bj][m][n], 0, 0, 0); __builtin_amdgcn_s_setprio(0); } while (0)
; #define PG8_WAIT_V(n) asm volatile("s_waitcnt vmcnt(" #n ")" ::: "memory")
; #define PG8_WAIT_L(n) asm volatile("s_waitcnt lgkmcnt(" #n ")" ::: "memory")
; #define PG8_BAR __builtin_amdgcn_s_barrier()
; #define PG8_SCHED __builtin_amdgcn_sched_barrier(0)
; template <class Epi, class Sched, bool ALIGN_EPI = false, bool SP2 = false>
; __device__ __forceinline__ void gemm_phase(PG8_LAS unsigned char* lds, const Gemm g, const Sched& S, const Epi& E) {
;     ...
;             PG8_LDB(B0, 0, 0); PG8_LDB(B1, 0, 1); PG8_SCHED; PG8_LDA(At, 0, 0); PG8_STAGE(PG8_SA(1, 1), a1 + hstep, voffA);
;             PG8_WAIT_V(8); PG8_WAIT_L(0); PG8_BAR; PG8_MMA(0, 0, At, B0); PG8_MMA(0, 1, At, B1); PG8_BAR; PG8_SCHED;
;             PG8_LDA(At, 0, 1); PG8_STAGE(PG8_SB(0, 0), b2, voffB); PG8_STAGE(PG8_SB(0, 1), b2 + hstep, voffB); PG8_STAGE(PG8_SA(0, 0), a2, voffA);
.LBB0_2053:
	ds_read_b128 v[128:131], v225
	ds_read_b128 v[132:135], v225 offset:1024
	ds_read_b128 v[136:139], v225 offset:2048
	ds_read_b128 v[140:143], v225 offset:3072
	ds_read_b128 v[144:147], v228
	ds_read_b128 v[148:151], v228 offset:1024
	ds_read_b128 v[152:155], v228 offset:2048
	ds_read_b128 v[156:159], v228 offset:3072
	s_add_u32 s24, s22, 0x100
	s_addc_u32 s25, s23, 0
	s_cmpk_eq_i32 s55, 0x54
	s_cselect_b32 s31, s21, s25
	s_cselect_b32 s30, s20, s24
	s_cselect_b32 s29, s9, s7
	s_cselect_b32 s28, s8, s6
	s_mov_b32 m0, s43
	v_lshl_add_u64 v[204:205], s[22:23], 0, v[184:185]
	ds_read_b128 v[160:163], v229
	ds_read_b128 v[164:167], v229 offset:1024
	ds_read_b128 v[168:171], v229 offset:2048
	ds_read_b128 v[172:175], v229 offset:3072
	ds_read_b128 v[188:191], v229 offset:4096
	ds_read_b128 v[192:195], v229 offset:5120
	ds_read_b128 v[196:199], v229 offset:6144
	ds_read_b128 v[200:203], v229 offset:7168
	global_load_lds_dwordx4 v[204:205], off
	v_lshl_add_u64 v[204:205], s[22:23], 0, v[186:187]
	s_mov_b32 m0, s44
	s_nop 0
	global_load_lds_dwordx4 v[204:205], off
	s_waitcnt vmcnt(8)
	s_waitcnt lgkmcnt(0)
	s_barrier
	s_setprio 1
	s_waitcnt lgkmcnt(0)
	v_mfma_f32_16x16x32_bf16 v[124:127], v[128:131], v[160:163], v[124:127]
	v_mfma_f32_16x16x32_bf16 v[120:123], v[136:139], v[160:163], v[120:123]
	v_mfma_f32_16x16x32_bf16 v[108:111], v[128:131], v[168:171], v[108:111]
	v_mfma_f32_16x16x32_bf16 v[104:107], v[136:139], v[168:171], v[104:107]
	v_mfma_f32_16x16x32_bf16 v[96:99], v[128:131], v[188:191], v[96:99]
	v_mfma_f32_16x16x32_bf16 v[88:91], v[136:139], v[188:191], v[88:91]
	v_mfma_f32_16x16x32_bf16 v[80:83], v[128:131], v[196:199], v[80:83]
	v_mfma_f32_16x16x32_bf16 v[72:75], v[136:139], v[196:199], v[72:75]
	v_mfma_f32_16x16x32_bf16 v[124:127], v[132:135], v[164:167], v[124:127]
	v_mfma_f32_16x16x32_bf16 v[120:123], v[140:143], v[164:167], v[120:123]
	v_mfma_f32_16x16x32_bf16 v[108:111], v[132:135], v[172:175], v[108:111]
	v_mfma_f32_16x16x32_bf16 v[104:107], v[140:143], v[172:175], v[104:107]
	v_mfma_f32_16x16x32_bf16 v[96:99], v[132:135], v[192:195], v[96:99]
	v_mfma_f32_16x16x32_bf16 v[88:91], v[140:143], v[192:195], v[88:91]
	v_mfma_f32_16x16x32_bf16 v[80:83], v[132:135], v[200:203], v[80:83]
	v_mfma_f32_16x16x32_bf16 v[72:75], v[140:143], v[200:203], v[72:75]
	s_setprio 0
	s_setprio 1
	v_mfma_f32_16x16x32_bf16 v[116:119], v[144:147], v[160:163], v[116:119]
	v_mfma_f32_16x16x32_bf16 v[112:115], v[152:155], v[160:163], v[112:115]
	v_mfma_f32_16x16x32_bf16 v[100:103], v[144:147], v[168:171], v[100:103]
	v_mfma_f32_16x16x32_bf16 v[92:95], v[152:155], v[168:171], v[92:95]
	v_mfma_f32_16x16x32_bf16 v[84:87], v[144:147], v[188:191], v[84:87]
	v_mfma_f32_16x16x32_bf16 v[76:79], v[152:155], v[188:191], v[76:79]
	v_mfma_f32_16x16x32_bf16 v[68:71], v[144:147], v[196:199], v[68:71]
	v_mfma_f32_16x16x32_bf16 v[64:67], v[152:155], v[196:199], v[64:67]
	v_mfma_f32_16x16x32_bf16 v[116:119], v[148:151], v[164:167], v[116:119]
	v_mfma_f32_16x16x32_bf16 v[112:115], v[156:159], v[164:167], v[112:115]
	v_mfma_f32_16x16x32_bf16 v[100:103], v[148:151], v[172:175], v[100:103]
	v_mfma_f32_16x16x32_bf16 v[92:95], v[156:159], v[172:175], v[92:95]
	v_mfma_f32_16x16x32_bf16 v[84:87], v[148:151], v[192:195], v[84:87]
	v_mfma_f32_16x16x32_bf16 v[76:79], v[156:159], v[192:195], v[76:79]
	v_mfma_f32_16x16x32_bf16 v[68:71], v[148:151], v[200:203], v[68:71]
	v_mfma_f32_16x16x32_bf16 v[64:67], v[156:159], v[200:203], v[64:67]
	s_setprio 0
	s_barrier
	s_mov_b32 m0, s45
	v_lshl_add_u64 v[204:205], s[28:29], 0, v[176:177]
	s_add_u32 s22, s28, 0x160000
	ds_read_b128 v[160:163], v229 offset:16384
	ds_read_b128 v[164:167], v229 offset:17408
	ds_read_b128 v[168:171], v229 offset:18432
	ds_read_b128 v[172:175], v229 offset:19456
	ds_read_b128 v[188:191], v229 offset:20480
	ds_read_b128 v[192:195], v229 offset:21504
	ds_read_b128 v[196:199], v229 offset:22528
	ds_read_b128 v[200:203], v229 offset:23552
	global_load_lds_dwordx4 v[204:205], off
	v_lshl_add_u64 v[206:207], s[28:29], 0, v[178:179]
	s_mov_b32 m0, s46
	s_addc_u32 s23, s29, 0
	global_load_lds_dwordx4 v[206:207], off
	v_lshl_add_u64 v[208:209], s[22:23], 0, v[176:177]
	s_mov_b32 m0, s47
	v_lshl_add_u64 v[210:211], s[30:31], 0, v[178:179]
	global_load_lds_dwordx4 v[208:209], off
	v_lshl_add_u64 v[208:209], s[22:23], 0, v[178:179]
	s_mov_b32 m0, s48
	s_nop 0
	global_load_lds_dwordx4 v[208:209], off
	v_lshl_add_u64 v[208:209], s[30:31], 0, v[176:177]
	s_mov_b32 m0, s34
	s_nop 0
	global_load_lds_dwordx4 v[208:209], off
	s_mov_b32 m0, s35
	s_nop 0
	global_load_lds_dwordx4 v[210:211], off
	s_waitcnt vmcnt(8)
	s_waitcnt lgkmcnt(0)
	s_barrier
; #define PG8_STAGE(bufoff, gbase, voff) do { _Pragma("unroll") for (int _i = 0; _i < 2; ++_i) \
;         __builtin_amdgcn_global_load_lds((const unsigned*)((const char*)(gbase) + (voff)[_i]), (PG8_LAS unsigned*)(lds + (bufoff) + ldsw + _i * 8192), 16, 0, 0); } while (0)
; #define PG8_LDA(dst, b, h) do { _Pragma("unroll") for (int m = 0; m < 4; ++m) _Pragma("unroll") for (int k = 0; k < 2; ++k) dst[m][k] = *(const PG8_LAS bf16x8*)(lds + PG8_SA(b, h) + aoff + m * 2048 + k * 1024); } while (0)
; #define PG8_LDB(dst, b, h) do { _Pragma("unroll") for (int n = 0; n < 2; ++n) _Pragma("unroll") for (int k = 0; k < 2; ++k) dst[n][k] = *(const PG8_LAS bf16x8*)(lds + PG8_SB(b, h) + boff + n * 2048 + k * 1024); } while (0)
; #define PG8_MMA(ai, bj, At, Bt) do { __builtin_amdgcn_s_setprio(1); _Pragma("unroll") for (int m = 0; m < 4; ++m) _Pragma("unroll") for (int n = 0; n < 2; ++n) _Pragma("unroll") for (int k = 0; k < 2; ++k) \
;         acc[ai][bj][m][n] = __builtin_amdgcn_mfma_f32_16x16x32_bf16(Bt[n][k], At[m][k], acc[ai][bj][m][n], 0, 0, 0); __builtin_amdgcn_s_setprio(0); } while (0)
; #define PG8_WAIT_V(n) asm volatile("s_waitcnt vmcnt(" #n ")" ::: "memory")
; #define PG8_WAIT_L(n) asm volatile("s_waitcnt lgkmcnt(" #n ")" ::: "memory")
; #define PG8_BAR __builtin_amdgcn_s_barrier()
; #define PG8_SCHED __builtin_amdgcn_sched_barrier(0)
; template <class Epi, class Sched, bool ALIGN_EPI = false, bool SP2 = false>
; __device__ __forceinline__ void gemm_phase(PG8_LAS unsigned char* lds, const Gemm g, const Sched& S, const Epi& E) {
;     ...
;             PG8_WAIT_V(8); PG8_WAIT_L(0); PG8_BAR; PG8_MMA(1, 0, At, B0); PG8_MMA(1, 1, At, B1); PG8_BAR; PG8_SCHED;
;             PG8_LDB(B0, 1, 0); PG8_LDB(B1, 1, 1); PG8_SCHED; PG8_LDA(At, 1, 0); PG8_STAGE(PG8_SA(0, 1), a2 + hstep, voffA);
;             PG8_WAIT_V(8); PG8_WAIT_L(0); PG8_BAR; PG8_MMA(0, 0, At, B0); PG8_MMA(0, 1, At, B1); PG8_BAR; PG8_SCHED;
	s_setprio 1
	s_nop 0
	s_waitcnt lgkmcnt(0)
	v_mfma_f32_16x16x32_bf16 v[60:63], v[128:131], v[160:163], v[60:63]
	v_mfma_f32_16x16x32_bf16 v[56:59], v[136:139], v[160:163], v[56:59]
	v_mfma_f32_16x16x32_bf16 v[44:47], v[128:131], v[168:171], v[44:47]
	v_mfma_f32_16x16x32_bf16 v[40:43], v[136:139], v[168:171], v[40:43]
	v_mfma_f32_16x16x32_bf16 v[32:35], v[128:131], v[188:191], v[32:35]
	v_mfma_f32_16x16x32_bf16 v[24:27], v[136:139], v[188:191], v[24:27]
	v_mfma_f32_16x16x32_bf16 v[16:19], v[128:131], v[196:199], v[16:19]
	v_mfma_f32_16x16x32_bf16 v[8:11], v[136:139], v[196:199], v[8:11]
	v_mfma_f32_16x16x32_bf16 v[60:63], v[132:135], v[164:167], v[60:63]
	v_mfma_f32_16x16x32_bf16 v[56:59], v[140:143], v[164:167], v[56:59]
	v_mfma_f32_16x16x32_bf16 v[44:47], v[132:135], v[172:175], v[44:47]
	v_mfma_f32_16x16x32_bf16 v[40:43], v[140:143], v[172:175], v[40:43]
	v_mfma_f32_16x16x32_bf16 v[32:35], v[132:135], v[192:195], v[32:35]
	v_mfma_f32_16x16x32_bf16 v[24:27], v[140:143], v[192:195], v[24:27]
	v_mfma_f32_16x16x32_bf16 v[16:19], v[132:135], v[200:203], v[16:19]
	v_mfma_f32_16x16x32_bf16 v[8:11], v[140:143], v[200:203], v[8:11]
	s_setprio 0
	s_setprio 1
	v_mfma_f32_16x16x32_bf16 v[52:55], v[144:147], v[160:163], v[52:55]
	v_mfma_f32_16x16x32_bf16 v[48:51], v[152:155], v[160:163], v[48:51]
	v_mfma_f32_16x16x32_bf16 v[36:39], v[144:147], v[168:171], v[36:39]
	v_mfma_f32_16x16x32_bf16 v[28:31], v[152:155], v[168:171], v[28:31]
	v_mfma_f32_16x16x32_bf16 v[20:23], v[144:147], v[188:191], v[20:23]
	v_mfma_f32_16x16x32_bf16 v[12:15], v[152:155], v[188:191], v[12:15]
	v_mfma_f32_16x16x32_bf16 v[4:7], v[144:147], v[196:199], v[4:7]
	v_mfma_f32_16x16x32_bf16 v[0:3], v[152:155], v[196:199], v[0:3]
	v_mfma_f32_16x16x32_bf16 v[52:55], v[148:151], v[164:167], v[52:55]
	v_mfma_f32_16x16x32_bf16 v[48:51], v[156:159], v[164:167], v[48:51]
	v_mfma_f32_16x16x32_bf16 v[36:39], v[148:151], v[172:175], v[36:39]
	v_mfma_f32_16x16x32_bf16 v[28:31], v[156:159], v[172:175], v[28:31]
	v_mfma_f32_16x16x32_bf16 v[20:23], v[148:151], v[192:195], v[20:23]
	v_mfma_f32_16x16x32_bf16 v[12:15], v[156:159], v[192:195], v[12:15]
	v_mfma_f32_16x16x32_bf16 v[4:7], v[148:151], v[200:203], v[4:7]
	v_mfma_f32_16x16x32_bf16 v[0:3], v[156:159], v[200:203], v[0:3]
	s_setprio 0
	s_barrier
	ds_read_b128 v[128:131], v232
	ds_read_b128 v[132:135], v232 offset:1024
	ds_read_b128 v[136:139], v232 offset:2048
	ds_read_b128 v[140:143], v232 offset:3072
	ds_read_b128 v[144:147], v233
	ds_read_b128 v[148:151], v233 offset:1024
	ds_read_b128 v[152:155], v233 offset:2048
	ds_read_b128 v[156:159], v233 offset:3072
	s_add_u32 s22, s30, 0x160000
	s_addc_u32 s23, s31, 0
	s_mov_b32 m0, s36
	v_lshl_add_u64 v[212:213], s[22:23], 0, v[176:177]
	ds_read_b128 v[160:163], v229 offset:32768
	ds_read_b128 v[164:167], v229 offset:33792
	ds_read_b128 v[168:171], v229 offset:34816
	ds_read_b128 v[172:175], v229 offset:35840
	ds_read_b128 v[188:191], v229 offset:36864
	ds_read_b128 v[192:195], v229 offset:37888
	ds_read_b128 v[196:199], v229 offset:38912
	ds_read_b128 v[200:203], v229 offset:39936
	global_load_lds_dwordx4 v[212:213], off
	v_lshl_add_u64 v[212:213], s[22:23], 0, v[178:179]
	s_mov_b32 m0, s37
	s_nop 0
	global_load_lds_dwordx4 v[212:213], off
	s_waitcnt vmcnt(8)
	s_waitcnt lgkmcnt(0)
	s_barrier
	s_setprio 1
	s_nop 0
	s_waitcnt lgkmcnt(0)
	v_mfma_f32_16x16x32_bf16 v[124:127], v[128:131], v[160:163], v[124:127]
	v_mfma_f32_16x16x32_bf16 v[120:123], v[136:139], v[160:163], v[120:123]
	v_mfma_f32_16x16x32_bf16 v[108:111], v[128:131], v[168:171], v[108:111]
	v_mfma_f32_16x16x32_bf16 v[104:107], v[136:139], v[168:171], v[104:107]
	v_mfma_f32_16x16x32_bf16 v[96:99], v[128:131], v[188:191], v[96:99]
	v_mfma_f32_16x16x32_bf16 v[88:91], v[136:139], v[188:191], v[88:91]
	v_mfma_f32_16x16x32_bf16 v[80:83], v[128:131], v[196:199], v[80:83]
	v_mfma_f32_16x16x32_bf16 v[72:75], v[136:139], v[196:199], v[72:75]
	v_mfma_f32_16x16x32_bf16 v[124:127], v[132:135], v[164:167], v[124:127]
	v_mfma_f32_16x16x32_bf16 v[120:123], v[140:143], v[164:167], v[120:123]
	v_mfma_f32_16x16x32_bf16 v[108:111], v[132:135], v[172:175], v[108:111]
	v_mfma_f32_16x16x32_bf16 v[104:107], v[140:143], v[172:175], v[104:107]
	v_mfma_f32_16x16x32_bf16 v[96:99], v[132:135], v[192:195], v[96:99]
	v_mfma_f32_16x16x32_bf16 v[88:91], v[140:143], v[192:195], v[88:91]
	v_mfma_f32_16x16x32_bf16 v[80:83], v[132:135], v[200:203], v[80:83]
	v_mfma_f32_16x16x32_bf16 v[72:75], v[140:143], v[200:203], v[72:75]
	s_setprio 0
	s_setprio 1
	v_mfma_f32_16x16x32_bf16 v[116:119], v[144:147], v[160:163], v[116:119]
	v_mfma_f32_16x16x32_bf16 v[112:115], v[152:155], v[160:163], v[112:115]
	v_mfma_f32_16x16x32_bf16 v[100:103], v[144:147], v[168:171], v[100:103]
	v_mfma_f32_16x16x32_bf16 v[92:95], v[152:155], v[168:171], v[92:95]
	v_mfma_f32_16x16x32_bf16 v[84:87], v[144:147], v[188:191], v[84:87]
	v_mfma_f32_16x16x32_bf16 v[76:79], v[152:155], v[188:191], v[76:79]
	v_mfma_f32_16x16x32_bf16 v[68:71], v[144:147], v[196:199], v[68:71]
	v_mfma_f32_16x16x32_bf16 v[64:67], v[152:155], v[196:199], v[64:67]
	v_mfma_f32_16x16x32_bf16 v[116:119], v[148:151], v[164:167], v[116:119]
	v_mfma_f32_16x16x32_bf16 v[112:115], v[156:159], v[164:167], v[112:115]
	v_mfma_f32_16x16x32_bf16 v[100:103], v[148:151], v[172:175], v[100:103]
	v_mfma_f32_16x16x32_bf16 v[92:95], v[156:159], v[172:175], v[92:95]
	v_mfma_f32_16x16x32_bf16 v[84:87], v[148:151], v[192:195], v[84:87]
	v_mfma_f32_16x16x32_bf16 v[76:79], v[156:159], v[192:195], v[76:79]
	v_mfma_f32_16x16x32_bf16 v[68:71], v[148:151], v[200:203], v[68:71]
	v_mfma_f32_16x16x32_bf16 v[64:67], v[156:159], v[200:203], v[64:67]
	s_setprio 0
	s_barrier
; #define PG8_STAGE(bufoff, gbase, voff) do { _Pragma("unroll") for (int _i = 0; _i < 2; ++_i) \
;         __builtin_amdgcn_global_load_lds((const unsigned*)((const char*)(gbase) + (voff)[_i]), (PG8_LAS unsigned*)(lds + (bufoff) + ldsw + _i * 8192), 16, 0, 0); } while (0)
; #define PG8_LDA(dst, b, h) do { _Pragma("unroll") for (int m = 0; m < 4; ++m) _Pragma("unroll") for (int k = 0; k < 2; ++k) dst[m][k] = *(const PG8_LAS bf16x8*)(lds + PG8_SA(b, h) + aoff + m * 2048 + k * 1024); } while (0)
; #define PG8_MMA(ai, bj, At, Bt) do { __builtin_amdgcn_s_setprio(1); _Pragma("unroll") for (int m = 0; m < 4; ++m) _Pragma("unroll") for (int n = 0; n < 2; ++n) _Pragma("unroll") for (int k = 0; k < 2; ++k) \
;         acc[ai][bj][m][n] = __builtin_amdgcn_mfma_f32_16x16x32_bf16(Bt[n][k], At[m][k], acc[ai][bj][m][n], 0, 0, 0); __builtin_amdgcn_s_setprio(0); } while (0)
; #define PG8_WAIT_V(n) asm volatile("s_waitcnt vmcnt(" #n ")" ::: "memory")
; #define PG8_WAIT_L(n) asm volatile("s_waitcnt lgkmcnt(" #n ")" ::: "memory")
; #define PG8_BAR __builtin_amdgcn_s_barrier()
; #define PG8_SCHED __builtin_amdgcn_sched_barrier(0)
; template <class Epi, class Sched, bool ALIGN_EPI = false, bool SP2 = false>
; __device__ __forceinline__ void gemm_phase(PG8_LAS unsigned char* lds, const Gemm g, const Sched& S, const Epi& E) {
;     ...
;         for (int t = 0; t < nt; t += 2) {
;     ...
;             PG8_LDA(At, 1, 1); PG8_STAGE(PG8_SB(1, 0), b3, voffB); PG8_STAGE(PG8_SB(1, 1), b3 + hstep, voffB); PG8_STAGE(PG8_SA(1, 0), a3, voffA);
;             PG8_WAIT_V(8); PG8_WAIT_L(0); PG8_BAR; PG8_MMA(1, 0, At, B0); PG8_MMA(1, 1, At, B1); PG8_BAR; PG8_SCHED;
;     ...
;         if constexpr (ALIGN_EPI) { if (wr == 0) PG8_BAR; }
	s_mov_b32 m0, s49
	v_lshl_add_u64 v[204:205], v[204:205], 0, s[14:15]
	s_add_u32 s22, s28, 0x160080
	ds_read_b128 v[160:163], v229 offset:49152
	ds_read_b128 v[164:167], v229 offset:50176
	ds_read_b128 v[168:171], v229 offset:51200
	ds_read_b128 v[172:175], v229 offset:52224
	ds_read_b128 v[188:191], v229 offset:53248
	ds_read_b128 v[192:195], v229 offset:54272
	ds_read_b128 v[196:199], v229 offset:55296
	ds_read_b128 v[200:203], v229 offset:56320
	global_load_lds_dwordx4 v[204:205], off
	v_lshl_add_u64 v[204:205], v[206:207], 0, s[14:15]
	s_mov_b32 m0, s50
	s_addc_u32 s23, s29, 0
	global_load_lds_dwordx4 v[204:205], off
	v_lshl_add_u64 v[204:205], s[22:23], 0, v[176:177]
	s_mov_b32 m0, s51
	s_nop 0
	global_load_lds_dwordx4 v[204:205], off
	v_lshl_add_u64 v[204:205], s[22:23], 0, v[178:179]
	s_mov_b32 m0, s52
	s_nop 0
	global_load_lds_dwordx4 v[204:205], off
	v_lshl_add_u64 v[204:205], v[208:209], 0, s[14:15]
	s_mov_b32 m0, s38
	s_nop 0
	global_load_lds_dwordx4 v[204:205], off
	v_lshl_add_u64 v[204:205], v[210:211], 0, s[14:15]
	s_mov_b32 m0, s39
	s_nop 0
	global_load_lds_dwordx4 v[204:205], off
	s_waitcnt vmcnt(8)
	s_waitcnt lgkmcnt(0)
	s_barrier
	s_setprio 1
	s_waitcnt lgkmcnt(0)
	v_mfma_f32_16x16x32_bf16 v[60:63], v[128:131], v[160:163], v[60:63]
	v_mfma_f32_16x16x32_bf16 v[56:59], v[136:139], v[160:163], v[56:59]
	v_mfma_f32_16x16x32_bf16 v[44:47], v[128:131], v[168:171], v[44:47]
	v_mfma_f32_16x16x32_bf16 v[40:43], v[136:139], v[168:171], v[40:43]
	v_mfma_f32_16x16x32_bf16 v[32:35], v[128:131], v[188:191], v[32:35]
	v_mfma_f32_16x16x32_bf16 v[24:27], v[136:139], v[188:191], v[24:27]
	v_mfma_f32_16x16x32_bf16 v[16:19], v[128:131], v[196:199], v[16:19]
	v_mfma_f32_16x16x32_bf16 v[8:11], v[136:139], v[196:199], v[8:11]
	v_mfma_f32_16x16x32_bf16 v[60:63], v[132:135], v[164:167], v[60:63]
	v_mfma_f32_16x16x32_bf16 v[56:59], v[140:143], v[164:167], v[56:59]
	v_mfma_f32_16x16x32_bf16 v[44:47], v[132:135], v[172:175], v[44:47]
	v_mfma_f32_16x16x32_bf16 v[40:43], v[140:143], v[172:175], v[40:43]
	v_mfma_f32_16x16x32_bf16 v[32:35], v[132:135], v[192:195], v[32:35]
	v_mfma_f32_16x16x32_bf16 v[24:27], v[140:143], v[192:195], v[24:27]
	v_mfma_f32_16x16x32_bf16 v[16:19], v[132:135], v[200:203], v[16:19]
	v_mfma_f32_16x16x32_bf16 v[8:11], v[140:143], v[200:203], v[8:11]
	s_setprio 0
	s_setprio 1
	v_mfma_f32_16x16x32_bf16 v[52:55], v[144:147], v[160:163], v[52:55]
	v_mfma_f32_16x16x32_bf16 v[48:51], v[152:155], v[160:163], v[48:51]
	v_mfma_f32_16x16x32_bf16 v[36:39], v[144:147], v[168:171], v[36:39]
	v_mfma_f32_16x16x32_bf16 v[28:31], v[152:155], v[168:171], v[28:31]
	v_mfma_f32_16x16x32_bf16 v[20:23], v[144:147], v[188:191], v[20:23]
	v_mfma_f32_16x16x32_bf16 v[12:15], v[152:155], v[188:191], v[12:15]
	v_mfma_f32_16x16x32_bf16 v[4:7], v[144:147], v[196:199], v[4:7]
	v_mfma_f32_16x16x32_bf16 v[0:3], v[152:155], v[196:199], v[0:3]
	v_mfma_f32_16x16x32_bf16 v[52:55], v[148:151], v[164:167], v[52:55]
	v_mfma_f32_16x16x32_bf16 v[48:51], v[156:159], v[164:167], v[48:51]
	v_mfma_f32_16x16x32_bf16 v[36:39], v[148:151], v[172:175], v[36:39]
	v_mfma_f32_16x16x32_bf16 v[28:31], v[156:159], v[172:175], v[28:31]
	v_mfma_f32_16x16x32_bf16 v[20:23], v[148:151], v[192:195], v[20:23]
	v_mfma_f32_16x16x32_bf16 v[12:15], v[156:159], v[192:195], v[12:15]
	v_mfma_f32_16x16x32_bf16 v[4:7], v[148:151], v[200:203], v[4:7]
	v_mfma_f32_16x16x32_bf16 v[0:3], v[156:159], v[200:203], v[0:3]
	s_setprio 0
	s_barrier
	s_add_i32 s55, s55, 2
	s_add_u32 s6, s6, 0x100
	s_addc_u32 s7, s7, 0
	s_cmpk_gt_u32 s55, 0x55
	s_mov_b64 s[22:23], s[24:25]
	s_cbranch_scc0 .LBB0_2053
	s_and_b64 vcc, exec, s[16:17]
	s_cbranch_vccz .LBB0_2056
	s_barrier
